# v19 (flips deleted) + the redundant s_waitcnt lgkmcnt(0) at the head of each of the 40 MMA segments deleted (the load segment already waited before the barrier); MMA segments are the measured critical
# baseline (speedup 1.0000x reference)
; #define PG8_STAGE(bufoff, gbase, voff) do { _Pragma("unroll") for (int _i = 0; _i < 2; ++_i) \
;         __builtin_amdgcn_global_load_lds((const unsigned*)((const char*)(gbase) + (voff)[_i]), (LAS unsigned*)(lds + (bufoff) + ldsw + _i * 8192), 16, 0, 0); } while (0)
; #define PG8_LDA(dst, b, h) do { _Pragma("unroll") for (int m = 0; m < 4; ++m) _Pragma("unroll") for (int k = 0; k < 2; ++k) dst[m][k] = *(const LAS bf16x8*)(lds + PG8_SA(b, h) + aoff + m * 2048 + k * 1024); } while (0)
; #define PG8_LDB(dst, b, h) do { _Pragma("unroll") for (int n = 0; n < 2; ++n) _Pragma("unroll") for (int k = 0; k < 2; ++k) dst[n][k] = *(const LAS bf16x8*)(lds + PG8_SB(b, h) + boff + n * 2048 + k * 1024); } while (0)
; #define PG8_MMA(ai, bj, At, Bt) do { __builtin_amdgcn_s_setprio(1); _Pragma("unroll") for (int m = 0; m < 4; ++m) _Pragma("unroll") for (int n = 0; n < 2; ++n) _Pragma("unroll") for (int k = 0; k < 2; ++k) \
;         acc[ai][bj][m][n] = __builtin_amdgcn_mfma_f32_16x16x32_bf16(Bt[n][k], At[m][k], acc[ai][bj][m][n], 0, 0, 0); __builtin_amdgcn_s_setprio(0); } while (0)
; #define PG8_WAIT_V(n) asm volatile("s_waitcnt vmcnt(" #n ")" ::: "memory")
; #define PG8_WAIT_L(n) asm volatile("s_waitcnt lgkmcnt(" #n ")" ::: "memory")
; #define PG8_BAR __builtin_amdgcn_s_barrier()
; #define PG8_SCHED __builtin_amdgcn_sched_barrier(0)
; template <class Epi, class Sched>
; __device__ __forceinline__ void gemm_phase(LAS unsigned char* lds, const int lda, const int ldb, const int K, const Sched& S, const Epi& E) {
;     ...
;         for (int t = 0; t < nt; t += 2) {
;             const bool last = (t == nt - 2);
;             const char* a1 = cA + (size_t)(t + 1) * kstep;
;             const char* a2 = last ? nA : cA + (size_t)(t + 2) * kstep; const char* b2 = last ? nB : cB + (size_t)(t + 2) * kstep;
;             const char* a3 = a2 + kstep; const char* b3 = b2 + kstep;
;             PG8_LDB(B0, 0, 0); PG8_LDB(B1, 0, 1); PG8_SCHED; PG8_LDA(At, 0, 0); PG8_STAGE(PG8_SA(1, 1), a1 + hstepA, voffA);
;             PG8_WAIT_V(8); PG8_WAIT_L(0); PG8_BAR; PG8_MMA(0, 0, At, B0); PG8_MMA(0, 1, At, B1); PG8_BAR; PG8_SCHED;
;             PG8_LDA(At, 0, 1); PG8_STAGE(PG8_SB(0, 0), b2, voffB); PG8_STAGE(PG8_SB(0, 1), b2 + hstepB, voffB); PG8_STAGE(PG8_SA(0, 0), a2, voffA);
;             PG8_WAIT_V(8); PG8_WAIT_L(0); PG8_BAR; PG8_MMA(1, 0, At, B0); PG8_MMA(1, 1, At, B1); PG8_BAR; PG8_SCHED;
.LBB0_240:
	s_lshl_b32 s20, s20, 8
	s_ashr_i32 s21, s20, 31
	s_add_u32 s22, s22, 0x40080
	s_addc_u32 s23, s23, 0
	s_add_u32 s13, s24, 0x100
	s_addc_u32 s15, s25, 0
	s_mov_b32 s65, -2
	v_lshl_add_u64 v[214:215], s[20:21], 2, v[204:205]
	v_add_u32_e32 v230, 0x80, v200
	v_add_u32_e32 v231, 0x80, v196
	v_add_u32_e32 v232, 0x80, v202
	v_add_u32_e32 v233, 0x80, v198
	s_add_u32 s21, s22, 0xfffc0080
	s_addc_u32 s24, s23, -1
	s_cmp_eq_u32 s65, 12
	s_cselect_b32 s29, s17, s24
	s_cselect_b32 s28, s16, s21
	s_cselect_b32 s31, s19, s15
	s_cselect_b32 s30, s18, s13
	s_add_i32 s72, s50, s3
	s_add_i32 m0, s37, 0xc000
	s_add_i32 s71, s37, 0xe000
	s_add_i32 s73, s72, 0x2000
	s_add_u32 s48, s30, 0x40000
	s_addc_u32 s49, s31, 0
	s_add_i32 s74, s51, s3
	s_add_i32 s75, s74, 0x2000
	s_add_i32 s76, 0, 0x18000
	s_add_i32 s77, 0, 0x1c000
	s_add_u32 s26, s28, 0x40000
	s_addc_u32 s27, s29, 0
	s_add_i32 s68, s76, s3
	s_add_i32 s21, s68, 0x2000
	s_add_u32 s24, s30, 0x40080
	s_addc_u32 s25, s31, 0
	s_add_i32 s70, s77, s3
	s_add_i32 s69, s70, 0x2000
	s_cmp_lg_u32 s65, 12
	global_load_lds_dwordx4 v206, s[22:23]
	s_mov_b32 m0, s71
	s_nop 0
	global_load_lds_dwordx4 v208, s[22:23]
	s_waitcnt vmcnt(8)
	s_waitcnt lgkmcnt(0)
	s_barrier
	v_mfma_f32_16x16x32_bf16 v[126:129], v[130:133], v[162:165], 0
	v_mfma_f32_16x16x32_bf16 v[118:121], v[138:141], v[162:165], 0
	v_mfma_f32_16x16x32_bf16 v[110:113], v[130:133], v[170:173], 0
	v_mfma_f32_16x16x32_bf16 v[102:105], v[138:141], v[170:173], 0
	v_mfma_f32_16x16x32_bf16 v[94:97], v[130:133], v[178:181], 0
	v_mfma_f32_16x16x32_bf16 v[86:89], v[138:141], v[178:181], 0
	v_mfma_f32_16x16x32_bf16 v[78:81], v[130:133], v[186:189], 0
	v_mfma_f32_16x16x32_bf16 v[70:73], v[138:141], v[186:189], 0
	v_mfma_f32_16x16x32_bf16 v[126:129], v[134:137], v[166:169], v[126:129]
	v_mfma_f32_16x16x32_bf16 v[118:121], v[142:145], v[166:169], v[118:121]
	v_mfma_f32_16x16x32_bf16 v[110:113], v[134:137], v[174:177], v[110:113]
	v_mfma_f32_16x16x32_bf16 v[102:105], v[142:145], v[174:177], v[102:105]
	v_mfma_f32_16x16x32_bf16 v[94:97], v[134:137], v[182:185], v[94:97]
	v_mfma_f32_16x16x32_bf16 v[86:89], v[142:145], v[182:185], v[86:89]
	v_mfma_f32_16x16x32_bf16 v[78:81], v[134:137], v[190:193], v[78:81]
	v_mfma_f32_16x16x32_bf16 v[70:73], v[142:145], v[190:193], v[70:73]
	v_mfma_f32_16x16x32_bf16 v[122:125], v[146:149], v[162:165], 0
	v_mfma_f32_16x16x32_bf16 v[114:117], v[154:157], v[162:165], 0
	v_mfma_f32_16x16x32_bf16 v[106:109], v[146:149], v[170:173], 0
	v_mfma_f32_16x16x32_bf16 v[98:101], v[154:157], v[170:173], 0
	v_mfma_f32_16x16x32_bf16 v[90:93], v[146:149], v[178:181], 0
	v_mfma_f32_16x16x32_bf16 v[82:85], v[154:157], v[178:181], 0
	v_mfma_f32_16x16x32_bf16 v[74:77], v[146:149], v[186:189], 0
	v_mfma_f32_16x16x32_bf16 v[66:69], v[154:157], v[186:189], 0
	v_mfma_f32_16x16x32_bf16 v[122:125], v[150:153], v[166:169], v[122:125]
	v_mfma_f32_16x16x32_bf16 v[114:117], v[158:161], v[166:169], v[114:117]
	v_mfma_f32_16x16x32_bf16 v[106:109], v[150:153], v[174:177], v[106:109]
	v_mfma_f32_16x16x32_bf16 v[98:101], v[158:161], v[174:177], v[98:101]
	v_mfma_f32_16x16x32_bf16 v[90:93], v[150:153], v[182:185], v[90:93]
	v_mfma_f32_16x16x32_bf16 v[82:85], v[158:161], v[182:185], v[82:85]
	v_mfma_f32_16x16x32_bf16 v[74:77], v[150:153], v[190:193], v[74:77]
	v_mfma_f32_16x16x32_bf16 v[66:69], v[158:161], v[190:193], v[66:69]
	s_barrier
	s_mov_b32 m0, s72
	ds_read_b128 v[162:165], v219 offset:16384
	ds_read_b128 v[166:169], v219 offset:17408
	ds_read_b128 v[170:173], v219 offset:18432
	ds_read_b128 v[174:177], v219 offset:19456
	ds_read_b128 v[178:181], v219 offset:20480
	ds_read_b128 v[182:185], v219 offset:21504
	ds_read_b128 v[186:189], v219 offset:22528
	ds_read_b128 v[190:193], v219 offset:23552
	global_load_lds_dwordx4 v200, s[30:31]
	s_mov_b32 m0, s73
	s_nop 0
	global_load_lds_dwordx4 v196, s[30:31]
	s_mov_b32 m0, s74
	s_nop 0
	global_load_lds_dwordx4 v200, s[48:49]
	s_mov_b32 m0, s75
	s_nop 0
	global_load_lds_dwordx4 v196, s[48:49]
	s_mov_b32 m0, s37
	s_nop 0
	global_load_lds_dwordx4 v202, s[28:29]
	s_mov_b32 m0, s38
	s_nop 0
	global_load_lds_dwordx4 v198, s[28:29]
	s_waitcnt vmcnt(8)
	s_waitcnt lgkmcnt(0)
	s_barrier
	v_mfma_f32_16x16x32_bf16 v[62:65], v[130:133], v[162:165], 0
	v_mfma_f32_16x16x32_bf16 v[54:57], v[138:141], v[162:165], 0
	v_mfma_f32_16x16x32_bf16 v[46:49], v[130:133], v[170:173], 0
	v_mfma_f32_16x16x32_bf16 v[38:41], v[138:141], v[170:173], 0
	v_mfma_f32_16x16x32_bf16 v[30:33], v[130:133], v[178:181], 0
	v_mfma_f32_16x16x32_bf16 v[22:25], v[138:141], v[178:181], 0
	v_mfma_f32_16x16x32_bf16 v[14:17], v[130:133], v[186:189], 0
	v_mfma_f32_16x16x32_bf16 v[6:9], v[138:141], v[186:189], 0
	v_mfma_f32_16x16x32_bf16 v[62:65], v[134:137], v[166:169], v[62:65]
	v_mfma_f32_16x16x32_bf16 v[54:57], v[142:145], v[166:169], v[54:57]
	v_mfma_f32_16x16x32_bf16 v[46:49], v[134:137], v[174:177], v[46:49]
	v_mfma_f32_16x16x32_bf16 v[38:41], v[142:145], v[174:177], v[38:41]
	v_mfma_f32_16x16x32_bf16 v[30:33], v[134:137], v[182:185], v[30:33]
	v_mfma_f32_16x16x32_bf16 v[22:25], v[142:145], v[182:185], v[22:25]
	v_mfma_f32_16x16x32_bf16 v[14:17], v[134:137], v[190:193], v[14:17]
	v_mfma_f32_16x16x32_bf16 v[6:9], v[142:145], v[190:193], v[6:9]
	v_mfma_f32_16x16x32_bf16 v[58:61], v[146:149], v[162:165], 0
	v_mfma_f32_16x16x32_bf16 v[50:53], v[154:157], v[162:165], 0
	v_mfma_f32_16x16x32_bf16 v[42:45], v[146:149], v[170:173], 0
	v_mfma_f32_16x16x32_bf16 v[34:37], v[154:157], v[170:173], 0
	v_mfma_f32_16x16x32_bf16 v[26:29], v[146:149], v[178:181], 0
	v_mfma_f32_16x16x32_bf16 v[18:21], v[154:157], v[178:181], 0
	v_mfma_f32_16x16x32_bf16 v[10:13], v[146:149], v[186:189], 0
	v_mfma_f32_16x16x32_bf16 v[2:5], v[154:157], v[186:189], 0
	v_mfma_f32_16x16x32_bf16 v[58:61], v[150:153], v[166:169], v[58:61]
	v_mfma_f32_16x16x32_bf16 v[50:53], v[158:161], v[166:169], v[50:53]
	v_mfma_f32_16x16x32_bf16 v[42:45], v[150:153], v[174:177], v[42:45]
	v_mfma_f32_16x16x32_bf16 v[34:37], v[158:161], v[174:177], v[34:37]
	v_mfma_f32_16x16x32_bf16 v[26:29], v[150:153], v[182:185], v[26:29]
	v_mfma_f32_16x16x32_bf16 v[18:21], v[158:161], v[182:185], v[18:21]
	v_mfma_f32_16x16x32_bf16 v[10:13], v[150:153], v[190:193], v[10:13]
	v_mfma_f32_16x16x32_bf16 v[2:5], v[158:161], v[190:193], v[2:5]
	s_barrier
	s_branch .Lpeel1_join
; #define PG8_STAGE(bufoff, gbase, voff) do { _Pragma("unroll") for (int _i = 0; _i < 2; ++_i) \
;         __builtin_amdgcn_global_load_lds((const unsigned*)((const char*)(gbase) + (voff)[_i]), (LAS unsigned*)(lds + (bufoff) + ldsw + _i * 8192), 16, 0, 0); } while (0)
; #define PG8_LDA(dst, b, h) do { _Pragma("unroll") for (int m = 0; m < 4; ++m) _Pragma("unroll") for (int k = 0; k < 2; ++k) dst[m][k] = *(const LAS bf16x8*)(lds + PG8_SA(b, h) + aoff + m * 2048 + k * 1024); } while (0)
; #define PG8_LDB(dst, b, h) do { _Pragma("unroll") for (int n = 0; n < 2; ++n) _Pragma("unroll") for (int k = 0; k < 2; ++k) dst[n][k] = *(const LAS bf16x8*)(lds + PG8_SB(b, h) + boff + n * 2048 + k * 1024); } while (0)
; #define PG8_MMA(ai, bj, At, Bt) do { __builtin_amdgcn_s_setprio(1); _Pragma("unroll") for (int m = 0; m < 4; ++m) _Pragma("unroll") for (int n = 0; n < 2; ++n) _Pragma("unroll") for (int k = 0; k < 2; ++k) \
;         acc[ai][bj][m][n] = __builtin_amdgcn_mfma_f32_16x16x32_bf16(Bt[n][k], At[m][k], acc[ai][bj][m][n], 0, 0, 0); __builtin_amdgcn_s_setprio(0); } while (0)
; template <class Epi, class Sched>
; __device__ __forceinline__ void gemm_phase(LAS unsigned char* lds, const int lda, const int ldb, const int K, const Sched& S, const Epi& E) {
;     ...
;             PG8_LDB(B0, 0, 0); PG8_LDB(B1, 0, 1); PG8_SCHED; PG8_LDA(At, 0, 0); PG8_STAGE(PG8_SA(1, 1), a1 + hstepA, voffA);
;             PG8_WAIT_V(8); PG8_WAIT_L(0); PG8_BAR; PG8_MMA(0, 0, At, B0); PG8_MMA(0, 1, At, B1); PG8_BAR; PG8_SCHED;
;             PG8_LDA(At, 0, 1); PG8_STAGE(PG8_SB(0, 0), b2, voffB); PG8_STAGE(PG8_SB(0, 1), b2 + hstepB, voffB); PG8_STAGE(PG8_SA(0, 0), a2, voffA);
;             PG8_WAIT_V(8); PG8_WAIT_L(0); PG8_BAR; PG8_MMA(1, 0, At, B0); PG8_MMA(1, 1, At, B1); PG8_BAR; PG8_SCHED;
;             PG8_LDB(B0, 1, 0); PG8_LDB(B1, 1, 1); PG8_SCHED; PG8_LDA(At, 1, 0); PG8_STAGE(PG8_SA(0, 1), a2 + hstepA, voffA);
;             PG8_WAIT_V(8); PG8_WAIT_L(0); PG8_BAR; PG8_MMA(0, 0, At, B0); PG8_MMA(0, 1, At, B1); PG8_BAR; PG8_SCHED;
;             PG8_LDA(At, 1, 1); PG8_STAGE(PG8_SB(1, 0), b3, voffB); PG8_STAGE(PG8_SB(1, 1), b3 + hstepB, voffB); PG8_STAGE(PG8_SA(1, 0), a3, voffA);
;             PG8_WAIT_V(8); PG8_WAIT_L(0); PG8_BAR;
;             if (last) E.pre(cur, wr, fr, rsv);
;             PG8_MMA(1, 0, At, B0); PG8_MMA(1, 1, At, B1); PG8_BAR; PG8_SCHED;
.LBB0_241:
	v_mfma_f32_16x16x32_bf16 v[62:65], v[146:149], v[186:189], v[62:65]
	v_mfma_f32_16x16x32_bf16 v[54:57], v[154:157], v[186:189], v[54:57]
	v_mfma_f32_16x16x32_bf16 v[46:49], v[146:149], v[178:181], v[46:49]
	v_mfma_f32_16x16x32_bf16 v[38:41], v[154:157], v[178:181], v[38:41]
	v_mfma_f32_16x16x32_bf16 v[30:33], v[146:149], v[170:173], v[30:33]
	v_mfma_f32_16x16x32_bf16 v[22:25], v[154:157], v[170:173], v[22:25]
	v_mfma_f32_16x16x32_bf16 v[14:17], v[146:149], v[162:165], v[14:17]
	v_mfma_f32_16x16x32_bf16 v[6:9], v[154:157], v[162:165], v[6:9]
	v_mfma_f32_16x16x32_bf16 v[62:65], v[150:153], v[190:193], v[62:65]
	v_mfma_f32_16x16x32_bf16 v[54:57], v[158:161], v[190:193], v[54:57]
	v_mfma_f32_16x16x32_bf16 v[46:49], v[150:153], v[182:185], v[46:49]
	v_mfma_f32_16x16x32_bf16 v[38:41], v[158:161], v[182:185], v[38:41]
	v_mfma_f32_16x16x32_bf16 v[30:33], v[150:153], v[174:177], v[30:33]
	v_mfma_f32_16x16x32_bf16 v[22:25], v[158:161], v[174:177], v[22:25]
	v_mfma_f32_16x16x32_bf16 v[14:17], v[150:153], v[166:169], v[14:17]
	v_mfma_f32_16x16x32_bf16 v[6:9], v[158:161], v[166:169], v[6:9]
	v_mfma_f32_16x16x32_bf16 v[58:61], v[130:133], v[186:189], v[58:61]
	v_mfma_f32_16x16x32_bf16 v[50:53], v[138:141], v[186:189], v[50:53]
	v_mfma_f32_16x16x32_bf16 v[42:45], v[130:133], v[178:181], v[42:45]
	v_mfma_f32_16x16x32_bf16 v[34:37], v[138:141], v[178:181], v[34:37]
	v_mfma_f32_16x16x32_bf16 v[26:29], v[130:133], v[170:173], v[26:29]
	v_mfma_f32_16x16x32_bf16 v[18:21], v[138:141], v[170:173], v[18:21]
	v_mfma_f32_16x16x32_bf16 v[10:13], v[130:133], v[162:165], v[10:13]
	v_mfma_f32_16x16x32_bf16 v[2:5], v[138:141], v[162:165], v[2:5]
	v_mfma_f32_16x16x32_bf16 v[58:61], v[134:137], v[190:193], v[58:61]
	v_mfma_f32_16x16x32_bf16 v[50:53], v[142:145], v[190:193], v[50:53]
	v_mfma_f32_16x16x32_bf16 v[42:45], v[134:137], v[182:185], v[42:45]
	v_mfma_f32_16x16x32_bf16 v[34:37], v[142:145], v[182:185], v[34:37]
	v_mfma_f32_16x16x32_bf16 v[26:29], v[134:137], v[174:177], v[26:29]
	v_mfma_f32_16x16x32_bf16 v[18:21], v[142:145], v[174:177], v[18:21]
	v_mfma_f32_16x16x32_bf16 v[10:13], v[134:137], v[166:169], v[10:13]
	v_mfma_f32_16x16x32_bf16 v[2:5], v[142:145], v[166:169], v[2:5]
	s_barrier
	s_add_i32 s65, s65, 2
	s_add_u32 s22, s22, 0x100
	s_addc_u32 s23, s23, 0
	s_add_u32 s13, s13, 0x100
	s_addc_u32 s15, s15, 0
	s_cmp_gt_u32 s65, 13
	s_cbranch_scc1 .LBB0_244
.LBB0_242:
	s_add_u32 s21, s22, 0xfffc0080
	s_addc_u32 s24, s23, -1
	s_cmp_eq_u32 s65, 12
	s_cselect_b32 s29, s17, s24
	s_cselect_b32 s28, s16, s21
	s_cselect_b32 s31, s19, s15
	s_cselect_b32 s30, s18, s13
	s_add_i32 s72, s50, s3
	ds_read_b128 v[130:133], v217
	ds_read_b128 v[134:137], v217 offset:1024
	ds_read_b128 v[138:141], v217 offset:2048
	ds_read_b128 v[142:145], v217 offset:3072
	ds_read_b128 v[146:149], v218
	ds_read_b128 v[150:153], v218 offset:1024
	ds_read_b128 v[154:157], v218 offset:2048
	ds_read_b128 v[158:161], v218 offset:3072
	s_add_i32 m0, s37, 0xc000
	s_add_i32 s71, s37, 0xe000
	s_add_i32 s73, s72, 0x2000
	s_add_u32 s48, s30, 0x40000
	s_addc_u32 s49, s31, 0
	s_add_i32 s74, s51, s3
	s_add_i32 s75, s74, 0x2000
	s_add_i32 s76, 0, 0x18000
	s_add_i32 s77, 0, 0x1c000
	s_add_u32 s26, s28, 0x40000
	s_addc_u32 s27, s29, 0
	s_add_i32 s68, s76, s3
	s_add_i32 s21, s68, 0x2000
	s_add_u32 s24, s30, 0x40080
	s_addc_u32 s25, s31, 0
	s_add_i32 s70, s77, s3
	s_add_i32 s69, s70, 0x2000
	s_cmp_lg_u32 s65, 12
	ds_read_b128 v[162:165], v219
	ds_read_b128 v[166:169], v219 offset:1024
	ds_read_b128 v[170:173], v219 offset:2048
	ds_read_b128 v[174:177], v219 offset:3072
	ds_read_b128 v[178:181], v219 offset:4096
	ds_read_b128 v[182:185], v219 offset:5120
	ds_read_b128 v[186:189], v219 offset:6144
	ds_read_b128 v[190:193], v219 offset:7168
	global_load_lds_dwordx4 v206, s[22:23]
	s_mov_b32 m0, s71
	s_nop 0
	global_load_lds_dwordx4 v208, s[22:23]
	s_waitcnt vmcnt(8)
	s_waitcnt lgkmcnt(0)
	s_barrier
	v_mfma_f32_16x16x32_bf16 v[126:129], v[130:133], v[162:165], v[126:129]
	v_mfma_f32_16x16x32_bf16 v[118:121], v[138:141], v[162:165], v[118:121]
	v_mfma_f32_16x16x32_bf16 v[110:113], v[130:133], v[170:173], v[110:113]
	v_mfma_f32_16x16x32_bf16 v[102:105], v[138:141], v[170:173], v[102:105]
	v_mfma_f32_16x16x32_bf16 v[94:97], v[130:133], v[178:181], v[94:97]
	v_mfma_f32_16x16x32_bf16 v[86:89], v[138:141], v[178:181], v[86:89]
	v_mfma_f32_16x16x32_bf16 v[78:81], v[130:133], v[186:189], v[78:81]
	v_mfma_f32_16x16x32_bf16 v[70:73], v[138:141], v[186:189], v[70:73]
	v_mfma_f32_16x16x32_bf16 v[126:129], v[134:137], v[166:169], v[126:129]
	v_mfma_f32_16x16x32_bf16 v[118:121], v[142:145], v[166:169], v[118:121]
	v_mfma_f32_16x16x32_bf16 v[110:113], v[134:137], v[174:177], v[110:113]
	v_mfma_f32_16x16x32_bf16 v[102:105], v[142:145], v[174:177], v[102:105]
	v_mfma_f32_16x16x32_bf16 v[94:97], v[134:137], v[182:185], v[94:97]
	v_mfma_f32_16x16x32_bf16 v[86:89], v[142:145], v[182:185], v[86:89]
	v_mfma_f32_16x16x32_bf16 v[78:81], v[134:137], v[190:193], v[78:81]
	v_mfma_f32_16x16x32_bf16 v[70:73], v[142:145], v[190:193], v[70:73]
	v_mfma_f32_16x16x32_bf16 v[122:125], v[146:149], v[162:165], v[122:125]
	v_mfma_f32_16x16x32_bf16 v[114:117], v[154:157], v[162:165], v[114:117]
	v_mfma_f32_16x16x32_bf16 v[106:109], v[146:149], v[170:173], v[106:109]
	v_mfma_f32_16x16x32_bf16 v[98:101], v[154:157], v[170:173], v[98:101]
	v_mfma_f32_16x16x32_bf16 v[90:93], v[146:149], v[178:181], v[90:93]
	v_mfma_f32_16x16x32_bf16 v[82:85], v[154:157], v[178:181], v[82:85]
	v_mfma_f32_16x16x32_bf16 v[74:77], v[146:149], v[186:189], v[74:77]
	v_mfma_f32_16x16x32_bf16 v[66:69], v[154:157], v[186:189], v[66:69]
	v_mfma_f32_16x16x32_bf16 v[122:125], v[150:153], v[166:169], v[122:125]
	v_mfma_f32_16x16x32_bf16 v[114:117], v[158:161], v[166:169], v[114:117]
	v_mfma_f32_16x16x32_bf16 v[106:109], v[150:153], v[174:177], v[106:109]
	v_mfma_f32_16x16x32_bf16 v[98:101], v[158:161], v[174:177], v[98:101]
	v_mfma_f32_16x16x32_bf16 v[90:93], v[150:153], v[182:185], v[90:93]
	v_mfma_f32_16x16x32_bf16 v[82:85], v[158:161], v[182:185], v[82:85]
	v_mfma_f32_16x16x32_bf16 v[74:77], v[150:153], v[190:193], v[74:77]
	v_mfma_f32_16x16x32_bf16 v[66:69], v[158:161], v[190:193], v[66:69]
	s_barrier
; #define PG8_STAGE(bufoff, gbase, voff) do { _Pragma("unroll") for (int _i = 0; _i < 2; ++_i) \
;         __builtin_amdgcn_global_load_lds((const unsigned*)((const char*)(gbase) + (voff)[_i]), (LAS unsigned*)(lds + (bufoff) + ldsw + _i * 8192), 16, 0, 0); } while (0)
; #define PG8_LDA(dst, b, h) do { _Pragma("unroll") for (int m = 0; m < 4; ++m) _Pragma("unroll") for (int k = 0; k < 2; ++k) dst[m][k] = *(const LAS bf16x8*)(lds + PG8_SA(b, h) + aoff + m * 2048 + k * 1024); } while (0)
; #define PG8_MMA(ai, bj, At, Bt) do { __builtin_amdgcn_s_setprio(1); _Pragma("unroll") for (int m = 0; m < 4; ++m) _Pragma("unroll") for (int n = 0; n < 2; ++n) _Pragma("unroll") for (int k = 0; k < 2; ++k) \
;         acc[ai][bj][m][n] = __builtin_amdgcn_mfma_f32_16x16x32_bf16(Bt[n][k], At[m][k], acc[ai][bj][m][n], 0, 0, 0); __builtin_amdgcn_s_setprio(0); } while (0)
; #define PG8_WAIT_V(n) asm volatile("s_waitcnt vmcnt(" #n ")" ::: "memory")
; #define PG8_WAIT_L(n) asm volatile("s_waitcnt lgkmcnt(" #n ")" ::: "memory")
; #define PG8_BAR __builtin_amdgcn_s_barrier()
; #define PG8_SCHED __builtin_amdgcn_sched_barrier(0)
; template <class Epi, class Sched>
; __device__ __forceinline__ void gemm_phase(LAS unsigned char* lds, const int lda, const int ldb, const int K, const Sched& S, const Epi& E) {
;     ...
;             PG8_LDA(At, 0, 1); PG8_STAGE(PG8_SB(0, 0), b2, voffB); PG8_STAGE(PG8_SB(0, 1), b2 + hstepB, voffB); PG8_STAGE(PG8_SA(0, 0), a2, voffA);
;             PG8_WAIT_V(8); PG8_WAIT_L(0); PG8_BAR; PG8_MMA(1, 0, At, B0); PG8_MMA(1, 1, At, B1); PG8_BAR; PG8_SCHED;
	s_mov_b32 m0, s72
	ds_read_b128 v[162:165], v219 offset:16384
	ds_read_b128 v[166:169], v219 offset:17408
	ds_read_b128 v[170:173], v219 offset:18432
	ds_read_b128 v[174:177], v219 offset:19456
	ds_read_b128 v[178:181], v219 offset:20480
	ds_read_b128 v[182:185], v219 offset:21504
	ds_read_b128 v[186:189], v219 offset:22528
	ds_read_b128 v[190:193], v219 offset:23552
	global_load_lds_dwordx4 v200, s[30:31]
	s_mov_b32 m0, s73
	s_nop 0
	global_load_lds_dwordx4 v196, s[30:31]
	s_mov_b32 m0, s74
	s_nop 0
	global_load_lds_dwordx4 v200, s[48:49]
	s_mov_b32 m0, s75
	s_nop 0
	global_load_lds_dwordx4 v196, s[48:49]
	s_mov_b32 m0, s37
	s_nop 0
	global_load_lds_dwordx4 v202, s[28:29]
	s_mov_b32 m0, s38
	s_nop 0
	global_load_lds_dwordx4 v198, s[28:29]
	s_waitcnt vmcnt(8)
	s_waitcnt lgkmcnt(0)
	s_barrier
	v_mfma_f32_16x16x32_bf16 v[62:65], v[130:133], v[162:165], v[62:65]
	v_mfma_f32_16x16x32_bf16 v[54:57], v[138:141], v[162:165], v[54:57]
	v_mfma_f32_16x16x32_bf16 v[46:49], v[130:133], v[170:173], v[46:49]
	v_mfma_f32_16x16x32_bf16 v[38:41], v[138:141], v[170:173], v[38:41]
	v_mfma_f32_16x16x32_bf16 v[30:33], v[130:133], v[178:181], v[30:33]
	v_mfma_f32_16x16x32_bf16 v[22:25], v[138:141], v[178:181], v[22:25]
	v_mfma_f32_16x16x32_bf16 v[14:17], v[130:133], v[186:189], v[14:17]
	v_mfma_f32_16x16x32_bf16 v[6:9], v[138:141], v[186:189], v[6:9]
	v_mfma_f32_16x16x32_bf16 v[62:65], v[134:137], v[166:169], v[62:65]
	v_mfma_f32_16x16x32_bf16 v[54:57], v[142:145], v[166:169], v[54:57]
	v_mfma_f32_16x16x32_bf16 v[46:49], v[134:137], v[174:177], v[46:49]
	v_mfma_f32_16x16x32_bf16 v[38:41], v[142:145], v[174:177], v[38:41]
	v_mfma_f32_16x16x32_bf16 v[30:33], v[134:137], v[182:185], v[30:33]
	v_mfma_f32_16x16x32_bf16 v[22:25], v[142:145], v[182:185], v[22:25]
	v_mfma_f32_16x16x32_bf16 v[14:17], v[134:137], v[190:193], v[14:17]
	v_mfma_f32_16x16x32_bf16 v[6:9], v[142:145], v[190:193], v[6:9]
	v_mfma_f32_16x16x32_bf16 v[58:61], v[146:149], v[162:165], v[58:61]
	v_mfma_f32_16x16x32_bf16 v[50:53], v[154:157], v[162:165], v[50:53]
	v_mfma_f32_16x16x32_bf16 v[42:45], v[146:149], v[170:173], v[42:45]
	v_mfma_f32_16x16x32_bf16 v[34:37], v[154:157], v[170:173], v[34:37]
	v_mfma_f32_16x16x32_bf16 v[26:29], v[146:149], v[178:181], v[26:29]
	v_mfma_f32_16x16x32_bf16 v[18:21], v[154:157], v[178:181], v[18:21]
	v_mfma_f32_16x16x32_bf16 v[10:13], v[146:149], v[186:189], v[10:13]
	v_mfma_f32_16x16x32_bf16 v[2:5], v[154:157], v[186:189], v[2:5]
	v_mfma_f32_16x16x32_bf16 v[58:61], v[150:153], v[166:169], v[58:61]
	v_mfma_f32_16x16x32_bf16 v[50:53], v[158:161], v[166:169], v[50:53]
	v_mfma_f32_16x16x32_bf16 v[42:45], v[150:153], v[174:177], v[42:45]
	v_mfma_f32_16x16x32_bf16 v[34:37], v[158:161], v[174:177], v[34:37]
	v_mfma_f32_16x16x32_bf16 v[26:29], v[150:153], v[182:185], v[26:29]
	v_mfma_f32_16x16x32_bf16 v[18:21], v[158:161], v[182:185], v[18:21]
	v_mfma_f32_16x16x32_bf16 v[10:13], v[150:153], v[190:193], v[10:13]
	v_mfma_f32_16x16x32_bf16 v[2:5], v[158:161], v[190:193], v[2:5]
	s_barrier
; #define PG8_STAGE(bufoff, gbase, voff) do { _Pragma("unroll") for (int _i = 0; _i < 2; ++_i) \
;         __builtin_amdgcn_global_load_lds((const unsigned*)((const char*)(gbase) + (voff)[_i]), (LAS unsigned*)(lds + (bufoff) + ldsw + _i * 8192), 16, 0, 0); } while (0)
; #define PG8_LDA(dst, b, h) do { _Pragma("unroll") for (int m = 0; m < 4; ++m) _Pragma("unroll") for (int k = 0; k < 2; ++k) dst[m][k] = *(const LAS bf16x8*)(lds + PG8_SA(b, h) + aoff + m * 2048 + k * 1024); } while (0)
; #define PG8_LDB(dst, b, h) do { _Pragma("unroll") for (int n = 0; n < 2; ++n) _Pragma("unroll") for (int k = 0; k < 2; ++k) dst[n][k] = *(const LAS bf16x8*)(lds + PG8_SB(b, h) + boff + n * 2048 + k * 1024); } while (0)
; #define PG8_MMA(ai, bj, At, Bt) do { __builtin_amdgcn_s_setprio(1); _Pragma("unroll") for (int m = 0; m < 4; ++m) _Pragma("unroll") for (int n = 0; n < 2; ++n) _Pragma("unroll") for (int k = 0; k < 2; ++k) \
;         acc[ai][bj][m][n] = __builtin_amdgcn_mfma_f32_16x16x32_bf16(Bt[n][k], At[m][k], acc[ai][bj][m][n], 0, 0, 0); __builtin_amdgcn_s_setprio(0); } while (0)
; #define PG8_WAIT_V(n) asm volatile("s_waitcnt vmcnt(" #n ")" ::: "memory")
; #define PG8_WAIT_L(n) asm volatile("s_waitcnt lgkmcnt(" #n ")" ::: "memory")
; #define PG8_BAR __builtin_amdgcn_s_barrier()
; #define PG8_SCHED __builtin_amdgcn_sched_barrier(0)
; template <class Epi, class Sched>
; __device__ __forceinline__ void gemm_phase(LAS unsigned char* lds, const int lda, const int ldb, const int K, const Sched& S, const Epi& E) {
;     ...
;             PG8_LDB(B0, 1, 0); PG8_LDB(B1, 1, 1); PG8_SCHED; PG8_LDA(At, 1, 0); PG8_STAGE(PG8_SA(0, 1), a2 + hstepA, voffA);
;             PG8_WAIT_V(8); PG8_WAIT_L(0); PG8_BAR; PG8_MMA(0, 0, At, B0); PG8_MMA(0, 1, At, B1); PG8_BAR; PG8_SCHED;
;             PG8_LDA(At, 1, 1); PG8_STAGE(PG8_SB(1, 0), b3, voffB); PG8_STAGE(PG8_SB(1, 1), b3 + hstepB, voffB); PG8_STAGE(PG8_SA(1, 0), a3, voffA);
;             PG8_WAIT_V(8); PG8_WAIT_L(0); PG8_BAR;
;             if (last) E.pre(cur, wr, fr, rsv);
;     __device__ __forceinline__ void pre(const pg8::Unit& u, int wr, int fr, float (&rsv)[8]) const {
;         const float* p = ss + u.pm * 256 + wr * 64 + fr;
; #pragma unroll
;         for (int ai = 0; ai < 2; ++ai)
; #pragma unroll
;             for (int m = 0; m < 4; ++m) rsv[ai * 4 + m] = p[ai * 128 + m * 16];
.Lpeel1_join:
	v_add_u32_e32 v130, s76, v195
	v_add_u32_e32 v142, s77, v195
	ds_read_b128 v[146:149], v130
	ds_read_b128 v[150:153], v130 offset:1024
	ds_read_b128 v[154:157], v130 offset:2048
	ds_read_b128 v[158:161], v130 offset:3072
	ds_read_b128 v[130:133], v142
	ds_read_b128 v[134:137], v142 offset:1024
	ds_read_b128 v[138:141], v142 offset:2048
	ds_read_b128 v[142:145], v142 offset:3072
	s_mov_b32 m0, s39
	ds_read_b128 v[162:165], v219 offset:32768
	ds_read_b128 v[166:169], v219 offset:33792
	ds_read_b128 v[170:173], v219 offset:34816
	ds_read_b128 v[174:177], v219 offset:35840
	ds_read_b128 v[178:181], v219 offset:36864
	ds_read_b128 v[182:185], v219 offset:37888
	ds_read_b128 v[186:189], v219 offset:38912
	ds_read_b128 v[190:193], v219 offset:39936
	global_load_lds_dwordx4 v202, s[26:27]
	s_mov_b32 m0, s40
	s_nop 0
	global_load_lds_dwordx4 v198, s[26:27]
	s_waitcnt vmcnt(8)
	s_waitcnt lgkmcnt(0)
	s_barrier
	v_mfma_f32_16x16x32_bf16 v[126:129], v[146:149], v[162:165], v[126:129]
	v_mfma_f32_16x16x32_bf16 v[118:121], v[154:157], v[162:165], v[118:121]
	v_mfma_f32_16x16x32_bf16 v[110:113], v[146:149], v[170:173], v[110:113]
	v_mfma_f32_16x16x32_bf16 v[102:105], v[154:157], v[170:173], v[102:105]
	v_mfma_f32_16x16x32_bf16 v[94:97], v[146:149], v[178:181], v[94:97]
	v_mfma_f32_16x16x32_bf16 v[86:89], v[154:157], v[178:181], v[86:89]
	v_mfma_f32_16x16x32_bf16 v[78:81], v[146:149], v[186:189], v[78:81]
	v_mfma_f32_16x16x32_bf16 v[70:73], v[154:157], v[186:189], v[70:73]
	v_mfma_f32_16x16x32_bf16 v[126:129], v[150:153], v[166:169], v[126:129]
	v_mfma_f32_16x16x32_bf16 v[118:121], v[158:161], v[166:169], v[118:121]
	v_mfma_f32_16x16x32_bf16 v[110:113], v[150:153], v[174:177], v[110:113]
	v_mfma_f32_16x16x32_bf16 v[102:105], v[158:161], v[174:177], v[102:105]
	v_mfma_f32_16x16x32_bf16 v[94:97], v[150:153], v[182:185], v[94:97]
	v_mfma_f32_16x16x32_bf16 v[86:89], v[158:161], v[182:185], v[86:89]
	v_mfma_f32_16x16x32_bf16 v[78:81], v[150:153], v[190:193], v[78:81]
	v_mfma_f32_16x16x32_bf16 v[70:73], v[158:161], v[190:193], v[70:73]
	v_mfma_f32_16x16x32_bf16 v[122:125], v[130:133], v[162:165], v[122:125]
	v_mfma_f32_16x16x32_bf16 v[114:117], v[138:141], v[162:165], v[114:117]
	v_mfma_f32_16x16x32_bf16 v[106:109], v[130:133], v[170:173], v[106:109]
	v_mfma_f32_16x16x32_bf16 v[98:101], v[138:141], v[170:173], v[98:101]
	v_mfma_f32_16x16x32_bf16 v[90:93], v[130:133], v[178:181], v[90:93]
	v_mfma_f32_16x16x32_bf16 v[82:85], v[138:141], v[178:181], v[82:85]
	v_mfma_f32_16x16x32_bf16 v[74:77], v[130:133], v[186:189], v[74:77]
	v_mfma_f32_16x16x32_bf16 v[66:69], v[138:141], v[186:189], v[66:69]
	v_mfma_f32_16x16x32_bf16 v[122:125], v[134:137], v[166:169], v[122:125]
	v_mfma_f32_16x16x32_bf16 v[114:117], v[142:145], v[166:169], v[114:117]
	v_mfma_f32_16x16x32_bf16 v[106:109], v[134:137], v[174:177], v[106:109]
	v_mfma_f32_16x16x32_bf16 v[98:101], v[142:145], v[174:177], v[98:101]
	v_mfma_f32_16x16x32_bf16 v[90:93], v[134:137], v[182:185], v[90:93]
	v_mfma_f32_16x16x32_bf16 v[82:85], v[142:145], v[182:185], v[82:85]
	v_mfma_f32_16x16x32_bf16 v[74:77], v[134:137], v[190:193], v[74:77]
	v_mfma_f32_16x16x32_bf16 v[66:69], v[142:145], v[190:193], v[66:69]
	s_barrier
	s_mov_b32 m0, s68
	ds_read_b128 v[186:189], v219 offset:49152
	ds_read_b128 v[190:193], v219 offset:50176
	ds_read_b128 v[178:181], v219 offset:51200
	ds_read_b128 v[182:185], v219 offset:52224
	ds_read_b128 v[170:173], v219 offset:53248
	ds_read_b128 v[174:177], v219 offset:54272
	ds_read_b128 v[162:165], v219 offset:55296
	ds_read_b128 v[166:169], v219 offset:56320
	global_load_lds_dwordx4 v230, s[30:31]
	s_mov_b32 m0, s21
	s_nop 0
	global_load_lds_dwordx4 v231, s[30:31]
	s_mov_b32 m0, s70
	s_nop 0
	global_load_lds_dwordx4 v200, s[24:25]
	s_mov_b32 m0, s69
	s_nop 0
	global_load_lds_dwordx4 v196, s[24:25]
	s_mov_b32 m0, s42
	s_nop 0
	global_load_lds_dwordx4 v232, s[28:29]
	s_mov_b32 m0, s43
	s_nop 0
	global_load_lds_dwordx4 v233, s[28:29]
	s_waitcnt vmcnt(8)
	s_waitcnt lgkmcnt(0)
	s_barrier
	s_cbranch_scc1 .LBB0_241
	global_load_dword v228, v[214:215], off
	global_load_dword v227, v[214:215], off offset:64
	global_load_dword v226, v[214:215], off offset:128
	global_load_dword v225, v[214:215], off offset:192
	global_load_dword v224, v[214:215], off offset:512
	global_load_dword v223, v[214:215], off offset:576
	global_load_dword v222, v[214:215], off offset:640
	global_load_dword v221, v[214:215], off offset:704
	s_branch .LBB0_241

; #define PG8_STAGE(bufoff, gbase, voff) do { _Pragma("unroll") for (int _i = 0; _i < 2; ++_i) \
;         __builtin_amdgcn_global_load_lds((const unsigned*)((const char*)(gbase) + (voff)[_i]), (LAS unsigned*)(lds + (bufoff) + ldsw + _i * 8192), 16, 0, 0); } while (0)
; #define PG8_LDA(dst, b, h) do { _Pragma("unroll") for (int m = 0; m < 4; ++m) _Pragma("unroll") for (int k = 0; k < 2; ++k) dst[m][k] = *(const LAS bf16x8*)(lds + PG8_SA(b, h) + aoff + m * 2048 + k * 1024); } while (0)
; #define PG8_LDB(dst, b, h) do { _Pragma("unroll") for (int n = 0; n < 2; ++n) _Pragma("unroll") for (int k = 0; k < 2; ++k) dst[n][k] = *(const LAS bf16x8*)(lds + PG8_SB(b, h) + boff + n * 2048 + k * 1024); } while (0)
; #define PG8_MMA(ai, bj, At, Bt) do { __builtin_amdgcn_s_setprio(1); _Pragma("unroll") for (int m = 0; m < 4; ++m) _Pragma("unroll") for (int n = 0; n < 2; ++n) _Pragma("unroll") for (int k = 0; k < 2; ++k) \
;         acc[ai][bj][m][n] = __builtin_amdgcn_mfma_f32_16x16x32_bf16(Bt[n][k], At[m][k], acc[ai][bj][m][n], 0, 0, 0); __builtin_amdgcn_s_setprio(0); } while (0)
; #define PG8_WAIT_V(n) asm volatile("s_waitcnt vmcnt(" #n ")" ::: "memory")
; #define PG8_WAIT_L(n) asm volatile("s_waitcnt lgkmcnt(" #n ")" ::: "memory")
; #define PG8_BAR __builtin_amdgcn_s_barrier()
; #define PG8_SCHED __builtin_amdgcn_sched_barrier(0)
; template <class Epi, class Sched>
; __device__ __forceinline__ void gemm_phase(LAS unsigned char* lds, const int lda, const int ldb, const int K, const Sched& S, const Epi& E) {
;     ...
;         for (int t = 0; t < nt; t += 2) {
;             const bool last = (t == nt - 2);
;             const char* a1 = cA + (size_t)(t + 1) * kstep;
;             const char* a2 = last ? nA : cA + (size_t)(t + 2) * kstep; const char* b2 = last ? nB : cB + (size_t)(t + 2) * kstep;
;             const char* a3 = a2 + kstep; const char* b3 = b2 + kstep;
;             PG8_LDB(B0, 0, 0); PG8_LDB(B1, 0, 1); PG8_SCHED; PG8_LDA(At, 0, 0); PG8_STAGE(PG8_SA(1, 1), a1 + hstepA, voffA);
;             PG8_WAIT_V(8); PG8_WAIT_L(0); PG8_BAR; PG8_MMA(0, 0, At, B0); PG8_MMA(0, 1, At, B1); PG8_BAR; PG8_SCHED;
;             PG8_LDA(At, 0, 1); PG8_STAGE(PG8_SB(0, 0), b2, voffB); PG8_STAGE(PG8_SB(0, 1), b2 + hstepB, voffB); PG8_STAGE(PG8_SA(0, 0), a2, voffA);
;             PG8_WAIT_V(8); PG8_WAIT_L(0); PG8_BAR; PG8_MMA(1, 0, At, B0); PG8_MMA(1, 1, At, B1); PG8_BAR; PG8_SCHED;
.LBB0_325:
	s_add_u32 s18, s18, 0xb0080
	s_addc_u32 s19, s19, 0
	s_add_u32 s48, s20, 0x100
	s_addc_u32 s49, s21, 0
	s_mov_b32 s50, -2
	s_waitcnt lgkmcnt(0)
	v_add_u32_e32 v192, 0x80, v156
	v_add_u32_e32 v193, 0x80, v160
	v_add_u32_e32 v220, 0x80, v154
	v_add_u32_e32 v221, 0x80, v158
	ds_read_b128 v[130:133], v188
	ds_read_b128 v[134:137], v188 offset:1024
	ds_read_b128 v[138:141], v188 offset:2048
	ds_read_b128 v[142:145], v188 offset:3072
	ds_read_b128 v[146:149], v189
	ds_read_b128 v[150:153], v189 offset:1024
	ds_read_b128 v[170:173], v189 offset:2048
	ds_read_b128 v[174:177], v189 offset:3072
	s_add_u32 s20, s18, 0xfff50080
	s_addc_u32 s21, s19, -1
	s_cmp_eq_u32 s50, 40
	s_cselect_b32 s23, s15, s21
	s_cselect_b32 s22, s14, s20
	s_cselect_b32 s21, s17, s49
	s_cselect_b32 s20, s16, s48
	s_add_i32 m0, s26, 0xc000
	ds_read_b128 v[178:181], v190
	ds_read_b128 v[182:185], v190 offset:1024
	ds_read_b128 v[196:199], v190 offset:2048
	ds_read_b128 v[200:203], v190 offset:3072
	ds_read_b128 v[204:207], v190 offset:4096
	ds_read_b128 v[208:211], v190 offset:5120
	ds_read_b128 v[212:215], v190 offset:6144
	ds_read_b128 v[216:219], v190 offset:7168
	global_load_lds_dwordx4 v162, s[18:19]
	s_add_i32 m0, s26, 0xe000
	s_nop 0
	global_load_lds_dwordx4 v164, s[18:19]
	s_waitcnt vmcnt(8)
	s_waitcnt lgkmcnt(0)
	s_barrier
	v_mfma_f32_16x16x32_bf16 v[126:129], v[130:133], v[178:181], 0
	v_mfma_f32_16x16x32_bf16 v[122:125], v[138:141], v[178:181], 0
	v_mfma_f32_16x16x32_bf16 v[110:113], v[130:133], v[196:199], 0
	v_mfma_f32_16x16x32_bf16 v[106:109], v[138:141], v[196:199], 0
	v_mfma_f32_16x16x32_bf16 v[94:97], v[130:133], v[204:207], 0
	v_mfma_f32_16x16x32_bf16 v[90:93], v[138:141], v[204:207], 0
	v_mfma_f32_16x16x32_bf16 v[78:81], v[130:133], v[212:215], 0
	v_mfma_f32_16x16x32_bf16 v[74:77], v[138:141], v[212:215], 0
	v_mfma_f32_16x16x32_bf16 v[126:129], v[134:137], v[182:185], v[126:129]
	v_mfma_f32_16x16x32_bf16 v[122:125], v[142:145], v[182:185], v[122:125]
	v_mfma_f32_16x16x32_bf16 v[110:113], v[134:137], v[200:203], v[110:113]
	v_mfma_f32_16x16x32_bf16 v[106:109], v[142:145], v[200:203], v[106:109]
	v_mfma_f32_16x16x32_bf16 v[94:97], v[134:137], v[208:211], v[94:97]
	v_mfma_f32_16x16x32_bf16 v[90:93], v[142:145], v[208:211], v[90:93]
	v_mfma_f32_16x16x32_bf16 v[78:81], v[134:137], v[216:219], v[78:81]
	v_mfma_f32_16x16x32_bf16 v[74:77], v[142:145], v[216:219], v[74:77]
	v_mfma_f32_16x16x32_bf16 v[118:121], v[146:149], v[178:181], 0
	v_mfma_f32_16x16x32_bf16 v[114:117], v[170:173], v[178:181], 0
	v_mfma_f32_16x16x32_bf16 v[102:105], v[146:149], v[196:199], 0
	v_mfma_f32_16x16x32_bf16 v[98:101], v[170:173], v[196:199], 0
	v_mfma_f32_16x16x32_bf16 v[86:89], v[146:149], v[204:207], 0
	v_mfma_f32_16x16x32_bf16 v[82:85], v[170:173], v[204:207], 0
	v_mfma_f32_16x16x32_bf16 v[70:73], v[146:149], v[212:215], 0
	v_mfma_f32_16x16x32_bf16 v[66:69], v[170:173], v[212:215], 0
	v_mfma_f32_16x16x32_bf16 v[118:121], v[150:153], v[182:185], v[118:121]
	v_mfma_f32_16x16x32_bf16 v[114:117], v[174:177], v[182:185], v[114:117]
	v_mfma_f32_16x16x32_bf16 v[102:105], v[150:153], v[200:203], v[102:105]
	v_mfma_f32_16x16x32_bf16 v[98:101], v[174:177], v[200:203], v[98:101]
	v_mfma_f32_16x16x32_bf16 v[86:89], v[150:153], v[208:211], v[86:89]
	v_mfma_f32_16x16x32_bf16 v[82:85], v[174:177], v[208:211], v[82:85]
	v_mfma_f32_16x16x32_bf16 v[70:73], v[150:153], v[216:219], v[70:73]
	v_mfma_f32_16x16x32_bf16 v[66:69], v[174:177], v[216:219], v[66:69]
	s_barrier
	s_add_i32 s51, s40, s25
	s_mov_b32 m0, s51
	ds_read_b128 v[178:181], v190 offset:16384
	ds_read_b128 v[182:185], v190 offset:17408
	ds_read_b128 v[196:199], v190 offset:18432
	ds_read_b128 v[200:203], v190 offset:19456
	ds_read_b128 v[204:207], v190 offset:20480
	ds_read_b128 v[208:211], v190 offset:21504
	ds_read_b128 v[212:215], v190 offset:22528
	ds_read_b128 v[216:219], v190 offset:23552
	global_load_lds_dwordx4 v156, s[20:21]
	s_add_i32 m0, s51, 0x2000
	s_add_u32 s62, s20, 0xb0000
	s_mov_b64 s[98:99], s[20:21]
	s_addc_u32 s63, s21, 0
	s_add_i32 s51, s41, s25
	global_load_lds_dwordx4 v160, s[20:21]
	s_mov_b32 m0, s51
	s_mov_b64 s[100:101], s[22:23]
	global_load_lds_dwordx4 v156, s[62:63]
	s_add_i32 m0, s51, 0x2000
	s_nop 0
	global_load_lds_dwordx4 v160, s[62:63]
	s_mov_b32 m0, s26
	s_nop 0
	global_load_lds_dwordx4 v154, s[22:23]
	s_mov_b32 m0, s27
	s_nop 0
	global_load_lds_dwordx4 v158, s[22:23]
	s_waitcnt vmcnt(8)
	s_waitcnt lgkmcnt(0)
	s_barrier
	v_mfma_f32_16x16x32_bf16 v[62:65], v[130:133], v[178:181], 0
	v_mfma_f32_16x16x32_bf16 v[58:61], v[138:141], v[178:181], 0
	v_mfma_f32_16x16x32_bf16 v[46:49], v[130:133], v[196:199], 0
	v_mfma_f32_16x16x32_bf16 v[42:45], v[138:141], v[196:199], 0
	v_mfma_f32_16x16x32_bf16 v[30:33], v[130:133], v[204:207], 0
	v_mfma_f32_16x16x32_bf16 v[26:29], v[138:141], v[204:207], 0
	v_mfma_f32_16x16x32_bf16 v[14:17], v[130:133], v[212:215], 0
	v_mfma_f32_16x16x32_bf16 v[10:13], v[138:141], v[212:215], 0
	v_mfma_f32_16x16x32_bf16 v[62:65], v[134:137], v[182:185], v[62:65]
	v_mfma_f32_16x16x32_bf16 v[58:61], v[142:145], v[182:185], v[58:61]
	v_mfma_f32_16x16x32_bf16 v[46:49], v[134:137], v[200:203], v[46:49]
	v_mfma_f32_16x16x32_bf16 v[42:45], v[142:145], v[200:203], v[42:45]
	v_mfma_f32_16x16x32_bf16 v[30:33], v[134:137], v[208:211], v[30:33]
	v_mfma_f32_16x16x32_bf16 v[26:29], v[142:145], v[208:211], v[26:29]
	v_mfma_f32_16x16x32_bf16 v[14:17], v[134:137], v[216:219], v[14:17]
	v_mfma_f32_16x16x32_bf16 v[10:13], v[142:145], v[216:219], v[10:13]
	v_mfma_f32_16x16x32_bf16 v[54:57], v[146:149], v[178:181], 0
	v_mfma_f32_16x16x32_bf16 v[50:53], v[170:173], v[178:181], 0
	v_mfma_f32_16x16x32_bf16 v[38:41], v[146:149], v[196:199], 0
	v_mfma_f32_16x16x32_bf16 v[34:37], v[170:173], v[196:199], 0
	v_mfma_f32_16x16x32_bf16 v[22:25], v[146:149], v[204:207], 0
	v_mfma_f32_16x16x32_bf16 v[18:21], v[170:173], v[204:207], 0
	v_mfma_f32_16x16x32_bf16 v[6:9], v[146:149], v[212:215], 0
	v_mfma_f32_16x16x32_bf16 v[2:5], v[170:173], v[212:215], 0
	v_mfma_f32_16x16x32_bf16 v[54:57], v[150:153], v[182:185], v[54:57]
	v_mfma_f32_16x16x32_bf16 v[50:53], v[174:177], v[182:185], v[50:53]
	v_mfma_f32_16x16x32_bf16 v[38:41], v[150:153], v[200:203], v[38:41]
	v_mfma_f32_16x16x32_bf16 v[34:37], v[174:177], v[200:203], v[34:37]
	v_mfma_f32_16x16x32_bf16 v[22:25], v[150:153], v[208:211], v[22:25]
	v_mfma_f32_16x16x32_bf16 v[18:21], v[174:177], v[208:211], v[18:21]
	v_mfma_f32_16x16x32_bf16 v[6:9], v[150:153], v[216:219], v[6:9]
	v_mfma_f32_16x16x32_bf16 v[2:5], v[174:177], v[216:219], v[2:5]
	s_barrier
	s_branch .Lpeel2_join
; #define PG8_STAGE(bufoff, gbase, voff) do { _Pragma("unroll") for (int _i = 0; _i < 2; ++_i) \
;         __builtin_amdgcn_global_load_lds((const unsigned*)((const char*)(gbase) + (voff)[_i]), (LAS unsigned*)(lds + (bufoff) + ldsw + _i * 8192), 16, 0, 0); } while (0)
; #define PG8_LDA(dst, b, h) do { _Pragma("unroll") for (int m = 0; m < 4; ++m) _Pragma("unroll") for (int k = 0; k < 2; ++k) dst[m][k] = *(const LAS bf16x8*)(lds + PG8_SA(b, h) + aoff + m * 2048 + k * 1024); } while (0)
; #define PG8_LDB(dst, b, h) do { _Pragma("unroll") for (int n = 0; n < 2; ++n) _Pragma("unroll") for (int k = 0; k < 2; ++k) dst[n][k] = *(const LAS bf16x8*)(lds + PG8_SB(b, h) + boff + n * 2048 + k * 1024); } while (0)
; #define PG8_MMA(ai, bj, At, Bt) do { __builtin_amdgcn_s_setprio(1); _Pragma("unroll") for (int m = 0; m < 4; ++m) _Pragma("unroll") for (int n = 0; n < 2; ++n) _Pragma("unroll") for (int k = 0; k < 2; ++k) \
;         acc[ai][bj][m][n] = __builtin_amdgcn_mfma_f32_16x16x32_bf16(Bt[n][k], At[m][k], acc[ai][bj][m][n], 0, 0, 0); __builtin_amdgcn_s_setprio(0); } while (0)
; #define PG8_WAIT_V(n) asm volatile("s_waitcnt vmcnt(" #n ")" ::: "memory")
; #define PG8_WAIT_L(n) asm volatile("s_waitcnt lgkmcnt(" #n ")" ::: "memory")
; #define PG8_BAR __builtin_amdgcn_s_barrier()
; #define PG8_SCHED __builtin_amdgcn_sched_barrier(0)
; template <class Epi, class Sched>
; __device__ __forceinline__ void gemm_phase(LAS unsigned char* lds, const int lda, const int ldb, const int K, const Sched& S, const Epi& E) {
;     ...
;             const bool last = (t == nt - 2);
;             const char* a1 = cA + (size_t)(t + 1) * kstep;
;             const char* a2 = last ? nA : cA + (size_t)(t + 2) * kstep; const char* b2 = last ? nB : cB + (size_t)(t + 2) * kstep;
;             const char* a3 = a2 + kstep; const char* b3 = b2 + kstep;
;             PG8_LDB(B0, 0, 0); PG8_LDB(B1, 0, 1); PG8_SCHED; PG8_LDA(At, 0, 0); PG8_STAGE(PG8_SA(1, 1), a1 + hstepA, voffA);
;             PG8_WAIT_V(8); PG8_WAIT_L(0); PG8_BAR; PG8_MMA(0, 0, At, B0); PG8_MMA(0, 1, At, B1); PG8_BAR; PG8_SCHED;
;             PG8_LDA(At, 0, 1); PG8_STAGE(PG8_SB(0, 0), b2, voffB); PG8_STAGE(PG8_SB(0, 1), b2 + hstepB, voffB); PG8_STAGE(PG8_SA(0, 0), a2, voffA);
;             PG8_WAIT_V(8); PG8_WAIT_L(0); PG8_BAR; PG8_MMA(1, 0, At, B0); PG8_MMA(1, 1, At, B1); PG8_BAR; PG8_SCHED;
.LBB0_326:
	ds_read_b128 v[130:133], v188
	ds_read_b128 v[134:137], v188 offset:1024
	ds_read_b128 v[138:141], v188 offset:2048
	ds_read_b128 v[142:145], v188 offset:3072
	ds_read_b128 v[146:149], v189
	ds_read_b128 v[150:153], v189 offset:1024
	ds_read_b128 v[170:173], v189 offset:2048
	ds_read_b128 v[174:177], v189 offset:3072
	s_add_u32 s20, s18, 0xfff50080
	s_addc_u32 s21, s19, -1
	s_cmp_eq_u32 s50, 40
	s_cselect_b32 s23, s15, s21
	s_cselect_b32 s22, s14, s20
	s_cselect_b32 s21, s17, s49
	s_cselect_b32 s20, s16, s48
	s_add_i32 m0, s26, 0xc000
	ds_read_b128 v[178:181], v190
	ds_read_b128 v[182:185], v190 offset:1024
	ds_read_b128 v[196:199], v190 offset:2048
	ds_read_b128 v[200:203], v190 offset:3072
	ds_read_b128 v[204:207], v190 offset:4096
	ds_read_b128 v[208:211], v190 offset:5120
	ds_read_b128 v[212:215], v190 offset:6144
	ds_read_b128 v[216:219], v190 offset:7168
	global_load_lds_dwordx4 v162, s[18:19]
	s_add_i32 m0, s26, 0xe000
	s_nop 0
	global_load_lds_dwordx4 v164, s[18:19]
	s_waitcnt vmcnt(8)
	s_waitcnt lgkmcnt(0)
	s_barrier
	v_mfma_f32_16x16x32_bf16 v[126:129], v[130:133], v[178:181], v[126:129]
	v_mfma_f32_16x16x32_bf16 v[122:125], v[138:141], v[178:181], v[122:125]
	v_mfma_f32_16x16x32_bf16 v[110:113], v[130:133], v[196:199], v[110:113]
	v_mfma_f32_16x16x32_bf16 v[106:109], v[138:141], v[196:199], v[106:109]
	v_mfma_f32_16x16x32_bf16 v[94:97], v[130:133], v[204:207], v[94:97]
	v_mfma_f32_16x16x32_bf16 v[90:93], v[138:141], v[204:207], v[90:93]
	v_mfma_f32_16x16x32_bf16 v[78:81], v[130:133], v[212:215], v[78:81]
	v_mfma_f32_16x16x32_bf16 v[74:77], v[138:141], v[212:215], v[74:77]
	v_mfma_f32_16x16x32_bf16 v[126:129], v[134:137], v[182:185], v[126:129]
	v_mfma_f32_16x16x32_bf16 v[122:125], v[142:145], v[182:185], v[122:125]
	v_mfma_f32_16x16x32_bf16 v[110:113], v[134:137], v[200:203], v[110:113]
	v_mfma_f32_16x16x32_bf16 v[106:109], v[142:145], v[200:203], v[106:109]
	v_mfma_f32_16x16x32_bf16 v[94:97], v[134:137], v[208:211], v[94:97]
	v_mfma_f32_16x16x32_bf16 v[90:93], v[142:145], v[208:211], v[90:93]
	v_mfma_f32_16x16x32_bf16 v[78:81], v[134:137], v[216:219], v[78:81]
	v_mfma_f32_16x16x32_bf16 v[74:77], v[142:145], v[216:219], v[74:77]
	v_mfma_f32_16x16x32_bf16 v[118:121], v[146:149], v[178:181], v[118:121]
	v_mfma_f32_16x16x32_bf16 v[114:117], v[170:173], v[178:181], v[114:117]
	v_mfma_f32_16x16x32_bf16 v[102:105], v[146:149], v[196:199], v[102:105]
	v_mfma_f32_16x16x32_bf16 v[98:101], v[170:173], v[196:199], v[98:101]
	v_mfma_f32_16x16x32_bf16 v[86:89], v[146:149], v[204:207], v[86:89]
	v_mfma_f32_16x16x32_bf16 v[82:85], v[170:173], v[204:207], v[82:85]
	v_mfma_f32_16x16x32_bf16 v[70:73], v[146:149], v[212:215], v[70:73]
	v_mfma_f32_16x16x32_bf16 v[66:69], v[170:173], v[212:215], v[66:69]
	v_mfma_f32_16x16x32_bf16 v[118:121], v[150:153], v[182:185], v[118:121]
	v_mfma_f32_16x16x32_bf16 v[114:117], v[174:177], v[182:185], v[114:117]
	v_mfma_f32_16x16x32_bf16 v[102:105], v[150:153], v[200:203], v[102:105]
	v_mfma_f32_16x16x32_bf16 v[98:101], v[174:177], v[200:203], v[98:101]
	v_mfma_f32_16x16x32_bf16 v[86:89], v[150:153], v[208:211], v[86:89]
	v_mfma_f32_16x16x32_bf16 v[82:85], v[174:177], v[208:211], v[82:85]
	v_mfma_f32_16x16x32_bf16 v[70:73], v[150:153], v[216:219], v[70:73]
	v_mfma_f32_16x16x32_bf16 v[66:69], v[174:177], v[216:219], v[66:69]
	s_barrier
	s_add_i32 s51, s40, s25
	s_mov_b32 m0, s51
	ds_read_b128 v[178:181], v190 offset:16384
	ds_read_b128 v[182:185], v190 offset:17408
	ds_read_b128 v[196:199], v190 offset:18432
	ds_read_b128 v[200:203], v190 offset:19456
	ds_read_b128 v[204:207], v190 offset:20480
	ds_read_b128 v[208:211], v190 offset:21504
	ds_read_b128 v[212:215], v190 offset:22528
	ds_read_b128 v[216:219], v190 offset:23552
	global_load_lds_dwordx4 v156, s[20:21]
	s_add_i32 m0, s51, 0x2000
	s_add_u32 s62, s20, 0xb0000
	s_mov_b64 s[98:99], s[20:21]
	s_addc_u32 s63, s21, 0
	s_add_i32 s51, s41, s25
	global_load_lds_dwordx4 v160, s[20:21]
	s_mov_b32 m0, s51
	s_mov_b64 s[100:101], s[22:23]
	global_load_lds_dwordx4 v156, s[62:63]
	s_add_i32 m0, s51, 0x2000
	s_nop 0
	global_load_lds_dwordx4 v160, s[62:63]
	s_mov_b32 m0, s26
	s_nop 0
	global_load_lds_dwordx4 v154, s[22:23]
	s_mov_b32 m0, s27
	s_nop 0
	global_load_lds_dwordx4 v158, s[22:23]
	s_waitcnt vmcnt(8)
	s_waitcnt lgkmcnt(0)
	s_barrier
	v_mfma_f32_16x16x32_bf16 v[62:65], v[130:133], v[178:181], v[62:65]
	v_mfma_f32_16x16x32_bf16 v[58:61], v[138:141], v[178:181], v[58:61]
	v_mfma_f32_16x16x32_bf16 v[46:49], v[130:133], v[196:199], v[46:49]
	v_mfma_f32_16x16x32_bf16 v[42:45], v[138:141], v[196:199], v[42:45]
	v_mfma_f32_16x16x32_bf16 v[30:33], v[130:133], v[204:207], v[30:33]
	v_mfma_f32_16x16x32_bf16 v[26:29], v[138:141], v[204:207], v[26:29]
	v_mfma_f32_16x16x32_bf16 v[14:17], v[130:133], v[212:215], v[14:17]
	v_mfma_f32_16x16x32_bf16 v[10:13], v[138:141], v[212:215], v[10:13]
	v_mfma_f32_16x16x32_bf16 v[62:65], v[134:137], v[182:185], v[62:65]
	v_mfma_f32_16x16x32_bf16 v[58:61], v[142:145], v[182:185], v[58:61]
	v_mfma_f32_16x16x32_bf16 v[46:49], v[134:137], v[200:203], v[46:49]
	v_mfma_f32_16x16x32_bf16 v[42:45], v[142:145], v[200:203], v[42:45]
	v_mfma_f32_16x16x32_bf16 v[30:33], v[134:137], v[208:211], v[30:33]
	v_mfma_f32_16x16x32_bf16 v[26:29], v[142:145], v[208:211], v[26:29]
	v_mfma_f32_16x16x32_bf16 v[14:17], v[134:137], v[216:219], v[14:17]
	v_mfma_f32_16x16x32_bf16 v[10:13], v[142:145], v[216:219], v[10:13]
	v_mfma_f32_16x16x32_bf16 v[54:57], v[146:149], v[178:181], v[54:57]
	v_mfma_f32_16x16x32_bf16 v[50:53], v[170:173], v[178:181], v[50:53]
	v_mfma_f32_16x16x32_bf16 v[38:41], v[146:149], v[196:199], v[38:41]
	v_mfma_f32_16x16x32_bf16 v[34:37], v[170:173], v[196:199], v[34:37]
	v_mfma_f32_16x16x32_bf16 v[22:25], v[146:149], v[204:207], v[22:25]
	v_mfma_f32_16x16x32_bf16 v[18:21], v[170:173], v[204:207], v[18:21]
	v_mfma_f32_16x16x32_bf16 v[6:9], v[146:149], v[212:215], v[6:9]
	v_mfma_f32_16x16x32_bf16 v[2:5], v[170:173], v[212:215], v[2:5]
	v_mfma_f32_16x16x32_bf16 v[54:57], v[150:153], v[182:185], v[54:57]
	v_mfma_f32_16x16x32_bf16 v[50:53], v[174:177], v[182:185], v[50:53]
	v_mfma_f32_16x16x32_bf16 v[38:41], v[150:153], v[200:203], v[38:41]
	v_mfma_f32_16x16x32_bf16 v[34:37], v[174:177], v[200:203], v[34:37]
	v_mfma_f32_16x16x32_bf16 v[22:25], v[150:153], v[208:211], v[22:25]
	v_mfma_f32_16x16x32_bf16 v[18:21], v[174:177], v[208:211], v[18:21]
	v_mfma_f32_16x16x32_bf16 v[6:9], v[150:153], v[216:219], v[6:9]
	v_mfma_f32_16x16x32_bf16 v[2:5], v[174:177], v[216:219], v[2:5]
	s_barrier
; #define PG8_STAGE(bufoff, gbase, voff) do { _Pragma("unroll") for (int _i = 0; _i < 2; ++_i) \
;         __builtin_amdgcn_global_load_lds((const unsigned*)((const char*)(gbase) + (voff)[_i]), (LAS unsigned*)(lds + (bufoff) + ldsw + _i * 8192), 16, 0, 0); } while (0)
; #define PG8_LDA(dst, b, h) do { _Pragma("unroll") for (int m = 0; m < 4; ++m) _Pragma("unroll") for (int k = 0; k < 2; ++k) dst[m][k] = *(const LAS bf16x8*)(lds + PG8_SA(b, h) + aoff + m * 2048 + k * 1024); } while (0)
; #define PG8_LDB(dst, b, h) do { _Pragma("unroll") for (int n = 0; n < 2; ++n) _Pragma("unroll") for (int k = 0; k < 2; ++k) dst[n][k] = *(const LAS bf16x8*)(lds + PG8_SB(b, h) + boff + n * 2048 + k * 1024); } while (0)
; #define PG8_MMA(ai, bj, At, Bt) do { __builtin_amdgcn_s_setprio(1); _Pragma("unroll") for (int m = 0; m < 4; ++m) _Pragma("unroll") for (int n = 0; n < 2; ++n) _Pragma("unroll") for (int k = 0; k < 2; ++k) \
;         acc[ai][bj][m][n] = __builtin_amdgcn_mfma_f32_16x16x32_bf16(Bt[n][k], At[m][k], acc[ai][bj][m][n], 0, 0, 0); __builtin_amdgcn_s_setprio(0); } while (0)
; #define PG8_WAIT_V(n) asm volatile("s_waitcnt vmcnt(" #n ")" ::: "memory")
; #define PG8_WAIT_L(n) asm volatile("s_waitcnt lgkmcnt(" #n ")" ::: "memory")
; #define PG8_BAR __builtin_amdgcn_s_barrier()
; #define PG8_SCHED __builtin_amdgcn_sched_barrier(0)
; template <class Epi, class Sched>
; __device__ __forceinline__ void gemm_phase(LAS unsigned char* lds, const int lda, const int ldb, const int K, const Sched& S, const Epi& E) {
;     ...
;             PG8_LDB(B0, 1, 0); PG8_LDB(B1, 1, 1); PG8_SCHED; PG8_LDA(At, 1, 0); PG8_STAGE(PG8_SA(0, 1), a2 + hstepA, voffA);
;             PG8_WAIT_V(8); PG8_WAIT_L(0); PG8_BAR; PG8_MMA(0, 0, At, B0); PG8_MMA(0, 1, At, B1); PG8_BAR; PG8_SCHED;
;             PG8_LDA(At, 1, 1); PG8_STAGE(PG8_SB(1, 0), b3, voffB); PG8_STAGE(PG8_SB(1, 1), b3 + hstepB, voffB); PG8_STAGE(PG8_SA(1, 0), a3, voffA);
;             PG8_WAIT_V(8); PG8_WAIT_L(0); PG8_BAR;
;             if (last) E.pre(cur, wr, fr, rsv);
;             PG8_MMA(1, 0, At, B0); PG8_MMA(1, 1, At, B1); PG8_BAR; PG8_SCHED;
;         }
;         if (wr == 0) PG8_BAR;
.Lpeel2_join:
	s_add_i32 s51, 0, 0x18000
	s_add_i32 s62, 0, 0x1c000
	v_add_u32_e32 v142, s51, v186
	v_add_u32_e32 v174, s62, v186
	ds_read_b128 v[130:133], v142
	ds_read_b128 v[134:137], v142 offset:1024
	ds_read_b128 v[138:141], v142 offset:2048
	ds_read_b128 v[142:145], v142 offset:3072
	ds_read_b128 v[146:149], v174
	ds_read_b128 v[150:153], v174 offset:1024
	ds_read_b128 v[170:173], v174 offset:2048
	ds_read_b128 v[174:177], v174 offset:3072
	s_add_u32 s22, s22, 0xb0000
	s_addc_u32 s23, s23, 0
	s_mov_b32 m0, s28
	ds_read_b128 v[178:181], v190 offset:32768
	ds_read_b128 v[182:185], v190 offset:33792
	ds_read_b128 v[196:199], v190 offset:34816
	ds_read_b128 v[200:203], v190 offset:35840
	ds_read_b128 v[204:207], v190 offset:36864
	ds_read_b128 v[208:211], v190 offset:37888
	ds_read_b128 v[212:215], v190 offset:38912
	ds_read_b128 v[216:219], v190 offset:39936
	global_load_lds_dwordx4 v154, s[22:23]
	s_mov_b32 m0, s29
	s_nop 0
	global_load_lds_dwordx4 v158, s[22:23]
	s_waitcnt vmcnt(8)
	s_waitcnt lgkmcnt(0)
	s_barrier
	v_mfma_f32_16x16x32_bf16 v[126:129], v[130:133], v[178:181], v[126:129]
	v_mfma_f32_16x16x32_bf16 v[122:125], v[138:141], v[178:181], v[122:125]
	v_mfma_f32_16x16x32_bf16 v[110:113], v[130:133], v[196:199], v[110:113]
	v_mfma_f32_16x16x32_bf16 v[106:109], v[138:141], v[196:199], v[106:109]
	v_mfma_f32_16x16x32_bf16 v[94:97], v[130:133], v[204:207], v[94:97]
	v_mfma_f32_16x16x32_bf16 v[90:93], v[138:141], v[204:207], v[90:93]
	v_mfma_f32_16x16x32_bf16 v[78:81], v[130:133], v[212:215], v[78:81]
	v_mfma_f32_16x16x32_bf16 v[74:77], v[138:141], v[212:215], v[74:77]
	v_mfma_f32_16x16x32_bf16 v[126:129], v[134:137], v[182:185], v[126:129]
	v_mfma_f32_16x16x32_bf16 v[122:125], v[142:145], v[182:185], v[122:125]
	v_mfma_f32_16x16x32_bf16 v[110:113], v[134:137], v[200:203], v[110:113]
	v_mfma_f32_16x16x32_bf16 v[106:109], v[142:145], v[200:203], v[106:109]
	v_mfma_f32_16x16x32_bf16 v[94:97], v[134:137], v[208:211], v[94:97]
	v_mfma_f32_16x16x32_bf16 v[90:93], v[142:145], v[208:211], v[90:93]
	v_mfma_f32_16x16x32_bf16 v[78:81], v[134:137], v[216:219], v[78:81]
	v_mfma_f32_16x16x32_bf16 v[74:77], v[142:145], v[216:219], v[74:77]
	v_mfma_f32_16x16x32_bf16 v[118:121], v[146:149], v[178:181], v[118:121]
	v_mfma_f32_16x16x32_bf16 v[114:117], v[170:173], v[178:181], v[114:117]
	v_mfma_f32_16x16x32_bf16 v[102:105], v[146:149], v[196:199], v[102:105]
	v_mfma_f32_16x16x32_bf16 v[98:101], v[170:173], v[196:199], v[98:101]
	v_mfma_f32_16x16x32_bf16 v[86:89], v[146:149], v[204:207], v[86:89]
	v_mfma_f32_16x16x32_bf16 v[82:85], v[170:173], v[204:207], v[82:85]
	v_mfma_f32_16x16x32_bf16 v[70:73], v[146:149], v[212:215], v[70:73]
	v_mfma_f32_16x16x32_bf16 v[66:69], v[170:173], v[212:215], v[66:69]
	v_mfma_f32_16x16x32_bf16 v[118:121], v[150:153], v[182:185], v[118:121]
	v_mfma_f32_16x16x32_bf16 v[114:117], v[174:177], v[182:185], v[114:117]
	v_mfma_f32_16x16x32_bf16 v[102:105], v[150:153], v[200:203], v[102:105]
	v_mfma_f32_16x16x32_bf16 v[98:101], v[174:177], v[200:203], v[98:101]
	v_mfma_f32_16x16x32_bf16 v[86:89], v[150:153], v[208:211], v[86:89]
	v_mfma_f32_16x16x32_bf16 v[82:85], v[174:177], v[208:211], v[82:85]
	v_mfma_f32_16x16x32_bf16 v[70:73], v[150:153], v[216:219], v[70:73]
	v_mfma_f32_16x16x32_bf16 v[66:69], v[174:177], v[216:219], v[66:69]
	s_barrier
	s_add_i32 s22, s51, s25
	s_mov_b32 m0, s22
	ds_read_b128 v[178:181], v190 offset:49152
	ds_read_b128 v[182:185], v190 offset:50176
	ds_read_b128 v[196:199], v190 offset:51200
	ds_read_b128 v[200:203], v190 offset:52224
	ds_read_b128 v[204:207], v190 offset:53248
	ds_read_b128 v[208:211], v190 offset:54272
	ds_read_b128 v[212:215], v190 offset:55296
	ds_read_b128 v[216:219], v190 offset:56320
	global_load_lds_dwordx4 v192, s[20:21]
	s_add_i32 m0, s22, 0x2000
	s_add_u32 s20, s20, 0xb0080
	s_addc_u32 s21, s21, 0
	s_add_i32 s22, s62, s25
	global_load_lds_dwordx4 v193, s[98:99]
	s_mov_b32 m0, s22
	s_nop 0
	global_load_lds_dwordx4 v156, s[20:21]
	s_add_i32 m0, s22, 0x2000
	s_nop 0
	global_load_lds_dwordx4 v160, s[20:21]
	s_mov_b32 m0, s33
	s_nop 0
	global_load_lds_dwordx4 v220, s[100:101]
	s_mov_b32 m0, s36
	s_nop 0
	global_load_lds_dwordx4 v221, s[100:101]
	s_waitcnt vmcnt(8)
	s_waitcnt lgkmcnt(0)
	s_barrier
	v_mfma_f32_16x16x32_bf16 v[62:65], v[130:133], v[178:181], v[62:65]
	v_mfma_f32_16x16x32_bf16 v[58:61], v[138:141], v[178:181], v[58:61]
	v_mfma_f32_16x16x32_bf16 v[46:49], v[130:133], v[196:199], v[46:49]
	v_mfma_f32_16x16x32_bf16 v[42:45], v[138:141], v[196:199], v[42:45]
	v_mfma_f32_16x16x32_bf16 v[30:33], v[130:133], v[204:207], v[30:33]
	v_mfma_f32_16x16x32_bf16 v[26:29], v[138:141], v[204:207], v[26:29]
	v_mfma_f32_16x16x32_bf16 v[14:17], v[130:133], v[212:215], v[14:17]
	v_mfma_f32_16x16x32_bf16 v[10:13], v[138:141], v[212:215], v[10:13]
	v_mfma_f32_16x16x32_bf16 v[62:65], v[134:137], v[182:185], v[62:65]
	v_mfma_f32_16x16x32_bf16 v[58:61], v[142:145], v[182:185], v[58:61]
	v_mfma_f32_16x16x32_bf16 v[46:49], v[134:137], v[200:203], v[46:49]
	v_mfma_f32_16x16x32_bf16 v[42:45], v[142:145], v[200:203], v[42:45]
	v_mfma_f32_16x16x32_bf16 v[30:33], v[134:137], v[208:211], v[30:33]
	v_mfma_f32_16x16x32_bf16 v[26:29], v[142:145], v[208:211], v[26:29]
	v_mfma_f32_16x16x32_bf16 v[14:17], v[134:137], v[216:219], v[14:17]
	v_mfma_f32_16x16x32_bf16 v[10:13], v[142:145], v[216:219], v[10:13]
	v_mfma_f32_16x16x32_bf16 v[54:57], v[146:149], v[178:181], v[54:57]
	v_mfma_f32_16x16x32_bf16 v[50:53], v[170:173], v[178:181], v[50:53]
	v_mfma_f32_16x16x32_bf16 v[38:41], v[146:149], v[196:199], v[38:41]
	v_mfma_f32_16x16x32_bf16 v[34:37], v[170:173], v[196:199], v[34:37]
	v_mfma_f32_16x16x32_bf16 v[22:25], v[146:149], v[204:207], v[22:25]
	v_mfma_f32_16x16x32_bf16 v[18:21], v[170:173], v[204:207], v[18:21]
	v_mfma_f32_16x16x32_bf16 v[6:9], v[146:149], v[212:215], v[6:9]
	v_mfma_f32_16x16x32_bf16 v[2:5], v[170:173], v[212:215], v[2:5]
	v_mfma_f32_16x16x32_bf16 v[54:57], v[150:153], v[182:185], v[54:57]
	v_mfma_f32_16x16x32_bf16 v[50:53], v[174:177], v[182:185], v[50:53]
	v_mfma_f32_16x16x32_bf16 v[38:41], v[150:153], v[200:203], v[38:41]
	v_mfma_f32_16x16x32_bf16 v[34:37], v[174:177], v[200:203], v[34:37]
	v_mfma_f32_16x16x32_bf16 v[22:25], v[150:153], v[208:211], v[22:25]
	v_mfma_f32_16x16x32_bf16 v[18:21], v[174:177], v[208:211], v[18:21]
	v_mfma_f32_16x16x32_bf16 v[6:9], v[150:153], v[216:219], v[6:9]
	v_mfma_f32_16x16x32_bf16 v[2:5], v[174:177], v[216:219], v[2:5]
	s_barrier
	s_add_i32 s50, s50, 2
	s_add_u32 s18, s18, 0x100
	s_addc_u32 s19, s19, 0
	s_add_u32 s48, s48, 0x100
	s_addc_u32 s49, s49, 0
	s_cmp_gt_u32 s50, 41
	s_cbranch_scc0 .LBB0_326
	s_and_b64 vcc, exec, s[12:13]
	s_cbranch_vccz .LBB0_329
	s_barrier

; #define PG8_STAGE(bufoff, gbase, voff) do { _Pragma("unroll") for (int _i = 0; _i < 2; ++_i) \
;         __builtin_amdgcn_global_load_lds((const unsigned*)((const char*)(gbase) + (voff)[_i]), (LAS unsigned*)(lds + (bufoff) + ldsw + _i * 8192), 16, 0, 0); } while (0)
; #define PG8_LDA(dst, b, h) do { _Pragma("unroll") for (int m = 0; m < 4; ++m) _Pragma("unroll") for (int k = 0; k < 2; ++k) dst[m][k] = *(const LAS bf16x8*)(lds + PG8_SA(b, h) + aoff + m * 2048 + k * 1024); } while (0)
; #define PG8_LDB(dst, b, h) do { _Pragma("unroll") for (int n = 0; n < 2; ++n) _Pragma("unroll") for (int k = 0; k < 2; ++k) dst[n][k] = *(const LAS bf16x8*)(lds + PG8_SB(b, h) + boff + n * 2048 + k * 1024); } while (0)
; #define PG8_MMA(ai, bj, At, Bt) do { __builtin_amdgcn_s_setprio(1); _Pragma("unroll") for (int m = 0; m < 4; ++m) _Pragma("unroll") for (int n = 0; n < 2; ++n) _Pragma("unroll") for (int k = 0; k < 2; ++k) \
;         acc[ai][bj][m][n] = __builtin_amdgcn_mfma_f32_16x16x32_bf16(Bt[n][k], At[m][k], acc[ai][bj][m][n], 0, 0, 0); __builtin_amdgcn_s_setprio(0); } while (0)
; #define PG8_WAIT_V(n) asm volatile("s_waitcnt vmcnt(" #n ")" ::: "memory")
; #define PG8_WAIT_L(n) asm volatile("s_waitcnt lgkmcnt(" #n ")" ::: "memory")
; #define PG8_BAR __builtin_amdgcn_s_barrier()
; #define PG8_SCHED __builtin_amdgcn_sched_barrier(0)
; template <class Epi, class Sched>
; __device__ __forceinline__ void gemm_phase(LAS unsigned char* lds, const int lda, const int ldb, const int K, const Sched& S, const Epi& E) {
;     ...
;         for (int t = 0; t < nt; t += 2) {
;             const bool last = (t == nt - 2);
;             const char* a1 = cA + (size_t)(t + 1) * kstep;
;             const char* a2 = last ? nA : cA + (size_t)(t + 2) * kstep; const char* b2 = last ? nB : cB + (size_t)(t + 2) * kstep;
;             const char* a3 = a2 + kstep; const char* b3 = b2 + kstep;
;             PG8_LDB(B0, 0, 0); PG8_LDB(B1, 0, 1); PG8_SCHED; PG8_LDA(At, 0, 0); PG8_STAGE(PG8_SA(1, 1), a1 + hstepA, voffA);
;             PG8_WAIT_V(8); PG8_WAIT_L(0); PG8_BAR; PG8_MMA(0, 0, At, B0); PG8_MMA(0, 1, At, B1); PG8_BAR; PG8_SCHED;
;             PG8_LDA(At, 0, 1); PG8_STAGE(PG8_SB(0, 0), b2, voffB); PG8_STAGE(PG8_SB(0, 1), b2 + hstepB, voffB); PG8_STAGE(PG8_SA(0, 0), a2, voffA);
;             PG8_WAIT_V(8); PG8_WAIT_L(0); PG8_BAR; PG8_MMA(1, 0, At, B0); PG8_MMA(1, 1, At, B1); PG8_BAR; PG8_SCHED;
.LBB0_424:
	s_lshl_b32 s4, s4, 8
	s_ashr_i32 s5, s4, 31
	s_add_u32 s6, s6, 0x40080
	s_addc_u32 s7, s7, 0
	v_lshl_add_u64 v[220:221], s[4:5], 2, v[206:207]
	s_add_u32 s5, s8, 0x100
	s_addc_u32 s51, s9, 0
	s_mov_b32 s69, -2
	v_add_u32_e32 v234, 0x80, v202
	v_add_u32_e32 v235, 0x80, v198
	v_add_u32_e32 v236, 0x80, v204
	v_add_u32_e32 v237, 0x80, v200
	s_add_u32 s8, s6, 0xfffc0080
	s_addc_u32 s9, s7, -1
	s_cmp_eq_u32 s69, 12
	s_cselect_b32 s13, s71, s9
	s_cselect_b32 s12, s70, s8
	s_cselect_b32 s15, s73, s51
	s_cselect_b32 s14, s72, s5
	s_add_i32 s81, s63, s36
	ds_read_b128 v[130:133], v222
	ds_read_b128 v[134:137], v222 offset:1024
	ds_read_b128 v[138:141], v222 offset:2048
	ds_read_b128 v[142:145], v222 offset:3072
	ds_read_b128 v[146:149], v223
	ds_read_b128 v[150:153], v223 offset:1024
	ds_read_b128 v[154:157], v223 offset:2048
	ds_read_b128 v[158:161], v223 offset:3072
	s_add_i32 m0, s39, 0xc000
	s_add_i32 s80, s39, 0xe000
	s_add_i32 s82, s81, 0x2000
	s_add_u32 s16, s14, 0x40000
	s_addc_u32 s17, s15, 0
	s_add_i32 s83, s64, s36
	s_add_i32 s84, s83, 0x2000
	s_add_i32 s85, 0, 0x18000
	s_add_i32 s86, 0, 0x1c000
	s_add_u32 s10, s12, 0x40000
	s_addc_u32 s11, s13, 0
	s_add_i32 s75, s85, s36
	s_add_i32 s74, s75, 0x2000
	s_add_u32 s8, s14, 0x40080
	s_addc_u32 s9, s15, 0
	s_add_i32 s79, s86, s36
	s_add_i32 s78, s79, 0x2000
	s_cmp_lg_u32 s69, 12
	ds_read_b128 v[162:165], v224
	ds_read_b128 v[166:169], v224 offset:1024
	ds_read_b128 v[170:173], v224 offset:2048
	ds_read_b128 v[174:177], v224 offset:3072
	ds_read_b128 v[178:181], v224 offset:4096
	ds_read_b128 v[182:185], v224 offset:5120
	ds_read_b128 v[186:189], v224 offset:6144
	ds_read_b128 v[190:193], v224 offset:7168
	global_load_lds_dwordx4 v212, s[6:7]
	s_mov_b32 m0, s80
	s_nop 0
	global_load_lds_dwordx4 v214, s[6:7]
	s_waitcnt vmcnt(8)
	s_waitcnt lgkmcnt(0)
	s_barrier
	v_mfma_f32_16x16x32_bf16 v[126:129], v[130:133], v[162:165], 0
	v_mfma_f32_16x16x32_bf16 v[118:121], v[138:141], v[162:165], 0
	v_mfma_f32_16x16x32_bf16 v[110:113], v[130:133], v[170:173], 0
	v_mfma_f32_16x16x32_bf16 v[102:105], v[138:141], v[170:173], 0
	v_mfma_f32_16x16x32_bf16 v[94:97], v[130:133], v[178:181], 0
	v_mfma_f32_16x16x32_bf16 v[86:89], v[138:141], v[178:181], 0
	v_mfma_f32_16x16x32_bf16 v[78:81], v[130:133], v[186:189], 0
	v_mfma_f32_16x16x32_bf16 v[70:73], v[138:141], v[186:189], 0
	v_mfma_f32_16x16x32_bf16 v[126:129], v[134:137], v[166:169], v[126:129]
	v_mfma_f32_16x16x32_bf16 v[118:121], v[142:145], v[166:169], v[118:121]
	v_mfma_f32_16x16x32_bf16 v[110:113], v[134:137], v[174:177], v[110:113]
	v_mfma_f32_16x16x32_bf16 v[102:105], v[142:145], v[174:177], v[102:105]
	v_mfma_f32_16x16x32_bf16 v[94:97], v[134:137], v[182:185], v[94:97]
	v_mfma_f32_16x16x32_bf16 v[86:89], v[142:145], v[182:185], v[86:89]
	v_mfma_f32_16x16x32_bf16 v[78:81], v[134:137], v[190:193], v[78:81]
	v_mfma_f32_16x16x32_bf16 v[70:73], v[142:145], v[190:193], v[70:73]
	v_mfma_f32_16x16x32_bf16 v[122:125], v[146:149], v[162:165], 0
	v_mfma_f32_16x16x32_bf16 v[114:117], v[154:157], v[162:165], 0
	v_mfma_f32_16x16x32_bf16 v[106:109], v[146:149], v[170:173], 0
	v_mfma_f32_16x16x32_bf16 v[98:101], v[154:157], v[170:173], 0
	v_mfma_f32_16x16x32_bf16 v[90:93], v[146:149], v[178:181], 0
	v_mfma_f32_16x16x32_bf16 v[82:85], v[154:157], v[178:181], 0
	v_mfma_f32_16x16x32_bf16 v[74:77], v[146:149], v[186:189], 0
	v_mfma_f32_16x16x32_bf16 v[66:69], v[154:157], v[186:189], 0
	v_mfma_f32_16x16x32_bf16 v[122:125], v[150:153], v[166:169], v[122:125]
	v_mfma_f32_16x16x32_bf16 v[114:117], v[158:161], v[166:169], v[114:117]
	v_mfma_f32_16x16x32_bf16 v[106:109], v[150:153], v[174:177], v[106:109]
	v_mfma_f32_16x16x32_bf16 v[98:101], v[158:161], v[174:177], v[98:101]
	v_mfma_f32_16x16x32_bf16 v[90:93], v[150:153], v[182:185], v[90:93]
	v_mfma_f32_16x16x32_bf16 v[82:85], v[158:161], v[182:185], v[82:85]
	v_mfma_f32_16x16x32_bf16 v[74:77], v[150:153], v[190:193], v[74:77]
	v_mfma_f32_16x16x32_bf16 v[66:69], v[158:161], v[190:193], v[66:69]
	s_barrier
	s_mov_b32 m0, s81
	ds_read_b128 v[162:165], v224 offset:16384
	ds_read_b128 v[166:169], v224 offset:17408
	ds_read_b128 v[170:173], v224 offset:18432
	ds_read_b128 v[174:177], v224 offset:19456
	ds_read_b128 v[178:181], v224 offset:20480
	ds_read_b128 v[182:185], v224 offset:21504
	ds_read_b128 v[186:189], v224 offset:22528
	ds_read_b128 v[190:193], v224 offset:23552
	global_load_lds_dwordx4 v202, s[14:15]
	s_mov_b32 m0, s82
	s_nop 0
	global_load_lds_dwordx4 v198, s[14:15]
	s_mov_b32 m0, s83
	s_nop 0
	global_load_lds_dwordx4 v202, s[16:17]
	s_mov_b32 m0, s84
	s_nop 0
	global_load_lds_dwordx4 v198, s[16:17]
	s_mov_b32 m0, s39
	s_nop 0
	global_load_lds_dwordx4 v204, s[12:13]
	s_mov_b32 m0, s40
	s_nop 0
	global_load_lds_dwordx4 v200, s[12:13]
	s_waitcnt vmcnt(8)
	s_waitcnt lgkmcnt(0)
	s_barrier
	v_mfma_f32_16x16x32_bf16 v[62:65], v[130:133], v[162:165], 0
	v_mfma_f32_16x16x32_bf16 v[54:57], v[138:141], v[162:165], 0
	v_mfma_f32_16x16x32_bf16 v[46:49], v[130:133], v[170:173], 0
	v_mfma_f32_16x16x32_bf16 v[38:41], v[138:141], v[170:173], 0
	v_mfma_f32_16x16x32_bf16 v[30:33], v[130:133], v[178:181], 0
	v_mfma_f32_16x16x32_bf16 v[22:25], v[138:141], v[178:181], 0
	v_mfma_f32_16x16x32_bf16 v[14:17], v[130:133], v[186:189], 0
	v_mfma_f32_16x16x32_bf16 v[6:9], v[138:141], v[186:189], 0
	v_mfma_f32_16x16x32_bf16 v[62:65], v[134:137], v[166:169], v[62:65]
	v_mfma_f32_16x16x32_bf16 v[54:57], v[142:145], v[166:169], v[54:57]
	v_mfma_f32_16x16x32_bf16 v[46:49], v[134:137], v[174:177], v[46:49]
	v_mfma_f32_16x16x32_bf16 v[38:41], v[142:145], v[174:177], v[38:41]
	v_mfma_f32_16x16x32_bf16 v[30:33], v[134:137], v[182:185], v[30:33]
	v_mfma_f32_16x16x32_bf16 v[22:25], v[142:145], v[182:185], v[22:25]
	v_mfma_f32_16x16x32_bf16 v[14:17], v[134:137], v[190:193], v[14:17]
	v_mfma_f32_16x16x32_bf16 v[6:9], v[142:145], v[190:193], v[6:9]
	v_mfma_f32_16x16x32_bf16 v[58:61], v[146:149], v[162:165], 0
	v_mfma_f32_16x16x32_bf16 v[50:53], v[154:157], v[162:165], 0
	v_mfma_f32_16x16x32_bf16 v[42:45], v[146:149], v[170:173], 0
	v_mfma_f32_16x16x32_bf16 v[34:37], v[154:157], v[170:173], 0
	v_mfma_f32_16x16x32_bf16 v[26:29], v[146:149], v[178:181], 0
	v_mfma_f32_16x16x32_bf16 v[18:21], v[154:157], v[178:181], 0
	v_mfma_f32_16x16x32_bf16 v[10:13], v[146:149], v[186:189], 0
	v_mfma_f32_16x16x32_bf16 v[2:5], v[154:157], v[186:189], 0
	v_mfma_f32_16x16x32_bf16 v[58:61], v[150:153], v[166:169], v[58:61]
	v_mfma_f32_16x16x32_bf16 v[50:53], v[158:161], v[166:169], v[50:53]
	v_mfma_f32_16x16x32_bf16 v[42:45], v[150:153], v[174:177], v[42:45]
	v_mfma_f32_16x16x32_bf16 v[34:37], v[158:161], v[174:177], v[34:37]
	v_mfma_f32_16x16x32_bf16 v[26:29], v[150:153], v[182:185], v[26:29]
	v_mfma_f32_16x16x32_bf16 v[18:21], v[158:161], v[182:185], v[18:21]
	v_mfma_f32_16x16x32_bf16 v[10:13], v[150:153], v[190:193], v[10:13]
	v_mfma_f32_16x16x32_bf16 v[2:5], v[158:161], v[190:193], v[2:5]
	s_barrier
	s_branch .Lpeel3_join
; #define PG8_STAGE(bufoff, gbase, voff) do { _Pragma("unroll") for (int _i = 0; _i < 2; ++_i) \
;         __builtin_amdgcn_global_load_lds((const unsigned*)((const char*)(gbase) + (voff)[_i]), (LAS unsigned*)(lds + (bufoff) + ldsw + _i * 8192), 16, 0, 0); } while (0)
; #define PG8_LDA(dst, b, h) do { _Pragma("unroll") for (int m = 0; m < 4; ++m) _Pragma("unroll") for (int k = 0; k < 2; ++k) dst[m][k] = *(const LAS bf16x8*)(lds + PG8_SA(b, h) + aoff + m * 2048 + k * 1024); } while (0)
; #define PG8_LDB(dst, b, h) do { _Pragma("unroll") for (int n = 0; n < 2; ++n) _Pragma("unroll") for (int k = 0; k < 2; ++k) dst[n][k] = *(const LAS bf16x8*)(lds + PG8_SB(b, h) + boff + n * 2048 + k * 1024); } while (0)
; #define PG8_MMA(ai, bj, At, Bt) do { __builtin_amdgcn_s_setprio(1); _Pragma("unroll") for (int m = 0; m < 4; ++m) _Pragma("unroll") for (int n = 0; n < 2; ++n) _Pragma("unroll") for (int k = 0; k < 2; ++k) \
;         acc[ai][bj][m][n] = __builtin_amdgcn_mfma_f32_16x16x32_bf16(Bt[n][k], At[m][k], acc[ai][bj][m][n], 0, 0, 0); __builtin_amdgcn_s_setprio(0); } while (0)
; template <class Epi, class Sched>
; __device__ __forceinline__ void gemm_phase(LAS unsigned char* lds, const int lda, const int ldb, const int K, const Sched& S, const Epi& E) {
;     ...
;             PG8_LDB(B0, 0, 0); PG8_LDB(B1, 0, 1); PG8_SCHED; PG8_LDA(At, 0, 0); PG8_STAGE(PG8_SA(1, 1), a1 + hstepA, voffA);
;             PG8_WAIT_V(8); PG8_WAIT_L(0); PG8_BAR; PG8_MMA(0, 0, At, B0); PG8_MMA(0, 1, At, B1); PG8_BAR; PG8_SCHED;
;             PG8_LDA(At, 0, 1); PG8_STAGE(PG8_SB(0, 0), b2, voffB); PG8_STAGE(PG8_SB(0, 1), b2 + hstepB, voffB); PG8_STAGE(PG8_SA(0, 0), a2, voffA);
;             PG8_WAIT_V(8); PG8_WAIT_L(0); PG8_BAR; PG8_MMA(1, 0, At, B0); PG8_MMA(1, 1, At, B1); PG8_BAR; PG8_SCHED;
;             PG8_LDB(B0, 1, 0); PG8_LDB(B1, 1, 1); PG8_SCHED; PG8_LDA(At, 1, 0); PG8_STAGE(PG8_SA(0, 1), a2 + hstepA, voffA);
;             PG8_WAIT_V(8); PG8_WAIT_L(0); PG8_BAR; PG8_MMA(0, 0, At, B0); PG8_MMA(0, 1, At, B1); PG8_BAR; PG8_SCHED;
;             PG8_LDA(At, 1, 1); PG8_STAGE(PG8_SB(1, 0), b3, voffB); PG8_STAGE(PG8_SB(1, 1), b3 + hstepB, voffB); PG8_STAGE(PG8_SA(1, 0), a3, voffA);
;             PG8_WAIT_V(8); PG8_WAIT_L(0); PG8_BAR;
;             if (last) E.pre(cur, wr, fr, rsv);
;             PG8_MMA(1, 0, At, B0); PG8_MMA(1, 1, At, B1); PG8_BAR; PG8_SCHED;
.LBB0_425:
	v_mfma_f32_16x16x32_bf16 v[62:65], v[146:149], v[186:189], v[62:65]
	v_mfma_f32_16x16x32_bf16 v[54:57], v[154:157], v[186:189], v[54:57]
	v_mfma_f32_16x16x32_bf16 v[46:49], v[146:149], v[178:181], v[46:49]
	v_mfma_f32_16x16x32_bf16 v[38:41], v[154:157], v[178:181], v[38:41]
	v_mfma_f32_16x16x32_bf16 v[30:33], v[146:149], v[170:173], v[30:33]
	v_mfma_f32_16x16x32_bf16 v[22:25], v[154:157], v[170:173], v[22:25]
	v_mfma_f32_16x16x32_bf16 v[14:17], v[146:149], v[162:165], v[14:17]
	v_mfma_f32_16x16x32_bf16 v[6:9], v[154:157], v[162:165], v[6:9]
	v_mfma_f32_16x16x32_bf16 v[62:65], v[150:153], v[190:193], v[62:65]
	v_mfma_f32_16x16x32_bf16 v[54:57], v[158:161], v[190:193], v[54:57]
	v_mfma_f32_16x16x32_bf16 v[46:49], v[150:153], v[182:185], v[46:49]
	v_mfma_f32_16x16x32_bf16 v[38:41], v[158:161], v[182:185], v[38:41]
	v_mfma_f32_16x16x32_bf16 v[30:33], v[150:153], v[174:177], v[30:33]
	v_mfma_f32_16x16x32_bf16 v[22:25], v[158:161], v[174:177], v[22:25]
	v_mfma_f32_16x16x32_bf16 v[14:17], v[150:153], v[166:169], v[14:17]
	v_mfma_f32_16x16x32_bf16 v[6:9], v[158:161], v[166:169], v[6:9]
	v_mfma_f32_16x16x32_bf16 v[58:61], v[130:133], v[186:189], v[58:61]
	v_mfma_f32_16x16x32_bf16 v[50:53], v[138:141], v[186:189], v[50:53]
	v_mfma_f32_16x16x32_bf16 v[42:45], v[130:133], v[178:181], v[42:45]
	v_mfma_f32_16x16x32_bf16 v[34:37], v[138:141], v[178:181], v[34:37]
	v_mfma_f32_16x16x32_bf16 v[26:29], v[130:133], v[170:173], v[26:29]
	v_mfma_f32_16x16x32_bf16 v[18:21], v[138:141], v[170:173], v[18:21]
	v_mfma_f32_16x16x32_bf16 v[10:13], v[130:133], v[162:165], v[10:13]
	v_mfma_f32_16x16x32_bf16 v[2:5], v[138:141], v[162:165], v[2:5]
	v_mfma_f32_16x16x32_bf16 v[58:61], v[134:137], v[190:193], v[58:61]
	v_mfma_f32_16x16x32_bf16 v[50:53], v[142:145], v[190:193], v[50:53]
	v_mfma_f32_16x16x32_bf16 v[42:45], v[134:137], v[182:185], v[42:45]
	v_mfma_f32_16x16x32_bf16 v[34:37], v[142:145], v[182:185], v[34:37]
	v_mfma_f32_16x16x32_bf16 v[26:29], v[134:137], v[174:177], v[26:29]
	v_mfma_f32_16x16x32_bf16 v[18:21], v[142:145], v[174:177], v[18:21]
	v_mfma_f32_16x16x32_bf16 v[10:13], v[134:137], v[166:169], v[10:13]
	v_mfma_f32_16x16x32_bf16 v[2:5], v[142:145], v[166:169], v[2:5]
	s_barrier
	s_add_i32 s69, s69, 2
	s_add_u32 s6, s6, 0x100
	s_addc_u32 s7, s7, 0
	s_add_u32 s5, s5, 0x100
	s_addc_u32 s51, s51, 0
	s_cmp_gt_u32 s69, 13
	s_cbranch_scc1 .LBB0_428
.LBB0_426:
	s_add_u32 s8, s6, 0xfffc0080
	s_addc_u32 s9, s7, -1
	s_cmp_eq_u32 s69, 12
	s_cselect_b32 s13, s71, s9
	s_cselect_b32 s12, s70, s8
	s_cselect_b32 s15, s73, s51
	s_cselect_b32 s14, s72, s5
	s_add_i32 s81, s63, s36
	ds_read_b128 v[130:133], v222
	ds_read_b128 v[134:137], v222 offset:1024
	ds_read_b128 v[138:141], v222 offset:2048
	ds_read_b128 v[142:145], v222 offset:3072
	ds_read_b128 v[146:149], v223
	ds_read_b128 v[150:153], v223 offset:1024
	ds_read_b128 v[154:157], v223 offset:2048
	ds_read_b128 v[158:161], v223 offset:3072
	s_add_i32 m0, s39, 0xc000
	s_add_i32 s80, s39, 0xe000
	s_add_i32 s82, s81, 0x2000
	s_add_u32 s16, s14, 0x40000
	s_addc_u32 s17, s15, 0
	s_add_i32 s83, s64, s36
	s_add_i32 s84, s83, 0x2000
	s_add_i32 s85, 0, 0x18000
	s_add_i32 s86, 0, 0x1c000
	s_add_u32 s10, s12, 0x40000
	s_addc_u32 s11, s13, 0
	s_add_i32 s75, s85, s36
	s_add_i32 s74, s75, 0x2000
	s_add_u32 s8, s14, 0x40080
	s_addc_u32 s9, s15, 0
	s_add_i32 s79, s86, s36
	s_add_i32 s78, s79, 0x2000
	s_cmp_lg_u32 s69, 12
	ds_read_b128 v[162:165], v224
	ds_read_b128 v[166:169], v224 offset:1024
	ds_read_b128 v[170:173], v224 offset:2048
	ds_read_b128 v[174:177], v224 offset:3072
	ds_read_b128 v[178:181], v224 offset:4096
	ds_read_b128 v[182:185], v224 offset:5120
	ds_read_b128 v[186:189], v224 offset:6144
	ds_read_b128 v[190:193], v224 offset:7168
	global_load_lds_dwordx4 v212, s[6:7]
	s_mov_b32 m0, s80
	s_nop 0
	global_load_lds_dwordx4 v214, s[6:7]
	s_waitcnt vmcnt(8)
	s_waitcnt lgkmcnt(0)
	s_barrier
	v_mfma_f32_16x16x32_bf16 v[126:129], v[130:133], v[162:165], v[126:129]
	v_mfma_f32_16x16x32_bf16 v[118:121], v[138:141], v[162:165], v[118:121]
	v_mfma_f32_16x16x32_bf16 v[110:113], v[130:133], v[170:173], v[110:113]
	v_mfma_f32_16x16x32_bf16 v[102:105], v[138:141], v[170:173], v[102:105]
	v_mfma_f32_16x16x32_bf16 v[94:97], v[130:133], v[178:181], v[94:97]
	v_mfma_f32_16x16x32_bf16 v[86:89], v[138:141], v[178:181], v[86:89]
	v_mfma_f32_16x16x32_bf16 v[78:81], v[130:133], v[186:189], v[78:81]
	v_mfma_f32_16x16x32_bf16 v[70:73], v[138:141], v[186:189], v[70:73]
	v_mfma_f32_16x16x32_bf16 v[126:129], v[134:137], v[166:169], v[126:129]
	v_mfma_f32_16x16x32_bf16 v[118:121], v[142:145], v[166:169], v[118:121]
	v_mfma_f32_16x16x32_bf16 v[110:113], v[134:137], v[174:177], v[110:113]
	v_mfma_f32_16x16x32_bf16 v[102:105], v[142:145], v[174:177], v[102:105]
	v_mfma_f32_16x16x32_bf16 v[94:97], v[134:137], v[182:185], v[94:97]
	v_mfma_f32_16x16x32_bf16 v[86:89], v[142:145], v[182:185], v[86:89]
	v_mfma_f32_16x16x32_bf16 v[78:81], v[134:137], v[190:193], v[78:81]
	v_mfma_f32_16x16x32_bf16 v[70:73], v[142:145], v[190:193], v[70:73]
	v_mfma_f32_16x16x32_bf16 v[122:125], v[146:149], v[162:165], v[122:125]
	v_mfma_f32_16x16x32_bf16 v[114:117], v[154:157], v[162:165], v[114:117]
	v_mfma_f32_16x16x32_bf16 v[106:109], v[146:149], v[170:173], v[106:109]
	v_mfma_f32_16x16x32_bf16 v[98:101], v[154:157], v[170:173], v[98:101]
	v_mfma_f32_16x16x32_bf16 v[90:93], v[146:149], v[178:181], v[90:93]
	v_mfma_f32_16x16x32_bf16 v[82:85], v[154:157], v[178:181], v[82:85]
	v_mfma_f32_16x16x32_bf16 v[74:77], v[146:149], v[186:189], v[74:77]
	v_mfma_f32_16x16x32_bf16 v[66:69], v[154:157], v[186:189], v[66:69]
	v_mfma_f32_16x16x32_bf16 v[122:125], v[150:153], v[166:169], v[122:125]
	v_mfma_f32_16x16x32_bf16 v[114:117], v[158:161], v[166:169], v[114:117]
	v_mfma_f32_16x16x32_bf16 v[106:109], v[150:153], v[174:177], v[106:109]
	v_mfma_f32_16x16x32_bf16 v[98:101], v[158:161], v[174:177], v[98:101]
	v_mfma_f32_16x16x32_bf16 v[90:93], v[150:153], v[182:185], v[90:93]
	v_mfma_f32_16x16x32_bf16 v[82:85], v[158:161], v[182:185], v[82:85]
	v_mfma_f32_16x16x32_bf16 v[74:77], v[150:153], v[190:193], v[74:77]
	v_mfma_f32_16x16x32_bf16 v[66:69], v[158:161], v[190:193], v[66:69]
	s_barrier
; #define PG8_STAGE(bufoff, gbase, voff) do { _Pragma("unroll") for (int _i = 0; _i < 2; ++_i) \
;         __builtin_amdgcn_global_load_lds((const unsigned*)((const char*)(gbase) + (voff)[_i]), (LAS unsigned*)(lds + (bufoff) + ldsw + _i * 8192), 16, 0, 0); } while (0)
; #define PG8_LDA(dst, b, h) do { _Pragma("unroll") for (int m = 0; m < 4; ++m) _Pragma("unroll") for (int k = 0; k < 2; ++k) dst[m][k] = *(const LAS bf16x8*)(lds + PG8_SA(b, h) + aoff + m * 2048 + k * 1024); } while (0)
; #define PG8_MMA(ai, bj, At, Bt) do { __builtin_amdgcn_s_setprio(1); _Pragma("unroll") for (int m = 0; m < 4; ++m) _Pragma("unroll") for (int n = 0; n < 2; ++n) _Pragma("unroll") for (int k = 0; k < 2; ++k) \
;         acc[ai][bj][m][n] = __builtin_amdgcn_mfma_f32_16x16x32_bf16(Bt[n][k], At[m][k], acc[ai][bj][m][n], 0, 0, 0); __builtin_amdgcn_s_setprio(0); } while (0)
; #define PG8_WAIT_V(n) asm volatile("s_waitcnt vmcnt(" #n ")" ::: "memory")
; #define PG8_WAIT_L(n) asm volatile("s_waitcnt lgkmcnt(" #n ")" ::: "memory")
; #define PG8_BAR __builtin_amdgcn_s_barrier()
; #define PG8_SCHED __builtin_amdgcn_sched_barrier(0)
; template <class Epi, class Sched>
; __device__ __forceinline__ void gemm_phase(LAS unsigned char* lds, const int lda, const int ldb, const int K, const Sched& S, const Epi& E) {
;     ...
;             PG8_LDA(At, 0, 1); PG8_STAGE(PG8_SB(0, 0), b2, voffB); PG8_STAGE(PG8_SB(0, 1), b2 + hstepB, voffB); PG8_STAGE(PG8_SA(0, 0), a2, voffA);
;             PG8_WAIT_V(8); PG8_WAIT_L(0); PG8_BAR; PG8_MMA(1, 0, At, B0); PG8_MMA(1, 1, At, B1); PG8_BAR; PG8_SCHED;
	s_mov_b32 m0, s81
	ds_read_b128 v[162:165], v224 offset:16384
	ds_read_b128 v[166:169], v224 offset:17408
	ds_read_b128 v[170:173], v224 offset:18432
	ds_read_b128 v[174:177], v224 offset:19456
	ds_read_b128 v[178:181], v224 offset:20480
	ds_read_b128 v[182:185], v224 offset:21504
	ds_read_b128 v[186:189], v224 offset:22528
	ds_read_b128 v[190:193], v224 offset:23552
	global_load_lds_dwordx4 v202, s[14:15]
	s_mov_b32 m0, s82
	s_nop 0
	global_load_lds_dwordx4 v198, s[14:15]
	s_mov_b32 m0, s83
	s_nop 0
	global_load_lds_dwordx4 v202, s[16:17]
	s_mov_b32 m0, s84
	s_nop 0
	global_load_lds_dwordx4 v198, s[16:17]
	s_mov_b32 m0, s39
	s_nop 0
	global_load_lds_dwordx4 v204, s[12:13]
	s_mov_b32 m0, s40
	s_nop 0
	global_load_lds_dwordx4 v200, s[12:13]
	s_waitcnt vmcnt(8)
	s_waitcnt lgkmcnt(0)
	s_barrier
	v_mfma_f32_16x16x32_bf16 v[62:65], v[130:133], v[162:165], v[62:65]
	v_mfma_f32_16x16x32_bf16 v[54:57], v[138:141], v[162:165], v[54:57]
	v_mfma_f32_16x16x32_bf16 v[46:49], v[130:133], v[170:173], v[46:49]
	v_mfma_f32_16x16x32_bf16 v[38:41], v[138:141], v[170:173], v[38:41]
	v_mfma_f32_16x16x32_bf16 v[30:33], v[130:133], v[178:181], v[30:33]
	v_mfma_f32_16x16x32_bf16 v[22:25], v[138:141], v[178:181], v[22:25]
	v_mfma_f32_16x16x32_bf16 v[14:17], v[130:133], v[186:189], v[14:17]
	v_mfma_f32_16x16x32_bf16 v[6:9], v[138:141], v[186:189], v[6:9]
	v_mfma_f32_16x16x32_bf16 v[62:65], v[134:137], v[166:169], v[62:65]
	v_mfma_f32_16x16x32_bf16 v[54:57], v[142:145], v[166:169], v[54:57]
	v_mfma_f32_16x16x32_bf16 v[46:49], v[134:137], v[174:177], v[46:49]
	v_mfma_f32_16x16x32_bf16 v[38:41], v[142:145], v[174:177], v[38:41]
	v_mfma_f32_16x16x32_bf16 v[30:33], v[134:137], v[182:185], v[30:33]
	v_mfma_f32_16x16x32_bf16 v[22:25], v[142:145], v[182:185], v[22:25]
	v_mfma_f32_16x16x32_bf16 v[14:17], v[134:137], v[190:193], v[14:17]
	v_mfma_f32_16x16x32_bf16 v[6:9], v[142:145], v[190:193], v[6:9]
	v_mfma_f32_16x16x32_bf16 v[58:61], v[146:149], v[162:165], v[58:61]
	v_mfma_f32_16x16x32_bf16 v[50:53], v[154:157], v[162:165], v[50:53]
	v_mfma_f32_16x16x32_bf16 v[42:45], v[146:149], v[170:173], v[42:45]
	v_mfma_f32_16x16x32_bf16 v[34:37], v[154:157], v[170:173], v[34:37]
	v_mfma_f32_16x16x32_bf16 v[26:29], v[146:149], v[178:181], v[26:29]
	v_mfma_f32_16x16x32_bf16 v[18:21], v[154:157], v[178:181], v[18:21]
	v_mfma_f32_16x16x32_bf16 v[10:13], v[146:149], v[186:189], v[10:13]
	v_mfma_f32_16x16x32_bf16 v[2:5], v[154:157], v[186:189], v[2:5]
	v_mfma_f32_16x16x32_bf16 v[58:61], v[150:153], v[166:169], v[58:61]
	v_mfma_f32_16x16x32_bf16 v[50:53], v[158:161], v[166:169], v[50:53]
	v_mfma_f32_16x16x32_bf16 v[42:45], v[150:153], v[174:177], v[42:45]
	v_mfma_f32_16x16x32_bf16 v[34:37], v[158:161], v[174:177], v[34:37]
	v_mfma_f32_16x16x32_bf16 v[26:29], v[150:153], v[182:185], v[26:29]
	v_mfma_f32_16x16x32_bf16 v[18:21], v[158:161], v[182:185], v[18:21]
	v_mfma_f32_16x16x32_bf16 v[10:13], v[150:153], v[190:193], v[10:13]
	v_mfma_f32_16x16x32_bf16 v[2:5], v[158:161], v[190:193], v[2:5]
	s_barrier
; #define PG8_STAGE(bufoff, gbase, voff) do { _Pragma("unroll") for (int _i = 0; _i < 2; ++_i) \
;         __builtin_amdgcn_global_load_lds((const unsigned*)((const char*)(gbase) + (voff)[_i]), (LAS unsigned*)(lds + (bufoff) + ldsw + _i * 8192), 16, 0, 0); } while (0)
; #define PG8_LDA(dst, b, h) do { _Pragma("unroll") for (int m = 0; m < 4; ++m) _Pragma("unroll") for (int k = 0; k < 2; ++k) dst[m][k] = *(const LAS bf16x8*)(lds + PG8_SA(b, h) + aoff + m * 2048 + k * 1024); } while (0)
; #define PG8_LDB(dst, b, h) do { _Pragma("unroll") for (int n = 0; n < 2; ++n) _Pragma("unroll") for (int k = 0; k < 2; ++k) dst[n][k] = *(const LAS bf16x8*)(lds + PG8_SB(b, h) + boff + n * 2048 + k * 1024); } while (0)
; #define PG8_MMA(ai, bj, At, Bt) do { __builtin_amdgcn_s_setprio(1); _Pragma("unroll") for (int m = 0; m < 4; ++m) _Pragma("unroll") for (int n = 0; n < 2; ++n) _Pragma("unroll") for (int k = 0; k < 2; ++k) \
;         acc[ai][bj][m][n] = __builtin_amdgcn_mfma_f32_16x16x32_bf16(Bt[n][k], At[m][k], acc[ai][bj][m][n], 0, 0, 0); __builtin_amdgcn_s_setprio(0); } while (0)
; #define PG8_WAIT_V(n) asm volatile("s_waitcnt vmcnt(" #n ")" ::: "memory")
; #define PG8_WAIT_L(n) asm volatile("s_waitcnt lgkmcnt(" #n ")" ::: "memory")
; #define PG8_BAR __builtin_amdgcn_s_barrier()
; #define PG8_SCHED __builtin_amdgcn_sched_barrier(0)
; template <class Epi, class Sched>
; __device__ __forceinline__ void gemm_phase(LAS unsigned char* lds, const int lda, const int ldb, const int K, const Sched& S, const Epi& E) {
;     ...
;             PG8_LDB(B0, 1, 0); PG8_LDB(B1, 1, 1); PG8_SCHED; PG8_LDA(At, 1, 0); PG8_STAGE(PG8_SA(0, 1), a2 + hstepA, voffA);
;             PG8_WAIT_V(8); PG8_WAIT_L(0); PG8_BAR; PG8_MMA(0, 0, At, B0); PG8_MMA(0, 1, At, B1); PG8_BAR; PG8_SCHED;
;             PG8_LDA(At, 1, 1); PG8_STAGE(PG8_SB(1, 0), b3, voffB); PG8_STAGE(PG8_SB(1, 1), b3 + hstepB, voffB); PG8_STAGE(PG8_SA(1, 0), a3, voffA);
;             PG8_WAIT_V(8); PG8_WAIT_L(0); PG8_BAR;
;             if (last) E.pre(cur, wr, fr, rsv);
;     __device__ __forceinline__ void pre(const pg8::Unit& u, int wr, int fr, float (&rsv)[8]) const {
;         const float* p = ss + u.pm * 256 + wr * 64 + fr;
; #pragma unroll
;         for (int ai = 0; ai < 2; ++ai)
; #pragma unroll
;             for (int m = 0; m < 4; ++m) rsv[ai * 4 + m] = p[ai * 128 + m * 16];
;     }
.Lpeel3_join:
	v_add_u32_e32 v130, s85, v195
	v_add_u32_e32 v142, s86, v195
	ds_read_b128 v[146:149], v130
	ds_read_b128 v[150:153], v130 offset:1024
	ds_read_b128 v[154:157], v130 offset:2048
	ds_read_b128 v[158:161], v130 offset:3072
	ds_read_b128 v[130:133], v142
	ds_read_b128 v[134:137], v142 offset:1024
	ds_read_b128 v[138:141], v142 offset:2048
	ds_read_b128 v[142:145], v142 offset:3072
	s_mov_b32 m0, s41
	ds_read_b128 v[162:165], v224 offset:32768
	ds_read_b128 v[166:169], v224 offset:33792
	ds_read_b128 v[170:173], v224 offset:34816
	ds_read_b128 v[174:177], v224 offset:35840
	ds_read_b128 v[178:181], v224 offset:36864
	ds_read_b128 v[182:185], v224 offset:37888
	ds_read_b128 v[186:189], v224 offset:38912
	ds_read_b128 v[190:193], v224 offset:39936
	global_load_lds_dwordx4 v204, s[10:11]
	s_mov_b32 m0, s42
	s_nop 0
	global_load_lds_dwordx4 v200, s[10:11]
	s_waitcnt vmcnt(8)
	s_waitcnt lgkmcnt(0)
	s_barrier
	v_mfma_f32_16x16x32_bf16 v[126:129], v[146:149], v[162:165], v[126:129]
	v_mfma_f32_16x16x32_bf16 v[118:121], v[154:157], v[162:165], v[118:121]
	v_mfma_f32_16x16x32_bf16 v[110:113], v[146:149], v[170:173], v[110:113]
	v_mfma_f32_16x16x32_bf16 v[102:105], v[154:157], v[170:173], v[102:105]
	v_mfma_f32_16x16x32_bf16 v[94:97], v[146:149], v[178:181], v[94:97]
	v_mfma_f32_16x16x32_bf16 v[86:89], v[154:157], v[178:181], v[86:89]
	v_mfma_f32_16x16x32_bf16 v[78:81], v[146:149], v[186:189], v[78:81]
	v_mfma_f32_16x16x32_bf16 v[70:73], v[154:157], v[186:189], v[70:73]
	v_mfma_f32_16x16x32_bf16 v[126:129], v[150:153], v[166:169], v[126:129]
	v_mfma_f32_16x16x32_bf16 v[118:121], v[158:161], v[166:169], v[118:121]
	v_mfma_f32_16x16x32_bf16 v[110:113], v[150:153], v[174:177], v[110:113]
	v_mfma_f32_16x16x32_bf16 v[102:105], v[158:161], v[174:177], v[102:105]
	v_mfma_f32_16x16x32_bf16 v[94:97], v[150:153], v[182:185], v[94:97]
	v_mfma_f32_16x16x32_bf16 v[86:89], v[158:161], v[182:185], v[86:89]
	v_mfma_f32_16x16x32_bf16 v[78:81], v[150:153], v[190:193], v[78:81]
	v_mfma_f32_16x16x32_bf16 v[70:73], v[158:161], v[190:193], v[70:73]
	v_mfma_f32_16x16x32_bf16 v[122:125], v[130:133], v[162:165], v[122:125]
	v_mfma_f32_16x16x32_bf16 v[114:117], v[138:141], v[162:165], v[114:117]
	v_mfma_f32_16x16x32_bf16 v[106:109], v[130:133], v[170:173], v[106:109]
	v_mfma_f32_16x16x32_bf16 v[98:101], v[138:141], v[170:173], v[98:101]
	v_mfma_f32_16x16x32_bf16 v[90:93], v[130:133], v[178:181], v[90:93]
	v_mfma_f32_16x16x32_bf16 v[82:85], v[138:141], v[178:181], v[82:85]
	v_mfma_f32_16x16x32_bf16 v[74:77], v[130:133], v[186:189], v[74:77]
	v_mfma_f32_16x16x32_bf16 v[66:69], v[138:141], v[186:189], v[66:69]
	v_mfma_f32_16x16x32_bf16 v[122:125], v[134:137], v[166:169], v[122:125]
	v_mfma_f32_16x16x32_bf16 v[114:117], v[142:145], v[166:169], v[114:117]
	v_mfma_f32_16x16x32_bf16 v[106:109], v[134:137], v[174:177], v[106:109]
	v_mfma_f32_16x16x32_bf16 v[98:101], v[142:145], v[174:177], v[98:101]
	v_mfma_f32_16x16x32_bf16 v[90:93], v[134:137], v[182:185], v[90:93]
	v_mfma_f32_16x16x32_bf16 v[82:85], v[142:145], v[182:185], v[82:85]
	v_mfma_f32_16x16x32_bf16 v[74:77], v[134:137], v[190:193], v[74:77]
	v_mfma_f32_16x16x32_bf16 v[66:69], v[142:145], v[190:193], v[66:69]
	s_barrier
	s_mov_b32 m0, s75
	ds_read_b128 v[186:189], v224 offset:49152
	ds_read_b128 v[190:193], v224 offset:50176
	ds_read_b128 v[178:181], v224 offset:51200
	ds_read_b128 v[182:185], v224 offset:52224
	ds_read_b128 v[170:173], v224 offset:53248
	ds_read_b128 v[174:177], v224 offset:54272
	ds_read_b128 v[162:165], v224 offset:55296
	ds_read_b128 v[166:169], v224 offset:56320
	global_load_lds_dwordx4 v234, s[14:15]
	s_mov_b32 m0, s74
	s_nop 0
	global_load_lds_dwordx4 v235, s[14:15]
	s_mov_b32 m0, s79
	s_nop 0
	global_load_lds_dwordx4 v202, s[8:9]
	s_mov_b32 m0, s78
	s_nop 0
	global_load_lds_dwordx4 v198, s[8:9]
	s_mov_b32 m0, s43
	s_nop 0
	global_load_lds_dwordx4 v236, s[12:13]
	s_mov_b32 m0, s44
	s_nop 0
	global_load_lds_dwordx4 v237, s[12:13]
	s_waitcnt vmcnt(8)
	s_waitcnt lgkmcnt(0)
	s_barrier
	s_cbranch_scc1 .LBB0_425
	global_load_dword v233, v[220:221], off
	global_load_dword v232, v[220:221], off offset:64
	global_load_dword v231, v[220:221], off offset:128
	global_load_dword v230, v[220:221], off offset:192
	global_load_dword v229, v[220:221], off offset:512
	global_load_dword v228, v[220:221], off offset:576
	global_load_dword v227, v[220:221], off offset:640
	global_load_dword v226, v[220:221], off offset:704
	s_branch .LBB0_425

; #define PG8_STAGE(bufoff, gbase, voff) do { _Pragma("unroll") for (int _i = 0; _i < 2; ++_i) \
;         __builtin_amdgcn_global_load_lds((const unsigned*)((const char*)(gbase) + (voff)[_i]), (LAS unsigned*)(lds + (bufoff) + ldsw + _i * 8192), 16, 0, 0); } while (0)
; #define PG8_LDA(dst, b, h) do { _Pragma("unroll") for (int m = 0; m < 4; ++m) _Pragma("unroll") for (int k = 0; k < 2; ++k) dst[m][k] = *(const LAS bf16x8*)(lds + PG8_SA(b, h) + aoff + m * 2048 + k * 1024); } while (0)
; #define PG8_LDB(dst, b, h) do { _Pragma("unroll") for (int n = 0; n < 2; ++n) _Pragma("unroll") for (int k = 0; k < 2; ++k) dst[n][k] = *(const LAS bf16x8*)(lds + PG8_SB(b, h) + boff + n * 2048 + k * 1024); } while (0)
; #define PG8_MMA(ai, bj, At, Bt) do { __builtin_amdgcn_s_setprio(1); _Pragma("unroll") for (int m = 0; m < 4; ++m) _Pragma("unroll") for (int n = 0; n < 2; ++n) _Pragma("unroll") for (int k = 0; k < 2; ++k) \
;         acc[ai][bj][m][n] = __builtin_amdgcn_mfma_f32_16x16x32_bf16(Bt[n][k], At[m][k], acc[ai][bj][m][n], 0, 0, 0); __builtin_amdgcn_s_setprio(0); } while (0)
; #define PG8_WAIT_V(n) asm volatile("s_waitcnt vmcnt(" #n ")" ::: "memory")
; #define PG8_WAIT_L(n) asm volatile("s_waitcnt lgkmcnt(" #n ")" ::: "memory")
; #define PG8_BAR __builtin_amdgcn_s_barrier()
; #define PG8_SCHED __builtin_amdgcn_sched_barrier(0)
; template <class Epi, class Sched>
; __device__ __forceinline__ void gemm_phase(LAS unsigned char* lds, const int lda, const int ldb, const int K, const Sched& S, const Epi& E) {
;     ...
;             const bool last = (t == nt - 2);
;             const char* a1 = cA + (size_t)(t + 1) * kstep;
;             const char* a2 = last ? nA : cA + (size_t)(t + 2) * kstep; const char* b2 = last ? nB : cB + (size_t)(t + 2) * kstep;
;             const char* a3 = a2 + kstep; const char* b3 = b2 + kstep;
;             PG8_LDB(B0, 0, 0); PG8_LDB(B1, 0, 1); PG8_SCHED; PG8_LDA(At, 0, 0); PG8_STAGE(PG8_SA(1, 1), a1 + hstepA, voffA);
;             PG8_WAIT_V(8); PG8_WAIT_L(0); PG8_BAR; PG8_MMA(0, 0, At, B0); PG8_MMA(0, 1, At, B1); PG8_BAR; PG8_SCHED;
;             PG8_LDA(At, 0, 1); PG8_STAGE(PG8_SB(0, 0), b2, voffB); PG8_STAGE(PG8_SB(0, 1), b2 + hstepB, voffB); PG8_STAGE(PG8_SA(0, 0), a2, voffA);
;             PG8_WAIT_V(8); PG8_WAIT_L(0); PG8_BAR; PG8_MMA(1, 0, At, B0); PG8_MMA(1, 1, At, B1); PG8_BAR; PG8_SCHED;
.LBB0_839:
	v_add_u32_e32 v3, s43, v195
	ds_read_b128 v[62:65], v3
	ds_read_b128 v[66:69], v3 offset:1024
	ds_read_b128 v[86:89], v3 offset:2048
	ds_read_b128 v[90:93], v3 offset:3072
	v_add_u32_e32 v3, s44, v195
	ds_read_b128 v[110:113], v3
	ds_read_b128 v[114:117], v3 offset:1024
	ds_read_b128 v[142:145], v3 offset:2048
	ds_read_b128 v[146:149], v3 offset:3072
	s_add_u32 s20, s4, 0xfff50080
	s_addc_u32 s21, s5, -1
	s_cmp_eq_u32 s64, 4
	s_cselect_b32 s23, s17, s21
	s_cselect_b32 s22, s16, s20
	s_cselect_b32 s21, s19, s63
	s_cselect_b32 s20, s18, s15
	s_add_i32 m0, s28, 0xc000
	ds_read_b128 v[166:169], v201
	ds_read_b128 v[186:189], v201 offset:1024
	ds_read_b128 v[190:193], v201 offset:2048
	ds_read_b128 v[196:199], v201 offset:3072
	ds_read_b128 v[202:205], v201 offset:4096
	ds_read_b128 v[206:209], v201 offset:5120
	ds_read_b128 v[210:213], v201 offset:6144
	ds_read_b128 v[214:217], v201 offset:7168
	global_load_lds_dwordx4 v178, s[4:5]
	s_add_i32 m0, s28, 0xe000
	s_nop 0
	global_load_lds_dwordx4 v180, s[4:5]
	s_waitcnt vmcnt(8)
	s_waitcnt lgkmcnt(0)
	s_barrier
	v_mfma_f32_16x16x32_bf16 v[74:77], v[62:65], v[166:169], v[74:77]
	v_mfma_f32_16x16x32_bf16 v[70:73], v[86:89], v[166:169], v[70:73]
	v_mfma_f32_16x16x32_bf16 v[106:109], v[62:65], v[190:193], v[106:109]
	v_mfma_f32_16x16x32_bf16 v[102:105], v[86:89], v[190:193], v[102:105]
	v_mfma_f32_16x16x32_bf16 v[138:141], v[62:65], v[202:205], v[138:141]
	v_mfma_f32_16x16x32_bf16 v[126:129], v[86:89], v[202:205], v[126:129]
	v_mfma_f32_16x16x32_bf16 v[122:125], v[62:65], v[210:213], v[122:125]
	v_mfma_f32_16x16x32_bf16 v[118:121], v[86:89], v[210:213], v[118:121]
	v_mfma_f32_16x16x32_bf16 v[74:77], v[66:69], v[186:189], v[74:77]
	v_mfma_f32_16x16x32_bf16 v[70:73], v[90:93], v[186:189], v[70:73]
	v_mfma_f32_16x16x32_bf16 v[106:109], v[66:69], v[196:199], v[106:109]
	v_mfma_f32_16x16x32_bf16 v[102:105], v[90:93], v[196:199], v[102:105]
	v_mfma_f32_16x16x32_bf16 v[138:141], v[66:69], v[206:209], v[138:141]
	v_mfma_f32_16x16x32_bf16 v[126:129], v[90:93], v[206:209], v[126:129]
	v_mfma_f32_16x16x32_bf16 v[122:125], v[66:69], v[214:217], v[122:125]
	v_mfma_f32_16x16x32_bf16 v[118:121], v[90:93], v[214:217], v[118:121]
	v_mfma_f32_16x16x32_bf16 v[162:165], v[110:113], v[166:169], v[162:165]
	v_mfma_f32_16x16x32_bf16 v[158:161], v[142:145], v[166:169], v[158:161]
	v_mfma_f32_16x16x32_bf16 v[154:157], v[110:113], v[190:193], v[154:157]
	v_mfma_f32_16x16x32_bf16 v[150:153], v[142:145], v[190:193], v[150:153]
	v_mfma_f32_16x16x32_bf16 v[134:137], v[110:113], v[202:205], v[134:137]
	v_mfma_f32_16x16x32_bf16 v[130:133], v[142:145], v[202:205], v[130:133]
	v_mfma_f32_16x16x32_bf16 v[98:101], v[110:113], v[210:213], v[98:101]
	v_mfma_f32_16x16x32_bf16 v[94:97], v[142:145], v[210:213], v[94:97]
	v_mfma_f32_16x16x32_bf16 v[162:165], v[114:117], v[186:189], v[162:165]
	v_mfma_f32_16x16x32_bf16 v[158:161], v[146:149], v[186:189], v[158:161]
	v_mfma_f32_16x16x32_bf16 v[154:157], v[114:117], v[196:199], v[154:157]
	v_mfma_f32_16x16x32_bf16 v[150:153], v[146:149], v[196:199], v[150:153]
	v_mfma_f32_16x16x32_bf16 v[134:137], v[114:117], v[206:209], v[134:137]
	v_mfma_f32_16x16x32_bf16 v[130:133], v[146:149], v[206:209], v[130:133]
	v_mfma_f32_16x16x32_bf16 v[98:101], v[114:117], v[214:217], v[98:101]
	v_mfma_f32_16x16x32_bf16 v[94:97], v[146:149], v[214:217], v[94:97]
	s_barrier
	s_add_i32 s65, s43, s27
	s_mov_b32 m0, s65
	ds_read_b128 v[166:169], v201 offset:16384
	ds_read_b128 v[186:189], v201 offset:17408
	ds_read_b128 v[190:193], v201 offset:18432
	ds_read_b128 v[196:199], v201 offset:19456
	ds_read_b128 v[202:205], v201 offset:20480
	ds_read_b128 v[206:209], v201 offset:21504
	ds_read_b128 v[210:213], v201 offset:22528
	ds_read_b128 v[214:217], v201 offset:23552
	global_load_lds_dwordx4 v172, s[20:21]
	s_add_i32 m0, s65, 0x2000
	s_add_u32 s68, s20, 0x20000
	s_mov_b64 s[98:99], s[20:21]
	s_addc_u32 s69, s21, 0
	s_add_i32 s65, s44, s27
	global_load_lds_dwordx4 v176, s[20:21]
	s_mov_b32 m0, s65
	s_mov_b64 s[100:101], s[22:23]
	global_load_lds_dwordx4 v172, s[68:69]
	s_add_i32 m0, s65, 0x2000
	s_nop 0
	global_load_lds_dwordx4 v176, s[68:69]
	s_mov_b32 m0, s28
	s_nop 0
	global_load_lds_dwordx4 v170, s[22:23]
	s_mov_b32 m0, s29
	s_nop 0
	global_load_lds_dwordx4 v174, s[22:23]
	s_waitcnt vmcnt(8)
	s_waitcnt lgkmcnt(0)
	s_barrier
	v_mfma_f32_16x16x32_bf16 v[82:85], v[62:65], v[166:169], v[82:85]
	v_mfma_f32_16x16x32_bf16 v[78:81], v[86:89], v[166:169], v[78:81]
	v_mfma_f32_16x16x32_bf16 v[50:53], v[62:65], v[190:193], v[50:53]
	v_mfma_f32_16x16x32_bf16 v[46:49], v[86:89], v[190:193], v[46:49]
	v_mfma_f32_16x16x32_bf16 v[34:37], v[62:65], v[202:205], v[34:37]
	v_mfma_f32_16x16x32_bf16 v[30:33], v[86:89], v[202:205], v[30:33]
	v_mfma_f32_16x16x32_bf16 v[18:21], v[62:65], v[210:213], v[18:21]
	v_mfma_f32_16x16x32_bf16 v[14:17], v[86:89], v[210:213], v[14:17]
	v_mfma_f32_16x16x32_bf16 v[82:85], v[66:69], v[186:189], v[82:85]
	v_mfma_f32_16x16x32_bf16 v[78:81], v[90:93], v[186:189], v[78:81]
	v_mfma_f32_16x16x32_bf16 v[50:53], v[66:69], v[196:199], v[50:53]
	v_mfma_f32_16x16x32_bf16 v[46:49], v[90:93], v[196:199], v[46:49]
	v_mfma_f32_16x16x32_bf16 v[34:37], v[66:69], v[206:209], v[34:37]
	v_mfma_f32_16x16x32_bf16 v[30:33], v[90:93], v[206:209], v[30:33]
	v_mfma_f32_16x16x32_bf16 v[18:21], v[66:69], v[214:217], v[18:21]
	v_mfma_f32_16x16x32_bf16 v[14:17], v[90:93], v[214:217], v[14:17]
	v_mfma_f32_16x16x32_bf16 v[58:61], v[110:113], v[166:169], v[58:61]
	v_mfma_f32_16x16x32_bf16 v[54:57], v[142:145], v[166:169], v[54:57]
	v_mfma_f32_16x16x32_bf16 v[42:45], v[110:113], v[190:193], v[42:45]
	v_mfma_f32_16x16x32_bf16 v[38:41], v[142:145], v[190:193], v[38:41]
	v_mfma_f32_16x16x32_bf16 v[26:29], v[110:113], v[202:205], v[26:29]
	v_mfma_f32_16x16x32_bf16 v[22:25], v[142:145], v[202:205], v[22:25]
	v_mfma_f32_16x16x32_bf16 v[10:13], v[110:113], v[210:213], v[10:13]
	v_mfma_f32_16x16x32_bf16 v[4:7], v[142:145], v[210:213], v[6:9]
	v_mfma_f32_16x16x32_bf16 v[58:61], v[114:117], v[186:189], v[58:61]
	v_mfma_f32_16x16x32_bf16 v[54:57], v[146:149], v[186:189], v[54:57]
	v_mfma_f32_16x16x32_bf16 v[42:45], v[114:117], v[196:199], v[42:45]
	v_mfma_f32_16x16x32_bf16 v[38:41], v[146:149], v[196:199], v[38:41]
	v_mfma_f32_16x16x32_bf16 v[26:29], v[114:117], v[206:209], v[26:29]
	v_mfma_f32_16x16x32_bf16 v[22:25], v[146:149], v[206:209], v[22:25]
	v_mfma_f32_16x16x32_bf16 v[10:13], v[114:117], v[214:217], v[10:13]
	v_mfma_f32_16x16x32_bf16 v[4:7], v[146:149], v[214:217], v[4:7]
	s_barrier
; #define PG8_STAGE(bufoff, gbase, voff) do { _Pragma("unroll") for (int _i = 0; _i < 2; ++_i) \
;         __builtin_amdgcn_global_load_lds((const unsigned*)((const char*)(gbase) + (voff)[_i]), (LAS unsigned*)(lds + (bufoff) + ldsw + _i * 8192), 16, 0, 0); } while (0)
; #define PG8_LDA(dst, b, h) do { _Pragma("unroll") for (int m = 0; m < 4; ++m) _Pragma("unroll") for (int k = 0; k < 2; ++k) dst[m][k] = *(const LAS bf16x8*)(lds + PG8_SA(b, h) + aoff + m * 2048 + k * 1024); } while (0)
; #define PG8_LDB(dst, b, h) do { _Pragma("unroll") for (int n = 0; n < 2; ++n) _Pragma("unroll") for (int k = 0; k < 2; ++k) dst[n][k] = *(const LAS bf16x8*)(lds + PG8_SB(b, h) + boff + n * 2048 + k * 1024); } while (0)
; #define PG8_MMA(ai, bj, At, Bt) do { __builtin_amdgcn_s_setprio(1); _Pragma("unroll") for (int m = 0; m < 4; ++m) _Pragma("unroll") for (int n = 0; n < 2; ++n) _Pragma("unroll") for (int k = 0; k < 2; ++k) \
;         acc[ai][bj][m][n] = __builtin_amdgcn_mfma_f32_16x16x32_bf16(Bt[n][k], At[m][k], acc[ai][bj][m][n], 0, 0, 0); __builtin_amdgcn_s_setprio(0); } while (0)
; #define PG8_WAIT_V(n) asm volatile("s_waitcnt vmcnt(" #n ")" ::: "memory")
; #define PG8_WAIT_L(n) asm volatile("s_waitcnt lgkmcnt(" #n ")" ::: "memory")
; #define PG8_BAR __builtin_amdgcn_s_barrier()
; #define PG8_SCHED __builtin_amdgcn_sched_barrier(0)
; template <class Epi, class Sched>
; __device__ __forceinline__ void gemm_phase(LAS unsigned char* lds, const int lda, const int ldb, const int K, const Sched& S, const Epi& E) {
;     ...
;             PG8_LDB(B0, 1, 0); PG8_LDB(B1, 1, 1); PG8_SCHED; PG8_LDA(At, 1, 0); PG8_STAGE(PG8_SA(0, 1), a2 + hstepA, voffA);
;             PG8_WAIT_V(8); PG8_WAIT_L(0); PG8_BAR; PG8_MMA(0, 0, At, B0); PG8_MMA(0, 1, At, B1); PG8_BAR; PG8_SCHED;
;             PG8_LDA(At, 1, 1); PG8_STAGE(PG8_SB(1, 0), b3, voffB); PG8_STAGE(PG8_SB(1, 1), b3 + hstepB, voffB); PG8_STAGE(PG8_SA(1, 0), a3, voffA);
;             PG8_WAIT_V(8); PG8_WAIT_L(0); PG8_BAR;
;             if (last) E.pre(cur, wr, fr, rsv);
;             PG8_MMA(1, 0, At, B0); PG8_MMA(1, 1, At, B1); PG8_BAR; PG8_SCHED;
;         }
	s_add_i32 s65, 0, 0x18000
	v_add_u32_e32 v3, s65, v195
	s_add_i32 s68, 0, 0x1c000
	ds_read_b128 v[62:65], v3
	ds_read_b128 v[66:69], v3 offset:1024
	ds_read_b128 v[86:89], v3 offset:2048
	ds_read_b128 v[90:93], v3 offset:3072
	v_add_u32_e32 v3, s68, v195
	ds_read_b128 v[110:113], v3
	ds_read_b128 v[114:117], v3 offset:1024
	ds_read_b128 v[142:145], v3 offset:2048
	ds_read_b128 v[146:149], v3 offset:3072
	s_add_u32 s22, s22, 0xb0000
	s_addc_u32 s23, s23, 0
	s_mov_b32 m0, s30
	ds_read_b128 v[166:169], v201 offset:32768
	ds_read_b128 v[186:189], v201 offset:33792
	ds_read_b128 v[190:193], v201 offset:34816
	ds_read_b128 v[196:199], v201 offset:35840
	ds_read_b128 v[202:205], v201 offset:36864
	ds_read_b128 v[206:209], v201 offset:37888
	ds_read_b128 v[210:213], v201 offset:38912
	ds_read_b128 v[214:217], v201 offset:39936
	global_load_lds_dwordx4 v170, s[22:23]
	s_mov_b32 m0, s31
	s_nop 0
	global_load_lds_dwordx4 v174, s[22:23]
	s_waitcnt vmcnt(8)
	s_waitcnt lgkmcnt(0)
	s_barrier
	v_mfma_f32_16x16x32_bf16 v[74:77], v[62:65], v[166:169], v[74:77]
	v_mfma_f32_16x16x32_bf16 v[70:73], v[86:89], v[166:169], v[70:73]
	v_mfma_f32_16x16x32_bf16 v[106:109], v[62:65], v[190:193], v[106:109]
	v_mfma_f32_16x16x32_bf16 v[102:105], v[86:89], v[190:193], v[102:105]
	v_mfma_f32_16x16x32_bf16 v[138:141], v[62:65], v[202:205], v[138:141]
	v_mfma_f32_16x16x32_bf16 v[126:129], v[86:89], v[202:205], v[126:129]
	v_mfma_f32_16x16x32_bf16 v[122:125], v[62:65], v[210:213], v[122:125]
	v_mfma_f32_16x16x32_bf16 v[118:121], v[86:89], v[210:213], v[118:121]
	v_mfma_f32_16x16x32_bf16 v[74:77], v[66:69], v[186:189], v[74:77]
	v_mfma_f32_16x16x32_bf16 v[70:73], v[90:93], v[186:189], v[70:73]
	v_mfma_f32_16x16x32_bf16 v[106:109], v[66:69], v[196:199], v[106:109]
	v_mfma_f32_16x16x32_bf16 v[102:105], v[90:93], v[196:199], v[102:105]
	v_mfma_f32_16x16x32_bf16 v[138:141], v[66:69], v[206:209], v[138:141]
	v_mfma_f32_16x16x32_bf16 v[126:129], v[90:93], v[206:209], v[126:129]
	v_mfma_f32_16x16x32_bf16 v[122:125], v[66:69], v[214:217], v[122:125]
	v_mfma_f32_16x16x32_bf16 v[118:121], v[90:93], v[214:217], v[118:121]
	v_mfma_f32_16x16x32_bf16 v[162:165], v[110:113], v[166:169], v[162:165]
	v_mfma_f32_16x16x32_bf16 v[158:161], v[142:145], v[166:169], v[158:161]
	v_mfma_f32_16x16x32_bf16 v[154:157], v[110:113], v[190:193], v[154:157]
	v_mfma_f32_16x16x32_bf16 v[150:153], v[142:145], v[190:193], v[150:153]
	v_mfma_f32_16x16x32_bf16 v[134:137], v[110:113], v[202:205], v[134:137]
	v_mfma_f32_16x16x32_bf16 v[130:133], v[142:145], v[202:205], v[130:133]
	v_mfma_f32_16x16x32_bf16 v[98:101], v[110:113], v[210:213], v[98:101]
	v_mfma_f32_16x16x32_bf16 v[94:97], v[142:145], v[210:213], v[94:97]
	v_mfma_f32_16x16x32_bf16 v[162:165], v[114:117], v[186:189], v[162:165]
	v_mfma_f32_16x16x32_bf16 v[158:161], v[146:149], v[186:189], v[158:161]
	v_mfma_f32_16x16x32_bf16 v[154:157], v[114:117], v[196:199], v[154:157]
	v_mfma_f32_16x16x32_bf16 v[150:153], v[146:149], v[196:199], v[150:153]
	v_mfma_f32_16x16x32_bf16 v[134:137], v[114:117], v[206:209], v[134:137]
	v_mfma_f32_16x16x32_bf16 v[130:133], v[146:149], v[206:209], v[130:133]
	v_mfma_f32_16x16x32_bf16 v[98:101], v[114:117], v[214:217], v[98:101]
	v_mfma_f32_16x16x32_bf16 v[94:97], v[146:149], v[214:217], v[94:97]
	s_barrier
	s_add_i32 s22, s65, s27
	s_mov_b32 m0, s22
	ds_read_b128 v[166:169], v201 offset:49152
	ds_read_b128 v[186:189], v201 offset:50176
	ds_read_b128 v[190:193], v201 offset:51200
	ds_read_b128 v[196:199], v201 offset:52224
	ds_read_b128 v[202:205], v201 offset:53248
	ds_read_b128 v[206:209], v201 offset:54272
	ds_read_b128 v[210:213], v201 offset:55296
	ds_read_b128 v[214:217], v201 offset:56320
	global_load_lds_dwordx4 v218, s[20:21]
	s_add_i32 m0, s22, 0x2000
	s_add_u32 s20, s20, 0x20080
	s_addc_u32 s21, s21, 0
	s_add_i32 s22, s68, s27
	global_load_lds_dwordx4 v219, s[98:99]
	s_mov_b32 m0, s22
	s_nop 0
	global_load_lds_dwordx4 v172, s[20:21]
	s_add_i32 m0, s22, 0x2000
	s_nop 0
	global_load_lds_dwordx4 v176, s[20:21]
	s_mov_b32 m0, s40
	s_nop 0
	global_load_lds_dwordx4 v220, s[100:101]
	s_mov_b32 m0, s41
	s_nop 0
	global_load_lds_dwordx4 v221, s[100:101]
	s_waitcnt vmcnt(8)
	s_waitcnt lgkmcnt(0)
	s_barrier
	v_mfma_f32_16x16x32_bf16 v[82:85], v[62:65], v[166:169], v[82:85]
	v_mfma_f32_16x16x32_bf16 v[78:81], v[86:89], v[166:169], v[78:81]
	v_mfma_f32_16x16x32_bf16 v[50:53], v[62:65], v[190:193], v[50:53]
	v_mfma_f32_16x16x32_bf16 v[46:49], v[86:89], v[190:193], v[46:49]
	v_mfma_f32_16x16x32_bf16 v[34:37], v[62:65], v[202:205], v[34:37]
	v_mfma_f32_16x16x32_bf16 v[30:33], v[86:89], v[202:205], v[30:33]
	v_mfma_f32_16x16x32_bf16 v[18:21], v[62:65], v[210:213], v[18:21]
	v_mfma_f32_16x16x32_bf16 v[14:17], v[86:89], v[210:213], v[14:17]
	v_mfma_f32_16x16x32_bf16 v[82:85], v[66:69], v[186:189], v[82:85]
	v_mfma_f32_16x16x32_bf16 v[78:81], v[90:93], v[186:189], v[78:81]
	v_mfma_f32_16x16x32_bf16 v[50:53], v[66:69], v[196:199], v[50:53]
	v_mfma_f32_16x16x32_bf16 v[46:49], v[90:93], v[196:199], v[46:49]
	v_mfma_f32_16x16x32_bf16 v[34:37], v[66:69], v[206:209], v[34:37]
	v_mfma_f32_16x16x32_bf16 v[30:33], v[90:93], v[206:209], v[30:33]
	v_mfma_f32_16x16x32_bf16 v[18:21], v[66:69], v[214:217], v[18:21]
	v_mfma_f32_16x16x32_bf16 v[14:17], v[90:93], v[214:217], v[14:17]
	v_mfma_f32_16x16x32_bf16 v[58:61], v[110:113], v[166:169], v[58:61]
	v_mfma_f32_16x16x32_bf16 v[54:57], v[142:145], v[166:169], v[54:57]
	v_mfma_f32_16x16x32_bf16 v[42:45], v[110:113], v[190:193], v[42:45]
	v_mfma_f32_16x16x32_bf16 v[38:41], v[142:145], v[190:193], v[38:41]
	v_mfma_f32_16x16x32_bf16 v[26:29], v[110:113], v[202:205], v[26:29]
	v_mfma_f32_16x16x32_bf16 v[22:25], v[142:145], v[202:205], v[22:25]
	v_mfma_f32_16x16x32_bf16 v[8:11], v[110:113], v[210:213], v[10:13]
	v_mfma_f32_16x16x32_bf16 v[4:7], v[142:145], v[210:213], v[4:7]
	v_mfma_f32_16x16x32_bf16 v[58:61], v[114:117], v[186:189], v[58:61]
	v_mfma_f32_16x16x32_bf16 v[54:57], v[146:149], v[186:189], v[54:57]
	v_mfma_f32_16x16x32_bf16 v[42:45], v[114:117], v[196:199], v[42:45]
	v_mfma_f32_16x16x32_bf16 v[38:41], v[146:149], v[196:199], v[38:41]
	v_mfma_f32_16x16x32_bf16 v[26:29], v[114:117], v[206:209], v[26:29]
	v_mfma_f32_16x16x32_bf16 v[22:25], v[146:149], v[206:209], v[22:25]
	v_mfma_f32_16x16x32_bf16 v[10:13], v[114:117], v[214:217], v[8:11]
	v_mfma_f32_16x16x32_bf16 v[6:9], v[146:149], v[214:217], v[4:7]
	s_barrier
	s_add_i32 s64, s64, 2
	s_add_u32 s4, s4, 0x100
	s_addc_u32 s5, s5, 0
	s_add_u32 s15, s15, 0x100
	s_addc_u32 s63, s63, 0
	s_cmp_gt_u32 s64, 5
	s_cbranch_scc0 .LBB0_839
	s_and_b64 vcc, exec, s[12:13]
	s_cbranch_vccz .LBB0_842
	s_barrier

; #define PG8_STAGE(bufoff, gbase, voff) do { _Pragma("unroll") for (int _i = 0; _i < 2; ++_i) \
;         __builtin_amdgcn_global_load_lds((const unsigned*)((const char*)(gbase) + (voff)[_i]), (LAS unsigned*)(lds + (bufoff) + ldsw + _i * 8192), 16, 0, 0); } while (0)
; #define PG8_LDA(dst, b, h) do { _Pragma("unroll") for (int m = 0; m < 4; ++m) _Pragma("unroll") for (int k = 0; k < 2; ++k) dst[m][k] = *(const LAS bf16x8*)(lds + PG8_SA(b, h) + aoff + m * 2048 + k * 1024); } while (0)
; #define PG8_LDB(dst, b, h) do { _Pragma("unroll") for (int n = 0; n < 2; ++n) _Pragma("unroll") for (int k = 0; k < 2; ++k) dst[n][k] = *(const LAS bf16x8*)(lds + PG8_SB(b, h) + boff + n * 2048 + k * 1024); } while (0)
; #define PG8_MMA(ai, bj, At, Bt) do { __builtin_amdgcn_s_setprio(1); _Pragma("unroll") for (int m = 0; m < 4; ++m) _Pragma("unroll") for (int n = 0; n < 2; ++n) _Pragma("unroll") for (int k = 0; k < 2; ++k) \
;         acc[ai][bj][m][n] = __builtin_amdgcn_mfma_f32_16x16x32_bf16(Bt[n][k], At[m][k], acc[ai][bj][m][n], 0, 0, 0); __builtin_amdgcn_s_setprio(0); } while (0)
; #define PG8_WAIT_V(n) asm volatile("s_waitcnt vmcnt(" #n ")" ::: "memory")
; #define PG8_WAIT_L(n) asm volatile("s_waitcnt lgkmcnt(" #n ")" ::: "memory")
; #define PG8_BAR __builtin_amdgcn_s_barrier()
; #define PG8_SCHED __builtin_amdgcn_sched_barrier(0)
; template <class Epi, class Sched>
; __device__ __forceinline__ void gemm_phase(LAS unsigned char* lds, const int lda, const int ldb, const int K, const Sched& S, const Epi& E) {
;     ...
;         for (int t = 0; t < nt; t += 2) {
;             const bool last = (t == nt - 2);
;             const char* a1 = cA + (size_t)(t + 1) * kstep;
;             const char* a2 = last ? nA : cA + (size_t)(t + 2) * kstep; const char* b2 = last ? nB : cB + (size_t)(t + 2) * kstep;
;             const char* a3 = a2 + kstep; const char* b3 = b2 + kstep;
;             PG8_LDB(B0, 0, 0); PG8_LDB(B1, 0, 1); PG8_SCHED; PG8_LDA(At, 0, 0); PG8_STAGE(PG8_SA(1, 1), a1 + hstepA, voffA);
;             PG8_WAIT_V(8); PG8_WAIT_L(0); PG8_BAR; PG8_MMA(0, 0, At, B0); PG8_MMA(0, 1, At, B1); PG8_BAR; PG8_SCHED;
;             PG8_LDA(At, 0, 1); PG8_STAGE(PG8_SB(0, 0), b2, voffB); PG8_STAGE(PG8_SB(0, 1), b2 + hstepB, voffB); PG8_STAGE(PG8_SA(0, 0), a2, voffA);
;             PG8_WAIT_V(8); PG8_WAIT_L(0); PG8_BAR; PG8_MMA(1, 0, At, B0); PG8_MMA(1, 1, At, B1); PG8_BAR; PG8_SCHED;
.LBB0_955:
	s_add_u32 s24, s24, 0x40080
	s_addc_u32 s25, s25, 0
	s_add_u32 s15, s26, 0x100
	s_addc_u32 s17, s27, 0
	s_mov_b32 s23, -2
	s_waitcnt lgkmcnt(0)
	v_add_u32_e32 v192, 0x80, v156
	v_add_u32_e32 v193, 0x80, v160
	v_add_u32_e32 v220, 0x80, v154
	v_add_u32_e32 v221, 0x80, v158
	ds_read_b128 v[130:133], v188
	ds_read_b128 v[134:137], v188 offset:1024
	ds_read_b128 v[138:141], v188 offset:2048
	ds_read_b128 v[142:145], v188 offset:3072
	ds_read_b128 v[146:149], v189
	ds_read_b128 v[150:153], v189 offset:1024
	ds_read_b128 v[170:173], v189 offset:2048
	ds_read_b128 v[174:177], v189 offset:3072
	s_add_u32 s26, s24, 0xfffc0080
	s_addc_u32 s27, s25, -1
	s_cmp_eq_u32 s23, 12
	s_cselect_b32 s29, s19, s27
	s_cselect_b32 s28, s18, s26
	s_cselect_b32 s27, s21, s17
	s_cselect_b32 s26, s20, s15
	s_add_i32 m0, s33, 0xc000
	ds_read_b128 v[178:181], v190
	ds_read_b128 v[182:185], v190 offset:1024
	ds_read_b128 v[196:199], v190 offset:2048
	ds_read_b128 v[200:203], v190 offset:3072
	ds_read_b128 v[204:207], v190 offset:4096
	ds_read_b128 v[208:211], v190 offset:5120
	ds_read_b128 v[212:215], v190 offset:6144
	ds_read_b128 v[216:219], v190 offset:7168
	global_load_lds_dwordx4 v162, s[24:25]
	s_add_i32 m0, s33, 0xe000
	s_nop 0
	global_load_lds_dwordx4 v164, s[24:25]
	s_waitcnt vmcnt(8)
	s_waitcnt lgkmcnt(0)
	s_barrier
	v_mfma_f32_16x16x32_bf16 v[126:129], v[130:133], v[178:181], 0
	v_mfma_f32_16x16x32_bf16 v[122:125], v[138:141], v[178:181], 0
	v_mfma_f32_16x16x32_bf16 v[110:113], v[130:133], v[196:199], 0
	v_mfma_f32_16x16x32_bf16 v[106:109], v[138:141], v[196:199], 0
	v_mfma_f32_16x16x32_bf16 v[94:97], v[130:133], v[204:207], 0
	v_mfma_f32_16x16x32_bf16 v[90:93], v[138:141], v[204:207], 0
	v_mfma_f32_16x16x32_bf16 v[78:81], v[130:133], v[212:215], 0
	v_mfma_f32_16x16x32_bf16 v[74:77], v[138:141], v[212:215], 0
	v_mfma_f32_16x16x32_bf16 v[126:129], v[134:137], v[182:185], v[126:129]
	v_mfma_f32_16x16x32_bf16 v[122:125], v[142:145], v[182:185], v[122:125]
	v_mfma_f32_16x16x32_bf16 v[110:113], v[134:137], v[200:203], v[110:113]
	v_mfma_f32_16x16x32_bf16 v[106:109], v[142:145], v[200:203], v[106:109]
	v_mfma_f32_16x16x32_bf16 v[94:97], v[134:137], v[208:211], v[94:97]
	v_mfma_f32_16x16x32_bf16 v[90:93], v[142:145], v[208:211], v[90:93]
	v_mfma_f32_16x16x32_bf16 v[78:81], v[134:137], v[216:219], v[78:81]
	v_mfma_f32_16x16x32_bf16 v[74:77], v[142:145], v[216:219], v[74:77]
	v_mfma_f32_16x16x32_bf16 v[118:121], v[146:149], v[178:181], 0
	v_mfma_f32_16x16x32_bf16 v[114:117], v[170:173], v[178:181], 0
	v_mfma_f32_16x16x32_bf16 v[102:105], v[146:149], v[196:199], 0
	v_mfma_f32_16x16x32_bf16 v[98:101], v[170:173], v[196:199], 0
	v_mfma_f32_16x16x32_bf16 v[86:89], v[146:149], v[204:207], 0
	v_mfma_f32_16x16x32_bf16 v[82:85], v[170:173], v[204:207], 0
	v_mfma_f32_16x16x32_bf16 v[70:73], v[146:149], v[212:215], 0
	v_mfma_f32_16x16x32_bf16 v[66:69], v[170:173], v[212:215], 0
	v_mfma_f32_16x16x32_bf16 v[118:121], v[150:153], v[182:185], v[118:121]
	v_mfma_f32_16x16x32_bf16 v[114:117], v[174:177], v[182:185], v[114:117]
	v_mfma_f32_16x16x32_bf16 v[102:105], v[150:153], v[200:203], v[102:105]
	v_mfma_f32_16x16x32_bf16 v[98:101], v[174:177], v[200:203], v[98:101]
	v_mfma_f32_16x16x32_bf16 v[86:89], v[150:153], v[208:211], v[86:89]
	v_mfma_f32_16x16x32_bf16 v[82:85], v[174:177], v[208:211], v[82:85]
	v_mfma_f32_16x16x32_bf16 v[70:73], v[150:153], v[216:219], v[70:73]
	v_mfma_f32_16x16x32_bf16 v[66:69], v[174:177], v[216:219], v[66:69]
	s_barrier
	s_add_i32 s51, s48, s31
	s_mov_b32 m0, s51
	ds_read_b128 v[178:181], v190 offset:16384
	ds_read_b128 v[182:185], v190 offset:17408
	ds_read_b128 v[196:199], v190 offset:18432
	ds_read_b128 v[200:203], v190 offset:19456
	ds_read_b128 v[204:207], v190 offset:20480
	ds_read_b128 v[208:211], v190 offset:21504
	ds_read_b128 v[212:215], v190 offset:22528
	ds_read_b128 v[216:219], v190 offset:23552
	global_load_lds_dwordx4 v156, s[26:27]
	s_add_i32 m0, s51, 0x2000
	s_add_u32 s62, s26, 0x40000
	s_mov_b64 s[98:99], s[26:27]
	s_addc_u32 s63, s27, 0
	s_add_i32 s51, s49, s31
	global_load_lds_dwordx4 v160, s[26:27]
	s_mov_b32 m0, s51
	s_mov_b64 s[100:101], s[28:29]
	global_load_lds_dwordx4 v156, s[62:63]
	s_add_i32 m0, s51, 0x2000
	s_nop 0
	global_load_lds_dwordx4 v160, s[62:63]
	s_mov_b32 m0, s33
	s_nop 0
	global_load_lds_dwordx4 v154, s[28:29]
	s_mov_b32 m0, s34
	s_nop 0
	global_load_lds_dwordx4 v158, s[28:29]
	s_waitcnt vmcnt(8)
	s_waitcnt lgkmcnt(0)
	s_barrier
	v_mfma_f32_16x16x32_bf16 v[62:65], v[130:133], v[178:181], 0
	v_mfma_f32_16x16x32_bf16 v[58:61], v[138:141], v[178:181], 0
	v_mfma_f32_16x16x32_bf16 v[46:49], v[130:133], v[196:199], 0
	v_mfma_f32_16x16x32_bf16 v[42:45], v[138:141], v[196:199], 0
	v_mfma_f32_16x16x32_bf16 v[30:33], v[130:133], v[204:207], 0
	v_mfma_f32_16x16x32_bf16 v[26:29], v[138:141], v[204:207], 0
	v_mfma_f32_16x16x32_bf16 v[14:17], v[130:133], v[212:215], 0
	v_mfma_f32_16x16x32_bf16 v[10:13], v[138:141], v[212:215], 0
	v_mfma_f32_16x16x32_bf16 v[62:65], v[134:137], v[182:185], v[62:65]
	v_mfma_f32_16x16x32_bf16 v[58:61], v[142:145], v[182:185], v[58:61]
	v_mfma_f32_16x16x32_bf16 v[46:49], v[134:137], v[200:203], v[46:49]
	v_mfma_f32_16x16x32_bf16 v[42:45], v[142:145], v[200:203], v[42:45]
	v_mfma_f32_16x16x32_bf16 v[30:33], v[134:137], v[208:211], v[30:33]
	v_mfma_f32_16x16x32_bf16 v[26:29], v[142:145], v[208:211], v[26:29]
	v_mfma_f32_16x16x32_bf16 v[14:17], v[134:137], v[216:219], v[14:17]
	v_mfma_f32_16x16x32_bf16 v[10:13], v[142:145], v[216:219], v[10:13]
	v_mfma_f32_16x16x32_bf16 v[54:57], v[146:149], v[178:181], 0
	v_mfma_f32_16x16x32_bf16 v[50:53], v[170:173], v[178:181], 0
	v_mfma_f32_16x16x32_bf16 v[38:41], v[146:149], v[196:199], 0
	v_mfma_f32_16x16x32_bf16 v[34:37], v[170:173], v[196:199], 0
	v_mfma_f32_16x16x32_bf16 v[22:25], v[146:149], v[204:207], 0
	v_mfma_f32_16x16x32_bf16 v[18:21], v[170:173], v[204:207], 0
	v_mfma_f32_16x16x32_bf16 v[6:9], v[146:149], v[212:215], 0
	v_mfma_f32_16x16x32_bf16 v[2:5], v[170:173], v[212:215], 0
	v_mfma_f32_16x16x32_bf16 v[54:57], v[150:153], v[182:185], v[54:57]
	v_mfma_f32_16x16x32_bf16 v[50:53], v[174:177], v[182:185], v[50:53]
	v_mfma_f32_16x16x32_bf16 v[38:41], v[150:153], v[200:203], v[38:41]
	v_mfma_f32_16x16x32_bf16 v[34:37], v[174:177], v[200:203], v[34:37]
	v_mfma_f32_16x16x32_bf16 v[22:25], v[150:153], v[208:211], v[22:25]
	v_mfma_f32_16x16x32_bf16 v[18:21], v[174:177], v[208:211], v[18:21]
	v_mfma_f32_16x16x32_bf16 v[6:9], v[150:153], v[216:219], v[6:9]
	v_mfma_f32_16x16x32_bf16 v[2:5], v[174:177], v[216:219], v[2:5]
	s_barrier
	s_branch .Lpeel5_join
; #define PG8_STAGE(bufoff, gbase, voff) do { _Pragma("unroll") for (int _i = 0; _i < 2; ++_i) \
;         __builtin_amdgcn_global_load_lds((const unsigned*)((const char*)(gbase) + (voff)[_i]), (LAS unsigned*)(lds + (bufoff) + ldsw + _i * 8192), 16, 0, 0); } while (0)
; #define PG8_LDA(dst, b, h) do { _Pragma("unroll") for (int m = 0; m < 4; ++m) _Pragma("unroll") for (int k = 0; k < 2; ++k) dst[m][k] = *(const LAS bf16x8*)(lds + PG8_SA(b, h) + aoff + m * 2048 + k * 1024); } while (0)
; #define PG8_LDB(dst, b, h) do { _Pragma("unroll") for (int n = 0; n < 2; ++n) _Pragma("unroll") for (int k = 0; k < 2; ++k) dst[n][k] = *(const LAS bf16x8*)(lds + PG8_SB(b, h) + boff + n * 2048 + k * 1024); } while (0)
; #define PG8_MMA(ai, bj, At, Bt) do { __builtin_amdgcn_s_setprio(1); _Pragma("unroll") for (int m = 0; m < 4; ++m) _Pragma("unroll") for (int n = 0; n < 2; ++n) _Pragma("unroll") for (int k = 0; k < 2; ++k) \
;         acc[ai][bj][m][n] = __builtin_amdgcn_mfma_f32_16x16x32_bf16(Bt[n][k], At[m][k], acc[ai][bj][m][n], 0, 0, 0); __builtin_amdgcn_s_setprio(0); } while (0)
; #define PG8_WAIT_V(n) asm volatile("s_waitcnt vmcnt(" #n ")" ::: "memory")
; #define PG8_WAIT_L(n) asm volatile("s_waitcnt lgkmcnt(" #n ")" ::: "memory")
; #define PG8_BAR __builtin_amdgcn_s_barrier()
; #define PG8_SCHED __builtin_amdgcn_sched_barrier(0)
; template <class Epi, class Sched>
; __device__ __forceinline__ void gemm_phase(LAS unsigned char* lds, const int lda, const int ldb, const int K, const Sched& S, const Epi& E) {
;     ...
;             const bool last = (t == nt - 2);
;             const char* a1 = cA + (size_t)(t + 1) * kstep;
;             const char* a2 = last ? nA : cA + (size_t)(t + 2) * kstep; const char* b2 = last ? nB : cB + (size_t)(t + 2) * kstep;
;             const char* a3 = a2 + kstep; const char* b3 = b2 + kstep;
;             PG8_LDB(B0, 0, 0); PG8_LDB(B1, 0, 1); PG8_SCHED; PG8_LDA(At, 0, 0); PG8_STAGE(PG8_SA(1, 1), a1 + hstepA, voffA);
;             PG8_WAIT_V(8); PG8_WAIT_L(0); PG8_BAR; PG8_MMA(0, 0, At, B0); PG8_MMA(0, 1, At, B1); PG8_BAR; PG8_SCHED;
;             PG8_LDA(At, 0, 1); PG8_STAGE(PG8_SB(0, 0), b2, voffB); PG8_STAGE(PG8_SB(0, 1), b2 + hstepB, voffB); PG8_STAGE(PG8_SA(0, 0), a2, voffA);
;             PG8_WAIT_V(8); PG8_WAIT_L(0); PG8_BAR; PG8_MMA(1, 0, At, B0); PG8_MMA(1, 1, At, B1); PG8_BAR; PG8_SCHED;
.LBB0_956:
	ds_read_b128 v[130:133], v188
	ds_read_b128 v[134:137], v188 offset:1024
	ds_read_b128 v[138:141], v188 offset:2048
	ds_read_b128 v[142:145], v188 offset:3072
	ds_read_b128 v[146:149], v189
	ds_read_b128 v[150:153], v189 offset:1024
	ds_read_b128 v[170:173], v189 offset:2048
	ds_read_b128 v[174:177], v189 offset:3072
	s_add_u32 s26, s24, 0xfffc0080
	s_addc_u32 s27, s25, -1
	s_cmp_eq_u32 s23, 12
	s_cselect_b32 s29, s19, s27
	s_cselect_b32 s28, s18, s26
	s_cselect_b32 s27, s21, s17
	s_cselect_b32 s26, s20, s15
	s_add_i32 m0, s33, 0xc000
	ds_read_b128 v[178:181], v190
	ds_read_b128 v[182:185], v190 offset:1024
	ds_read_b128 v[196:199], v190 offset:2048
	ds_read_b128 v[200:203], v190 offset:3072
	ds_read_b128 v[204:207], v190 offset:4096
	ds_read_b128 v[208:211], v190 offset:5120
	ds_read_b128 v[212:215], v190 offset:6144
	ds_read_b128 v[216:219], v190 offset:7168
	global_load_lds_dwordx4 v162, s[24:25]
	s_add_i32 m0, s33, 0xe000
	s_nop 0
	global_load_lds_dwordx4 v164, s[24:25]
	s_waitcnt vmcnt(8)
	s_waitcnt lgkmcnt(0)
	s_barrier
	v_mfma_f32_16x16x32_bf16 v[126:129], v[130:133], v[178:181], v[126:129]
	v_mfma_f32_16x16x32_bf16 v[122:125], v[138:141], v[178:181], v[122:125]
	v_mfma_f32_16x16x32_bf16 v[110:113], v[130:133], v[196:199], v[110:113]
	v_mfma_f32_16x16x32_bf16 v[106:109], v[138:141], v[196:199], v[106:109]
	v_mfma_f32_16x16x32_bf16 v[94:97], v[130:133], v[204:207], v[94:97]
	v_mfma_f32_16x16x32_bf16 v[90:93], v[138:141], v[204:207], v[90:93]
	v_mfma_f32_16x16x32_bf16 v[78:81], v[130:133], v[212:215], v[78:81]
	v_mfma_f32_16x16x32_bf16 v[74:77], v[138:141], v[212:215], v[74:77]
	v_mfma_f32_16x16x32_bf16 v[126:129], v[134:137], v[182:185], v[126:129]
	v_mfma_f32_16x16x32_bf16 v[122:125], v[142:145], v[182:185], v[122:125]
	v_mfma_f32_16x16x32_bf16 v[110:113], v[134:137], v[200:203], v[110:113]
	v_mfma_f32_16x16x32_bf16 v[106:109], v[142:145], v[200:203], v[106:109]
	v_mfma_f32_16x16x32_bf16 v[94:97], v[134:137], v[208:211], v[94:97]
	v_mfma_f32_16x16x32_bf16 v[90:93], v[142:145], v[208:211], v[90:93]
	v_mfma_f32_16x16x32_bf16 v[78:81], v[134:137], v[216:219], v[78:81]
	v_mfma_f32_16x16x32_bf16 v[74:77], v[142:145], v[216:219], v[74:77]
	v_mfma_f32_16x16x32_bf16 v[118:121], v[146:149], v[178:181], v[118:121]
	v_mfma_f32_16x16x32_bf16 v[114:117], v[170:173], v[178:181], v[114:117]
	v_mfma_f32_16x16x32_bf16 v[102:105], v[146:149], v[196:199], v[102:105]
	v_mfma_f32_16x16x32_bf16 v[98:101], v[170:173], v[196:199], v[98:101]
	v_mfma_f32_16x16x32_bf16 v[86:89], v[146:149], v[204:207], v[86:89]
	v_mfma_f32_16x16x32_bf16 v[82:85], v[170:173], v[204:207], v[82:85]
	v_mfma_f32_16x16x32_bf16 v[70:73], v[146:149], v[212:215], v[70:73]
	v_mfma_f32_16x16x32_bf16 v[66:69], v[170:173], v[212:215], v[66:69]
	v_mfma_f32_16x16x32_bf16 v[118:121], v[150:153], v[182:185], v[118:121]
	v_mfma_f32_16x16x32_bf16 v[114:117], v[174:177], v[182:185], v[114:117]
	v_mfma_f32_16x16x32_bf16 v[102:105], v[150:153], v[200:203], v[102:105]
	v_mfma_f32_16x16x32_bf16 v[98:101], v[174:177], v[200:203], v[98:101]
	v_mfma_f32_16x16x32_bf16 v[86:89], v[150:153], v[208:211], v[86:89]
	v_mfma_f32_16x16x32_bf16 v[82:85], v[174:177], v[208:211], v[82:85]
	v_mfma_f32_16x16x32_bf16 v[70:73], v[150:153], v[216:219], v[70:73]
	v_mfma_f32_16x16x32_bf16 v[66:69], v[174:177], v[216:219], v[66:69]
	s_barrier
	s_add_i32 s51, s48, s31
	s_mov_b32 m0, s51
	ds_read_b128 v[178:181], v190 offset:16384
	ds_read_b128 v[182:185], v190 offset:17408
	ds_read_b128 v[196:199], v190 offset:18432
	ds_read_b128 v[200:203], v190 offset:19456
	ds_read_b128 v[204:207], v190 offset:20480
	ds_read_b128 v[208:211], v190 offset:21504
	ds_read_b128 v[212:215], v190 offset:22528
	ds_read_b128 v[216:219], v190 offset:23552
	global_load_lds_dwordx4 v156, s[26:27]
	s_add_i32 m0, s51, 0x2000
	s_add_u32 s62, s26, 0x40000
	s_mov_b64 s[98:99], s[26:27]
	s_addc_u32 s63, s27, 0
	s_add_i32 s51, s49, s31
	global_load_lds_dwordx4 v160, s[26:27]
	s_mov_b32 m0, s51
	s_mov_b64 s[100:101], s[28:29]
	global_load_lds_dwordx4 v156, s[62:63]
	s_add_i32 m0, s51, 0x2000
	s_nop 0
	global_load_lds_dwordx4 v160, s[62:63]
	s_mov_b32 m0, s33
	s_nop 0
	global_load_lds_dwordx4 v154, s[28:29]
	s_mov_b32 m0, s34
	s_nop 0
	global_load_lds_dwordx4 v158, s[28:29]
	s_waitcnt vmcnt(8)
	s_waitcnt lgkmcnt(0)
	s_barrier
	v_mfma_f32_16x16x32_bf16 v[62:65], v[130:133], v[178:181], v[62:65]
	v_mfma_f32_16x16x32_bf16 v[58:61], v[138:141], v[178:181], v[58:61]
	v_mfma_f32_16x16x32_bf16 v[46:49], v[130:133], v[196:199], v[46:49]
	v_mfma_f32_16x16x32_bf16 v[42:45], v[138:141], v[196:199], v[42:45]
	v_mfma_f32_16x16x32_bf16 v[30:33], v[130:133], v[204:207], v[30:33]
	v_mfma_f32_16x16x32_bf16 v[26:29], v[138:141], v[204:207], v[26:29]
	v_mfma_f32_16x16x32_bf16 v[14:17], v[130:133], v[212:215], v[14:17]
	v_mfma_f32_16x16x32_bf16 v[10:13], v[138:141], v[212:215], v[10:13]
	v_mfma_f32_16x16x32_bf16 v[62:65], v[134:137], v[182:185], v[62:65]
	v_mfma_f32_16x16x32_bf16 v[58:61], v[142:145], v[182:185], v[58:61]
	v_mfma_f32_16x16x32_bf16 v[46:49], v[134:137], v[200:203], v[46:49]
	v_mfma_f32_16x16x32_bf16 v[42:45], v[142:145], v[200:203], v[42:45]
	v_mfma_f32_16x16x32_bf16 v[30:33], v[134:137], v[208:211], v[30:33]
	v_mfma_f32_16x16x32_bf16 v[26:29], v[142:145], v[208:211], v[26:29]
	v_mfma_f32_16x16x32_bf16 v[14:17], v[134:137], v[216:219], v[14:17]
	v_mfma_f32_16x16x32_bf16 v[10:13], v[142:145], v[216:219], v[10:13]
	v_mfma_f32_16x16x32_bf16 v[54:57], v[146:149], v[178:181], v[54:57]
	v_mfma_f32_16x16x32_bf16 v[50:53], v[170:173], v[178:181], v[50:53]
	v_mfma_f32_16x16x32_bf16 v[38:41], v[146:149], v[196:199], v[38:41]
	v_mfma_f32_16x16x32_bf16 v[34:37], v[170:173], v[196:199], v[34:37]
	v_mfma_f32_16x16x32_bf16 v[22:25], v[146:149], v[204:207], v[22:25]
	v_mfma_f32_16x16x32_bf16 v[18:21], v[170:173], v[204:207], v[18:21]
	v_mfma_f32_16x16x32_bf16 v[6:9], v[146:149], v[212:215], v[6:9]
	v_mfma_f32_16x16x32_bf16 v[2:5], v[170:173], v[212:215], v[2:5]
	v_mfma_f32_16x16x32_bf16 v[54:57], v[150:153], v[182:185], v[54:57]
	v_mfma_f32_16x16x32_bf16 v[50:53], v[174:177], v[182:185], v[50:53]
	v_mfma_f32_16x16x32_bf16 v[38:41], v[150:153], v[200:203], v[38:41]
	v_mfma_f32_16x16x32_bf16 v[34:37], v[174:177], v[200:203], v[34:37]
	v_mfma_f32_16x16x32_bf16 v[22:25], v[150:153], v[208:211], v[22:25]
	v_mfma_f32_16x16x32_bf16 v[18:21], v[174:177], v[208:211], v[18:21]
	v_mfma_f32_16x16x32_bf16 v[6:9], v[150:153], v[216:219], v[6:9]
	v_mfma_f32_16x16x32_bf16 v[2:5], v[174:177], v[216:219], v[2:5]
	s_barrier
; #define PG8_STAGE(bufoff, gbase, voff) do { _Pragma("unroll") for (int _i = 0; _i < 2; ++_i) \
;         __builtin_amdgcn_global_load_lds((const unsigned*)((const char*)(gbase) + (voff)[_i]), (LAS unsigned*)(lds + (bufoff) + ldsw + _i * 8192), 16, 0, 0); } while (0)
; #define PG8_LDA(dst, b, h) do { _Pragma("unroll") for (int m = 0; m < 4; ++m) _Pragma("unroll") for (int k = 0; k < 2; ++k) dst[m][k] = *(const LAS bf16x8*)(lds + PG8_SA(b, h) + aoff + m * 2048 + k * 1024); } while (0)
; #define PG8_LDB(dst, b, h) do { _Pragma("unroll") for (int n = 0; n < 2; ++n) _Pragma("unroll") for (int k = 0; k < 2; ++k) dst[n][k] = *(const LAS bf16x8*)(lds + PG8_SB(b, h) + boff + n * 2048 + k * 1024); } while (0)
; #define PG8_MMA(ai, bj, At, Bt) do { __builtin_amdgcn_s_setprio(1); _Pragma("unroll") for (int m = 0; m < 4; ++m) _Pragma("unroll") for (int n = 0; n < 2; ++n) _Pragma("unroll") for (int k = 0; k < 2; ++k) \
;         acc[ai][bj][m][n] = __builtin_amdgcn_mfma_f32_16x16x32_bf16(Bt[n][k], At[m][k], acc[ai][bj][m][n], 0, 0, 0); __builtin_amdgcn_s_setprio(0); } while (0)
; #define PG8_WAIT_V(n) asm volatile("s_waitcnt vmcnt(" #n ")" ::: "memory")
; #define PG8_WAIT_L(n) asm volatile("s_waitcnt lgkmcnt(" #n ")" ::: "memory")
; #define PG8_BAR __builtin_amdgcn_s_barrier()
; #define PG8_SCHED __builtin_amdgcn_sched_barrier(0)
; template <class Epi, class Sched>
; __device__ __forceinline__ void gemm_phase(LAS unsigned char* lds, const int lda, const int ldb, const int K, const Sched& S, const Epi& E) {
;     ...
;             PG8_LDB(B0, 1, 0); PG8_LDB(B1, 1, 1); PG8_SCHED; PG8_LDA(At, 1, 0); PG8_STAGE(PG8_SA(0, 1), a2 + hstepA, voffA);
;             PG8_WAIT_V(8); PG8_WAIT_L(0); PG8_BAR; PG8_MMA(0, 0, At, B0); PG8_MMA(0, 1, At, B1); PG8_BAR; PG8_SCHED;
;             PG8_LDA(At, 1, 1); PG8_STAGE(PG8_SB(1, 0), b3, voffB); PG8_STAGE(PG8_SB(1, 1), b3 + hstepB, voffB); PG8_STAGE(PG8_SA(1, 0), a3, voffA);
;             PG8_WAIT_V(8); PG8_WAIT_L(0); PG8_BAR;
;             if (last) E.pre(cur, wr, fr, rsv);
;             PG8_MMA(1, 0, At, B0); PG8_MMA(1, 1, At, B1); PG8_BAR; PG8_SCHED;
;         }
;         if (wr == 0) PG8_BAR;
.Lpeel5_join:
	s_add_i32 s51, 0, 0x18000
	s_add_i32 s62, 0, 0x1c000
	v_add_u32_e32 v142, s51, v186
	v_add_u32_e32 v174, s62, v186
	ds_read_b128 v[130:133], v142
	ds_read_b128 v[134:137], v142 offset:1024
	ds_read_b128 v[138:141], v142 offset:2048
	ds_read_b128 v[142:145], v142 offset:3072
	ds_read_b128 v[146:149], v174
	ds_read_b128 v[150:153], v174 offset:1024
	ds_read_b128 v[170:173], v174 offset:2048
	ds_read_b128 v[174:177], v174 offset:3072
	s_add_u32 s28, s28, 0x40000
	s_addc_u32 s29, s29, 0
	s_mov_b32 m0, s35
	ds_read_b128 v[178:181], v190 offset:32768
	ds_read_b128 v[182:185], v190 offset:33792
	ds_read_b128 v[196:199], v190 offset:34816
	ds_read_b128 v[200:203], v190 offset:35840
	ds_read_b128 v[204:207], v190 offset:36864
	ds_read_b128 v[208:211], v190 offset:37888
	ds_read_b128 v[212:215], v190 offset:38912
	ds_read_b128 v[216:219], v190 offset:39936
	global_load_lds_dwordx4 v154, s[28:29]
	s_mov_b32 m0, s38
	s_nop 0
	global_load_lds_dwordx4 v158, s[28:29]
	s_waitcnt vmcnt(8)
	s_waitcnt lgkmcnt(0)
	s_barrier
	v_mfma_f32_16x16x32_bf16 v[126:129], v[130:133], v[178:181], v[126:129]
	v_mfma_f32_16x16x32_bf16 v[122:125], v[138:141], v[178:181], v[122:125]
	v_mfma_f32_16x16x32_bf16 v[110:113], v[130:133], v[196:199], v[110:113]
	v_mfma_f32_16x16x32_bf16 v[106:109], v[138:141], v[196:199], v[106:109]
	v_mfma_f32_16x16x32_bf16 v[94:97], v[130:133], v[204:207], v[94:97]
	v_mfma_f32_16x16x32_bf16 v[90:93], v[138:141], v[204:207], v[90:93]
	v_mfma_f32_16x16x32_bf16 v[78:81], v[130:133], v[212:215], v[78:81]
	v_mfma_f32_16x16x32_bf16 v[74:77], v[138:141], v[212:215], v[74:77]
	v_mfma_f32_16x16x32_bf16 v[126:129], v[134:137], v[182:185], v[126:129]
	v_mfma_f32_16x16x32_bf16 v[122:125], v[142:145], v[182:185], v[122:125]
	v_mfma_f32_16x16x32_bf16 v[110:113], v[134:137], v[200:203], v[110:113]
	v_mfma_f32_16x16x32_bf16 v[106:109], v[142:145], v[200:203], v[106:109]
	v_mfma_f32_16x16x32_bf16 v[94:97], v[134:137], v[208:211], v[94:97]
	v_mfma_f32_16x16x32_bf16 v[90:93], v[142:145], v[208:211], v[90:93]
	v_mfma_f32_16x16x32_bf16 v[78:81], v[134:137], v[216:219], v[78:81]
	v_mfma_f32_16x16x32_bf16 v[74:77], v[142:145], v[216:219], v[74:77]
	v_mfma_f32_16x16x32_bf16 v[118:121], v[146:149], v[178:181], v[118:121]
	v_mfma_f32_16x16x32_bf16 v[114:117], v[170:173], v[178:181], v[114:117]
	v_mfma_f32_16x16x32_bf16 v[102:105], v[146:149], v[196:199], v[102:105]
	v_mfma_f32_16x16x32_bf16 v[98:101], v[170:173], v[196:199], v[98:101]
	v_mfma_f32_16x16x32_bf16 v[86:89], v[146:149], v[204:207], v[86:89]
	v_mfma_f32_16x16x32_bf16 v[82:85], v[170:173], v[204:207], v[82:85]
	v_mfma_f32_16x16x32_bf16 v[70:73], v[146:149], v[212:215], v[70:73]
	v_mfma_f32_16x16x32_bf16 v[66:69], v[170:173], v[212:215], v[66:69]
	v_mfma_f32_16x16x32_bf16 v[118:121], v[150:153], v[182:185], v[118:121]
	v_mfma_f32_16x16x32_bf16 v[114:117], v[174:177], v[182:185], v[114:117]
	v_mfma_f32_16x16x32_bf16 v[102:105], v[150:153], v[200:203], v[102:105]
	v_mfma_f32_16x16x32_bf16 v[98:101], v[174:177], v[200:203], v[98:101]
	v_mfma_f32_16x16x32_bf16 v[86:89], v[150:153], v[208:211], v[86:89]
	v_mfma_f32_16x16x32_bf16 v[82:85], v[174:177], v[208:211], v[82:85]
	v_mfma_f32_16x16x32_bf16 v[70:73], v[150:153], v[216:219], v[70:73]
	v_mfma_f32_16x16x32_bf16 v[66:69], v[174:177], v[216:219], v[66:69]
	s_barrier
	s_add_i32 s28, s51, s31
	s_mov_b32 m0, s28
	ds_read_b128 v[178:181], v190 offset:49152
	ds_read_b128 v[182:185], v190 offset:50176
	ds_read_b128 v[196:199], v190 offset:51200
	ds_read_b128 v[200:203], v190 offset:52224
	ds_read_b128 v[204:207], v190 offset:53248
	ds_read_b128 v[208:211], v190 offset:54272
	ds_read_b128 v[212:215], v190 offset:55296
	ds_read_b128 v[216:219], v190 offset:56320
	global_load_lds_dwordx4 v192, s[26:27]
	s_add_i32 m0, s28, 0x2000
	s_add_u32 s26, s26, 0x40080
	s_addc_u32 s27, s27, 0
	s_add_i32 s28, s62, s31
	global_load_lds_dwordx4 v193, s[98:99]
	s_mov_b32 m0, s28
	s_nop 0
	global_load_lds_dwordx4 v156, s[26:27]
	s_add_i32 m0, s28, 0x2000
	s_nop 0
	global_load_lds_dwordx4 v160, s[26:27]
	s_mov_b32 m0, s41
	s_nop 0
	global_load_lds_dwordx4 v220, s[100:101]
	s_mov_b32 m0, s42
	s_nop 0
	global_load_lds_dwordx4 v221, s[100:101]
	s_waitcnt vmcnt(8)
	s_waitcnt lgkmcnt(0)
	s_barrier
	v_mfma_f32_16x16x32_bf16 v[62:65], v[130:133], v[178:181], v[62:65]
	v_mfma_f32_16x16x32_bf16 v[58:61], v[138:141], v[178:181], v[58:61]
	v_mfma_f32_16x16x32_bf16 v[46:49], v[130:133], v[196:199], v[46:49]
	v_mfma_f32_16x16x32_bf16 v[42:45], v[138:141], v[196:199], v[42:45]
	v_mfma_f32_16x16x32_bf16 v[30:33], v[130:133], v[204:207], v[30:33]
	v_mfma_f32_16x16x32_bf16 v[26:29], v[138:141], v[204:207], v[26:29]
	v_mfma_f32_16x16x32_bf16 v[14:17], v[130:133], v[212:215], v[14:17]
	v_mfma_f32_16x16x32_bf16 v[10:13], v[138:141], v[212:215], v[10:13]
	v_mfma_f32_16x16x32_bf16 v[62:65], v[134:137], v[182:185], v[62:65]
	v_mfma_f32_16x16x32_bf16 v[58:61], v[142:145], v[182:185], v[58:61]
	v_mfma_f32_16x16x32_bf16 v[46:49], v[134:137], v[200:203], v[46:49]
	v_mfma_f32_16x16x32_bf16 v[42:45], v[142:145], v[200:203], v[42:45]
	v_mfma_f32_16x16x32_bf16 v[30:33], v[134:137], v[208:211], v[30:33]
	v_mfma_f32_16x16x32_bf16 v[26:29], v[142:145], v[208:211], v[26:29]
	v_mfma_f32_16x16x32_bf16 v[14:17], v[134:137], v[216:219], v[14:17]
	v_mfma_f32_16x16x32_bf16 v[10:13], v[142:145], v[216:219], v[10:13]
	v_mfma_f32_16x16x32_bf16 v[54:57], v[146:149], v[178:181], v[54:57]
	v_mfma_f32_16x16x32_bf16 v[50:53], v[170:173], v[178:181], v[50:53]
	v_mfma_f32_16x16x32_bf16 v[38:41], v[146:149], v[196:199], v[38:41]
	v_mfma_f32_16x16x32_bf16 v[34:37], v[170:173], v[196:199], v[34:37]
	v_mfma_f32_16x16x32_bf16 v[22:25], v[146:149], v[204:207], v[22:25]
	v_mfma_f32_16x16x32_bf16 v[18:21], v[170:173], v[204:207], v[18:21]
	v_mfma_f32_16x16x32_bf16 v[6:9], v[146:149], v[212:215], v[6:9]
	v_mfma_f32_16x16x32_bf16 v[2:5], v[170:173], v[212:215], v[2:5]
	v_mfma_f32_16x16x32_bf16 v[54:57], v[150:153], v[182:185], v[54:57]
	v_mfma_f32_16x16x32_bf16 v[50:53], v[174:177], v[182:185], v[50:53]
	v_mfma_f32_16x16x32_bf16 v[38:41], v[150:153], v[200:203], v[38:41]
	v_mfma_f32_16x16x32_bf16 v[34:37], v[174:177], v[200:203], v[34:37]
	v_mfma_f32_16x16x32_bf16 v[22:25], v[150:153], v[208:211], v[22:25]
	v_mfma_f32_16x16x32_bf16 v[18:21], v[174:177], v[208:211], v[18:21]
	v_mfma_f32_16x16x32_bf16 v[6:9], v[150:153], v[216:219], v[6:9]
	v_mfma_f32_16x16x32_bf16 v[2:5], v[174:177], v[216:219], v[2:5]
	s_barrier
	s_add_i32 s23, s23, 2
	s_add_u32 s24, s24, 0x100
	s_addc_u32 s25, s25, 0
	s_add_u32 s15, s15, 0x100
	s_addc_u32 s17, s17, 0
	s_cmp_gt_u32 s23, 13
	s_cbranch_scc0 .LBB0_956
	s_and_b64 vcc, exec, s[12:13]
	s_cbranch_vccz .LBB0_959
	s_barrier

; #define PG8_STAGE(bufoff, gbase, voff) do { _Pragma("unroll") for (int _i = 0; _i < 2; ++_i) \
;         __builtin_amdgcn_global_load_lds((const unsigned*)((const char*)(gbase) + (voff)[_i]), (LAS unsigned*)(lds + (bufoff) + ldsw + _i * 8192), 16, 0, 0); } while (0)
; #define PG8_LDA(dst, b, h) do { _Pragma("unroll") for (int m = 0; m < 4; ++m) _Pragma("unroll") for (int k = 0; k < 2; ++k) dst[m][k] = *(const LAS bf16x8*)(lds + PG8_SA(b, h) + aoff + m * 2048 + k * 1024); } while (0)
; #define PG8_LDB(dst, b, h) do { _Pragma("unroll") for (int n = 0; n < 2; ++n) _Pragma("unroll") for (int k = 0; k < 2; ++k) dst[n][k] = *(const LAS bf16x8*)(lds + PG8_SB(b, h) + boff + n * 2048 + k * 1024); } while (0)
; #define PG8_MMA(ai, bj, At, Bt) do { __builtin_amdgcn_s_setprio(1); _Pragma("unroll") for (int m = 0; m < 4; ++m) _Pragma("unroll") for (int n = 0; n < 2; ++n) _Pragma("unroll") for (int k = 0; k < 2; ++k) \
;         acc[ai][bj][m][n] = __builtin_amdgcn_mfma_f32_16x16x32_bf16(Bt[n][k], At[m][k], acc[ai][bj][m][n], 0, 0, 0); __builtin_amdgcn_s_setprio(0); } while (0)
; #define PG8_WAIT_V(n) asm volatile("s_waitcnt vmcnt(" #n ")" ::: "memory")
; #define PG8_WAIT_L(n) asm volatile("s_waitcnt lgkmcnt(" #n ")" ::: "memory")
; #define PG8_BAR __builtin_amdgcn_s_barrier()
; #define PG8_SCHED __builtin_amdgcn_sched_barrier(0)
; template <class Epi, class Sched>
; __device__ __forceinline__ void gemm_phase(LAS unsigned char* lds, const int lda, const int ldb, const int K, const Sched& S, const Epi& E) {
;     ...
;         for (int t = 0; t < nt; t += 2) {
;             const bool last = (t == nt - 2);
;             const char* a1 = cA + (size_t)(t + 1) * kstep;
;             const char* a2 = last ? nA : cA + (size_t)(t + 2) * kstep; const char* b2 = last ? nB : cB + (size_t)(t + 2) * kstep;
;             const char* a3 = a2 + kstep; const char* b3 = b2 + kstep;
;             PG8_LDB(B0, 0, 0); PG8_LDB(B1, 0, 1); PG8_SCHED; PG8_LDA(At, 0, 0); PG8_STAGE(PG8_SA(1, 1), a1 + hstepA, voffA);
;             PG8_WAIT_V(8); PG8_WAIT_L(0); PG8_BAR; PG8_MMA(0, 0, At, B0); PG8_MMA(0, 1, At, B1); PG8_BAR; PG8_SCHED;
;             PG8_LDA(At, 0, 1); PG8_STAGE(PG8_SB(0, 0), b2, voffB); PG8_STAGE(PG8_SB(0, 1), b2 + hstepB, voffB); PG8_STAGE(PG8_SA(0, 0), a2, voffA);
;             PG8_WAIT_V(8); PG8_WAIT_L(0); PG8_BAR; PG8_MMA(1, 0, At, B0); PG8_MMA(1, 1, At, B1); PG8_BAR; PG8_SCHED;
.LBB0_1052:
	s_lshl_b32 s20, s20, 8
	s_ashr_i32 s21, s20, 31
	s_add_u32 s22, s22, 0x40080
	s_addc_u32 s23, s23, 0
	s_add_u32 s13, s24, 0x100
	v_lshl_add_u64 v[214:215], s[20:21], 2, v[204:205]
	s_addc_u32 s15, s25, 0
	s_mov_b32 s21, -2
	v_add_u32_e32 v230, 0x80, v200
	v_add_u32_e32 v231, 0x80, v196
	v_add_u32_e32 v232, 0x80, v202
	v_add_u32_e32 v233, 0x80, v198
	s_add_u32 s24, s22, 0xfffc0080
	s_addc_u32 s25, s23, -1
	s_cmp_eq_u32 s21, 12
	s_cselect_b32 s29, s17, s25
	s_cselect_b32 s28, s16, s24
	s_cselect_b32 s31, s19, s15
	s_cselect_b32 s30, s18, s13
	s_add_i32 s70, s50, s36
	s_add_i32 m0, s39, 0xc000
	s_add_i32 s69, s39, 0xe000
	s_add_i32 s71, s70, 0x2000
	s_add_u32 s34, s30, 0x40000
	s_addc_u32 s35, s31, 0
	s_add_i32 s72, s51, s36
	s_add_i32 s73, s72, 0x2000
	s_add_i32 s74, 0, 0x18000
	s_add_i32 s75, 0, 0x1c000
	s_add_u32 s26, s28, 0x40000
	s_addc_u32 s27, s29, 0
	s_add_i32 s66, s74, s36
	s_add_i32 s65, s66, 0x2000
	s_add_u32 s24, s30, 0x40080
	s_addc_u32 s25, s31, 0
	s_add_i32 s68, s75, s36
	s_add_i32 s67, s68, 0x2000
	s_cmp_lg_u32 s21, 12
	global_load_lds_dwordx4 v206, s[22:23]
	s_mov_b32 m0, s69
	s_nop 0
	global_load_lds_dwordx4 v208, s[22:23]
	s_waitcnt vmcnt(8)
	s_waitcnt lgkmcnt(0)
	s_barrier
	v_mfma_f32_16x16x32_bf16 v[126:129], v[130:133], v[162:165], 0
	v_mfma_f32_16x16x32_bf16 v[118:121], v[138:141], v[162:165], 0
	v_mfma_f32_16x16x32_bf16 v[110:113], v[130:133], v[170:173], 0
	v_mfma_f32_16x16x32_bf16 v[102:105], v[138:141], v[170:173], 0
	v_mfma_f32_16x16x32_bf16 v[94:97], v[130:133], v[178:181], 0
	v_mfma_f32_16x16x32_bf16 v[86:89], v[138:141], v[178:181], 0
	v_mfma_f32_16x16x32_bf16 v[78:81], v[130:133], v[186:189], 0
	v_mfma_f32_16x16x32_bf16 v[70:73], v[138:141], v[186:189], 0
	v_mfma_f32_16x16x32_bf16 v[126:129], v[134:137], v[166:169], v[126:129]
	v_mfma_f32_16x16x32_bf16 v[118:121], v[142:145], v[166:169], v[118:121]
	v_mfma_f32_16x16x32_bf16 v[110:113], v[134:137], v[174:177], v[110:113]
	v_mfma_f32_16x16x32_bf16 v[102:105], v[142:145], v[174:177], v[102:105]
	v_mfma_f32_16x16x32_bf16 v[94:97], v[134:137], v[182:185], v[94:97]
	v_mfma_f32_16x16x32_bf16 v[86:89], v[142:145], v[182:185], v[86:89]
	v_mfma_f32_16x16x32_bf16 v[78:81], v[134:137], v[190:193], v[78:81]
	v_mfma_f32_16x16x32_bf16 v[70:73], v[142:145], v[190:193], v[70:73]
	v_mfma_f32_16x16x32_bf16 v[122:125], v[146:149], v[162:165], 0
	v_mfma_f32_16x16x32_bf16 v[114:117], v[154:157], v[162:165], 0
	v_mfma_f32_16x16x32_bf16 v[106:109], v[146:149], v[170:173], 0
	v_mfma_f32_16x16x32_bf16 v[98:101], v[154:157], v[170:173], 0
	v_mfma_f32_16x16x32_bf16 v[90:93], v[146:149], v[178:181], 0
	v_mfma_f32_16x16x32_bf16 v[82:85], v[154:157], v[178:181], 0
	v_mfma_f32_16x16x32_bf16 v[74:77], v[146:149], v[186:189], 0
	v_mfma_f32_16x16x32_bf16 v[66:69], v[154:157], v[186:189], 0
	v_mfma_f32_16x16x32_bf16 v[122:125], v[150:153], v[166:169], v[122:125]
	v_mfma_f32_16x16x32_bf16 v[114:117], v[158:161], v[166:169], v[114:117]
	v_mfma_f32_16x16x32_bf16 v[106:109], v[150:153], v[174:177], v[106:109]
	v_mfma_f32_16x16x32_bf16 v[98:101], v[158:161], v[174:177], v[98:101]
	v_mfma_f32_16x16x32_bf16 v[90:93], v[150:153], v[182:185], v[90:93]
	v_mfma_f32_16x16x32_bf16 v[82:85], v[158:161], v[182:185], v[82:85]
	v_mfma_f32_16x16x32_bf16 v[74:77], v[150:153], v[190:193], v[74:77]
	v_mfma_f32_16x16x32_bf16 v[66:69], v[158:161], v[190:193], v[66:69]
	s_barrier
	s_mov_b32 m0, s70
	ds_read_b128 v[162:165], v219 offset:16384
	ds_read_b128 v[166:169], v219 offset:17408
	ds_read_b128 v[170:173], v219 offset:18432
	ds_read_b128 v[174:177], v219 offset:19456
	ds_read_b128 v[178:181], v219 offset:20480
	ds_read_b128 v[182:185], v219 offset:21504
	ds_read_b128 v[186:189], v219 offset:22528
	ds_read_b128 v[190:193], v219 offset:23552
	global_load_lds_dwordx4 v200, s[30:31]
	s_mov_b32 m0, s71
	s_nop 0
	global_load_lds_dwordx4 v196, s[30:31]
	s_mov_b32 m0, s72
	s_nop 0
	global_load_lds_dwordx4 v200, s[34:35]
	s_mov_b32 m0, s73
	s_nop 0
	global_load_lds_dwordx4 v196, s[34:35]
	s_mov_b32 m0, s39
	s_nop 0
	global_load_lds_dwordx4 v202, s[28:29]
	s_mov_b32 m0, s40
	s_nop 0
	global_load_lds_dwordx4 v198, s[28:29]
	s_waitcnt vmcnt(8)
	s_waitcnt lgkmcnt(0)
	s_barrier
	v_mfma_f32_16x16x32_bf16 v[62:65], v[130:133], v[162:165], 0
	v_mfma_f32_16x16x32_bf16 v[54:57], v[138:141], v[162:165], 0
	v_mfma_f32_16x16x32_bf16 v[46:49], v[130:133], v[170:173], 0
	v_mfma_f32_16x16x32_bf16 v[38:41], v[138:141], v[170:173], 0
	v_mfma_f32_16x16x32_bf16 v[30:33], v[130:133], v[178:181], 0
	v_mfma_f32_16x16x32_bf16 v[22:25], v[138:141], v[178:181], 0
	v_mfma_f32_16x16x32_bf16 v[14:17], v[130:133], v[186:189], 0
	v_mfma_f32_16x16x32_bf16 v[6:9], v[138:141], v[186:189], 0
	v_mfma_f32_16x16x32_bf16 v[62:65], v[134:137], v[166:169], v[62:65]
	v_mfma_f32_16x16x32_bf16 v[54:57], v[142:145], v[166:169], v[54:57]
	v_mfma_f32_16x16x32_bf16 v[46:49], v[134:137], v[174:177], v[46:49]
	v_mfma_f32_16x16x32_bf16 v[38:41], v[142:145], v[174:177], v[38:41]
	v_mfma_f32_16x16x32_bf16 v[30:33], v[134:137], v[182:185], v[30:33]
	v_mfma_f32_16x16x32_bf16 v[22:25], v[142:145], v[182:185], v[22:25]
	v_mfma_f32_16x16x32_bf16 v[14:17], v[134:137], v[190:193], v[14:17]
	v_mfma_f32_16x16x32_bf16 v[6:9], v[142:145], v[190:193], v[6:9]
	v_mfma_f32_16x16x32_bf16 v[58:61], v[146:149], v[162:165], 0
	v_mfma_f32_16x16x32_bf16 v[50:53], v[154:157], v[162:165], 0
	v_mfma_f32_16x16x32_bf16 v[42:45], v[146:149], v[170:173], 0
	v_mfma_f32_16x16x32_bf16 v[34:37], v[154:157], v[170:173], 0
	v_mfma_f32_16x16x32_bf16 v[26:29], v[146:149], v[178:181], 0
	v_mfma_f32_16x16x32_bf16 v[18:21], v[154:157], v[178:181], 0
	v_mfma_f32_16x16x32_bf16 v[10:13], v[146:149], v[186:189], 0
	v_mfma_f32_16x16x32_bf16 v[2:5], v[154:157], v[186:189], 0
	v_mfma_f32_16x16x32_bf16 v[58:61], v[150:153], v[166:169], v[58:61]
	v_mfma_f32_16x16x32_bf16 v[50:53], v[158:161], v[166:169], v[50:53]
	v_mfma_f32_16x16x32_bf16 v[42:45], v[150:153], v[174:177], v[42:45]
	v_mfma_f32_16x16x32_bf16 v[34:37], v[158:161], v[174:177], v[34:37]
	v_mfma_f32_16x16x32_bf16 v[26:29], v[150:153], v[182:185], v[26:29]
	v_mfma_f32_16x16x32_bf16 v[18:21], v[158:161], v[182:185], v[18:21]
	v_mfma_f32_16x16x32_bf16 v[10:13], v[150:153], v[190:193], v[10:13]
	v_mfma_f32_16x16x32_bf16 v[2:5], v[158:161], v[190:193], v[2:5]
	s_barrier
	s_branch .Lpeel6_join
; #define PG8_STAGE(bufoff, gbase, voff) do { _Pragma("unroll") for (int _i = 0; _i < 2; ++_i) \
;         __builtin_amdgcn_global_load_lds((const unsigned*)((const char*)(gbase) + (voff)[_i]), (LAS unsigned*)(lds + (bufoff) + ldsw + _i * 8192), 16, 0, 0); } while (0)
; #define PG8_LDA(dst, b, h) do { _Pragma("unroll") for (int m = 0; m < 4; ++m) _Pragma("unroll") for (int k = 0; k < 2; ++k) dst[m][k] = *(const LAS bf16x8*)(lds + PG8_SA(b, h) + aoff + m * 2048 + k * 1024); } while (0)
; #define PG8_LDB(dst, b, h) do { _Pragma("unroll") for (int n = 0; n < 2; ++n) _Pragma("unroll") for (int k = 0; k < 2; ++k) dst[n][k] = *(const LAS bf16x8*)(lds + PG8_SB(b, h) + boff + n * 2048 + k * 1024); } while (0)
; #define PG8_MMA(ai, bj, At, Bt) do { __builtin_amdgcn_s_setprio(1); _Pragma("unroll") for (int m = 0; m < 4; ++m) _Pragma("unroll") for (int n = 0; n < 2; ++n) _Pragma("unroll") for (int k = 0; k < 2; ++k) \
;         acc[ai][bj][m][n] = __builtin_amdgcn_mfma_f32_16x16x32_bf16(Bt[n][k], At[m][k], acc[ai][bj][m][n], 0, 0, 0); __builtin_amdgcn_s_setprio(0); } while (0)
; template <class Epi, class Sched>
; __device__ __forceinline__ void gemm_phase(LAS unsigned char* lds, const int lda, const int ldb, const int K, const Sched& S, const Epi& E) {
;     ...
;             PG8_LDB(B0, 0, 0); PG8_LDB(B1, 0, 1); PG8_SCHED; PG8_LDA(At, 0, 0); PG8_STAGE(PG8_SA(1, 1), a1 + hstepA, voffA);
;             PG8_WAIT_V(8); PG8_WAIT_L(0); PG8_BAR; PG8_MMA(0, 0, At, B0); PG8_MMA(0, 1, At, B1); PG8_BAR; PG8_SCHED;
;             PG8_LDA(At, 0, 1); PG8_STAGE(PG8_SB(0, 0), b2, voffB); PG8_STAGE(PG8_SB(0, 1), b2 + hstepB, voffB); PG8_STAGE(PG8_SA(0, 0), a2, voffA);
;             PG8_WAIT_V(8); PG8_WAIT_L(0); PG8_BAR; PG8_MMA(1, 0, At, B0); PG8_MMA(1, 1, At, B1); PG8_BAR; PG8_SCHED;
;             PG8_LDB(B0, 1, 0); PG8_LDB(B1, 1, 1); PG8_SCHED; PG8_LDA(At, 1, 0); PG8_STAGE(PG8_SA(0, 1), a2 + hstepA, voffA);
;             PG8_WAIT_V(8); PG8_WAIT_L(0); PG8_BAR; PG8_MMA(0, 0, At, B0); PG8_MMA(0, 1, At, B1); PG8_BAR; PG8_SCHED;
;             PG8_LDA(At, 1, 1); PG8_STAGE(PG8_SB(1, 0), b3, voffB); PG8_STAGE(PG8_SB(1, 1), b3 + hstepB, voffB); PG8_STAGE(PG8_SA(1, 0), a3, voffA);
;             PG8_WAIT_V(8); PG8_WAIT_L(0); PG8_BAR;
;             if (last) E.pre(cur, wr, fr, rsv);
;             PG8_MMA(1, 0, At, B0); PG8_MMA(1, 1, At, B1); PG8_BAR; PG8_SCHED;
.LBB0_1053:
	v_mfma_f32_16x16x32_bf16 v[62:65], v[146:149], v[186:189], v[62:65]
	v_mfma_f32_16x16x32_bf16 v[54:57], v[154:157], v[186:189], v[54:57]
	v_mfma_f32_16x16x32_bf16 v[46:49], v[146:149], v[178:181], v[46:49]
	v_mfma_f32_16x16x32_bf16 v[38:41], v[154:157], v[178:181], v[38:41]
	v_mfma_f32_16x16x32_bf16 v[30:33], v[146:149], v[170:173], v[30:33]
	v_mfma_f32_16x16x32_bf16 v[22:25], v[154:157], v[170:173], v[22:25]
	v_mfma_f32_16x16x32_bf16 v[14:17], v[146:149], v[162:165], v[14:17]
	v_mfma_f32_16x16x32_bf16 v[6:9], v[154:157], v[162:165], v[6:9]
	v_mfma_f32_16x16x32_bf16 v[62:65], v[150:153], v[190:193], v[62:65]
	v_mfma_f32_16x16x32_bf16 v[54:57], v[158:161], v[190:193], v[54:57]
	v_mfma_f32_16x16x32_bf16 v[46:49], v[150:153], v[182:185], v[46:49]
	v_mfma_f32_16x16x32_bf16 v[38:41], v[158:161], v[182:185], v[38:41]
	v_mfma_f32_16x16x32_bf16 v[30:33], v[150:153], v[174:177], v[30:33]
	v_mfma_f32_16x16x32_bf16 v[22:25], v[158:161], v[174:177], v[22:25]
	v_mfma_f32_16x16x32_bf16 v[14:17], v[150:153], v[166:169], v[14:17]
	v_mfma_f32_16x16x32_bf16 v[6:9], v[158:161], v[166:169], v[6:9]
	v_mfma_f32_16x16x32_bf16 v[58:61], v[130:133], v[186:189], v[58:61]
	v_mfma_f32_16x16x32_bf16 v[50:53], v[138:141], v[186:189], v[50:53]
	v_mfma_f32_16x16x32_bf16 v[42:45], v[130:133], v[178:181], v[42:45]
	v_mfma_f32_16x16x32_bf16 v[34:37], v[138:141], v[178:181], v[34:37]
	v_mfma_f32_16x16x32_bf16 v[26:29], v[130:133], v[170:173], v[26:29]
	v_mfma_f32_16x16x32_bf16 v[18:21], v[138:141], v[170:173], v[18:21]
	v_mfma_f32_16x16x32_bf16 v[10:13], v[130:133], v[162:165], v[10:13]
	v_mfma_f32_16x16x32_bf16 v[2:5], v[138:141], v[162:165], v[2:5]
	v_mfma_f32_16x16x32_bf16 v[58:61], v[134:137], v[190:193], v[58:61]
	v_mfma_f32_16x16x32_bf16 v[50:53], v[142:145], v[190:193], v[50:53]
	v_mfma_f32_16x16x32_bf16 v[42:45], v[134:137], v[182:185], v[42:45]
	v_mfma_f32_16x16x32_bf16 v[34:37], v[142:145], v[182:185], v[34:37]
	v_mfma_f32_16x16x32_bf16 v[26:29], v[134:137], v[174:177], v[26:29]
	v_mfma_f32_16x16x32_bf16 v[18:21], v[142:145], v[174:177], v[18:21]
	v_mfma_f32_16x16x32_bf16 v[10:13], v[134:137], v[166:169], v[10:13]
	v_mfma_f32_16x16x32_bf16 v[2:5], v[142:145], v[166:169], v[2:5]
	s_barrier
	s_add_i32 s21, s21, 2
	s_add_u32 s22, s22, 0x100
	s_addc_u32 s23, s23, 0
	s_add_u32 s13, s13, 0x100
	s_addc_u32 s15, s15, 0
	s_cmp_gt_u32 s21, 13
	s_cbranch_scc1 .LBB0_1056
.LBB0_1054:
	s_add_u32 s24, s22, 0xfffc0080
	s_addc_u32 s25, s23, -1
	s_cmp_eq_u32 s21, 12
	s_cselect_b32 s29, s17, s25
	s_cselect_b32 s28, s16, s24
	s_cselect_b32 s31, s19, s15
	s_cselect_b32 s30, s18, s13
	s_add_i32 s70, s50, s36
	ds_read_b128 v[130:133], v217
	ds_read_b128 v[134:137], v217 offset:1024
	ds_read_b128 v[138:141], v217 offset:2048
	ds_read_b128 v[142:145], v217 offset:3072
	ds_read_b128 v[146:149], v218
	ds_read_b128 v[150:153], v218 offset:1024
	ds_read_b128 v[154:157], v218 offset:2048
	ds_read_b128 v[158:161], v218 offset:3072
	s_add_i32 m0, s39, 0xc000
	s_add_i32 s69, s39, 0xe000
	s_add_i32 s71, s70, 0x2000
	s_add_u32 s34, s30, 0x40000
	s_addc_u32 s35, s31, 0
	s_add_i32 s72, s51, s36
	s_add_i32 s73, s72, 0x2000
	s_add_i32 s74, 0, 0x18000
	s_add_i32 s75, 0, 0x1c000
	s_add_u32 s26, s28, 0x40000
	s_addc_u32 s27, s29, 0
	s_add_i32 s66, s74, s36
	s_add_i32 s65, s66, 0x2000
	s_add_u32 s24, s30, 0x40080
	s_addc_u32 s25, s31, 0
	s_add_i32 s68, s75, s36
	s_add_i32 s67, s68, 0x2000
	s_cmp_lg_u32 s21, 12
	ds_read_b128 v[162:165], v219
	ds_read_b128 v[166:169], v219 offset:1024
	ds_read_b128 v[170:173], v219 offset:2048
	ds_read_b128 v[174:177], v219 offset:3072
	ds_read_b128 v[178:181], v219 offset:4096
	ds_read_b128 v[182:185], v219 offset:5120
	ds_read_b128 v[186:189], v219 offset:6144
	ds_read_b128 v[190:193], v219 offset:7168
	global_load_lds_dwordx4 v206, s[22:23]
	s_mov_b32 m0, s69
	s_nop 0
	global_load_lds_dwordx4 v208, s[22:23]
	s_waitcnt vmcnt(8)
	s_waitcnt lgkmcnt(0)
	s_barrier
	v_mfma_f32_16x16x32_bf16 v[126:129], v[130:133], v[162:165], v[126:129]
	v_mfma_f32_16x16x32_bf16 v[118:121], v[138:141], v[162:165], v[118:121]
	v_mfma_f32_16x16x32_bf16 v[110:113], v[130:133], v[170:173], v[110:113]
	v_mfma_f32_16x16x32_bf16 v[102:105], v[138:141], v[170:173], v[102:105]
	v_mfma_f32_16x16x32_bf16 v[94:97], v[130:133], v[178:181], v[94:97]
	v_mfma_f32_16x16x32_bf16 v[86:89], v[138:141], v[178:181], v[86:89]
	v_mfma_f32_16x16x32_bf16 v[78:81], v[130:133], v[186:189], v[78:81]
	v_mfma_f32_16x16x32_bf16 v[70:73], v[138:141], v[186:189], v[70:73]
	v_mfma_f32_16x16x32_bf16 v[126:129], v[134:137], v[166:169], v[126:129]
	v_mfma_f32_16x16x32_bf16 v[118:121], v[142:145], v[166:169], v[118:121]
	v_mfma_f32_16x16x32_bf16 v[110:113], v[134:137], v[174:177], v[110:113]
	v_mfma_f32_16x16x32_bf16 v[102:105], v[142:145], v[174:177], v[102:105]
	v_mfma_f32_16x16x32_bf16 v[94:97], v[134:137], v[182:185], v[94:97]
	v_mfma_f32_16x16x32_bf16 v[86:89], v[142:145], v[182:185], v[86:89]
	v_mfma_f32_16x16x32_bf16 v[78:81], v[134:137], v[190:193], v[78:81]
	v_mfma_f32_16x16x32_bf16 v[70:73], v[142:145], v[190:193], v[70:73]
	v_mfma_f32_16x16x32_bf16 v[122:125], v[146:149], v[162:165], v[122:125]
	v_mfma_f32_16x16x32_bf16 v[114:117], v[154:157], v[162:165], v[114:117]
	v_mfma_f32_16x16x32_bf16 v[106:109], v[146:149], v[170:173], v[106:109]
	v_mfma_f32_16x16x32_bf16 v[98:101], v[154:157], v[170:173], v[98:101]
	v_mfma_f32_16x16x32_bf16 v[90:93], v[146:149], v[178:181], v[90:93]
	v_mfma_f32_16x16x32_bf16 v[82:85], v[154:157], v[178:181], v[82:85]
	v_mfma_f32_16x16x32_bf16 v[74:77], v[146:149], v[186:189], v[74:77]
	v_mfma_f32_16x16x32_bf16 v[66:69], v[154:157], v[186:189], v[66:69]
	v_mfma_f32_16x16x32_bf16 v[122:125], v[150:153], v[166:169], v[122:125]
	v_mfma_f32_16x16x32_bf16 v[114:117], v[158:161], v[166:169], v[114:117]
	v_mfma_f32_16x16x32_bf16 v[106:109], v[150:153], v[174:177], v[106:109]
	v_mfma_f32_16x16x32_bf16 v[98:101], v[158:161], v[174:177], v[98:101]
	v_mfma_f32_16x16x32_bf16 v[90:93], v[150:153], v[182:185], v[90:93]
	v_mfma_f32_16x16x32_bf16 v[82:85], v[158:161], v[182:185], v[82:85]
	v_mfma_f32_16x16x32_bf16 v[74:77], v[150:153], v[190:193], v[74:77]
	v_mfma_f32_16x16x32_bf16 v[66:69], v[158:161], v[190:193], v[66:69]
	s_barrier
; #define PG8_STAGE(bufoff, gbase, voff) do { _Pragma("unroll") for (int _i = 0; _i < 2; ++_i) \
;         __builtin_amdgcn_global_load_lds((const unsigned*)((const char*)(gbase) + (voff)[_i]), (LAS unsigned*)(lds + (bufoff) + ldsw + _i * 8192), 16, 0, 0); } while (0)
; #define PG8_LDA(dst, b, h) do { _Pragma("unroll") for (int m = 0; m < 4; ++m) _Pragma("unroll") for (int k = 0; k < 2; ++k) dst[m][k] = *(const LAS bf16x8*)(lds + PG8_SA(b, h) + aoff + m * 2048 + k * 1024); } while (0)
; #define PG8_MMA(ai, bj, At, Bt) do { __builtin_amdgcn_s_setprio(1); _Pragma("unroll") for (int m = 0; m < 4; ++m) _Pragma("unroll") for (int n = 0; n < 2; ++n) _Pragma("unroll") for (int k = 0; k < 2; ++k) \
;         acc[ai][bj][m][n] = __builtin_amdgcn_mfma_f32_16x16x32_bf16(Bt[n][k], At[m][k], acc[ai][bj][m][n], 0, 0, 0); __builtin_amdgcn_s_setprio(0); } while (0)
; #define PG8_WAIT_V(n) asm volatile("s_waitcnt vmcnt(" #n ")" ::: "memory")
; #define PG8_WAIT_L(n) asm volatile("s_waitcnt lgkmcnt(" #n ")" ::: "memory")
; #define PG8_BAR __builtin_amdgcn_s_barrier()
; #define PG8_SCHED __builtin_amdgcn_sched_barrier(0)
; template <class Epi, class Sched>
; __device__ __forceinline__ void gemm_phase(LAS unsigned char* lds, const int lda, const int ldb, const int K, const Sched& S, const Epi& E) {
;     ...
;             PG8_LDA(At, 0, 1); PG8_STAGE(PG8_SB(0, 0), b2, voffB); PG8_STAGE(PG8_SB(0, 1), b2 + hstepB, voffB); PG8_STAGE(PG8_SA(0, 0), a2, voffA);
;             PG8_WAIT_V(8); PG8_WAIT_L(0); PG8_BAR; PG8_MMA(1, 0, At, B0); PG8_MMA(1, 1, At, B1); PG8_BAR; PG8_SCHED;
	s_mov_b32 m0, s70
	ds_read_b128 v[162:165], v219 offset:16384
	ds_read_b128 v[166:169], v219 offset:17408
	ds_read_b128 v[170:173], v219 offset:18432
	ds_read_b128 v[174:177], v219 offset:19456
	ds_read_b128 v[178:181], v219 offset:20480
	ds_read_b128 v[182:185], v219 offset:21504
	ds_read_b128 v[186:189], v219 offset:22528
	ds_read_b128 v[190:193], v219 offset:23552
	global_load_lds_dwordx4 v200, s[30:31]
	s_mov_b32 m0, s71
	s_nop 0
	global_load_lds_dwordx4 v196, s[30:31]
	s_mov_b32 m0, s72
	s_nop 0
	global_load_lds_dwordx4 v200, s[34:35]
	s_mov_b32 m0, s73
	s_nop 0
	global_load_lds_dwordx4 v196, s[34:35]
	s_mov_b32 m0, s39
	s_nop 0
	global_load_lds_dwordx4 v202, s[28:29]
	s_mov_b32 m0, s40
	s_nop 0
	global_load_lds_dwordx4 v198, s[28:29]
	s_waitcnt vmcnt(8)
	s_waitcnt lgkmcnt(0)
	s_barrier
	v_mfma_f32_16x16x32_bf16 v[62:65], v[130:133], v[162:165], v[62:65]
	v_mfma_f32_16x16x32_bf16 v[54:57], v[138:141], v[162:165], v[54:57]
	v_mfma_f32_16x16x32_bf16 v[46:49], v[130:133], v[170:173], v[46:49]
	v_mfma_f32_16x16x32_bf16 v[38:41], v[138:141], v[170:173], v[38:41]
	v_mfma_f32_16x16x32_bf16 v[30:33], v[130:133], v[178:181], v[30:33]
	v_mfma_f32_16x16x32_bf16 v[22:25], v[138:141], v[178:181], v[22:25]
	v_mfma_f32_16x16x32_bf16 v[14:17], v[130:133], v[186:189], v[14:17]
	v_mfma_f32_16x16x32_bf16 v[6:9], v[138:141], v[186:189], v[6:9]
	v_mfma_f32_16x16x32_bf16 v[62:65], v[134:137], v[166:169], v[62:65]
	v_mfma_f32_16x16x32_bf16 v[54:57], v[142:145], v[166:169], v[54:57]
	v_mfma_f32_16x16x32_bf16 v[46:49], v[134:137], v[174:177], v[46:49]
	v_mfma_f32_16x16x32_bf16 v[38:41], v[142:145], v[174:177], v[38:41]
	v_mfma_f32_16x16x32_bf16 v[30:33], v[134:137], v[182:185], v[30:33]
	v_mfma_f32_16x16x32_bf16 v[22:25], v[142:145], v[182:185], v[22:25]
	v_mfma_f32_16x16x32_bf16 v[14:17], v[134:137], v[190:193], v[14:17]
	v_mfma_f32_16x16x32_bf16 v[6:9], v[142:145], v[190:193], v[6:9]
	v_mfma_f32_16x16x32_bf16 v[58:61], v[146:149], v[162:165], v[58:61]
	v_mfma_f32_16x16x32_bf16 v[50:53], v[154:157], v[162:165], v[50:53]
	v_mfma_f32_16x16x32_bf16 v[42:45], v[146:149], v[170:173], v[42:45]
	v_mfma_f32_16x16x32_bf16 v[34:37], v[154:157], v[170:173], v[34:37]
	v_mfma_f32_16x16x32_bf16 v[26:29], v[146:149], v[178:181], v[26:29]
	v_mfma_f32_16x16x32_bf16 v[18:21], v[154:157], v[178:181], v[18:21]
	v_mfma_f32_16x16x32_bf16 v[10:13], v[146:149], v[186:189], v[10:13]
	v_mfma_f32_16x16x32_bf16 v[2:5], v[154:157], v[186:189], v[2:5]
	v_mfma_f32_16x16x32_bf16 v[58:61], v[150:153], v[166:169], v[58:61]
	v_mfma_f32_16x16x32_bf16 v[50:53], v[158:161], v[166:169], v[50:53]
	v_mfma_f32_16x16x32_bf16 v[42:45], v[150:153], v[174:177], v[42:45]
	v_mfma_f32_16x16x32_bf16 v[34:37], v[158:161], v[174:177], v[34:37]
	v_mfma_f32_16x16x32_bf16 v[26:29], v[150:153], v[182:185], v[26:29]
	v_mfma_f32_16x16x32_bf16 v[18:21], v[158:161], v[182:185], v[18:21]
	v_mfma_f32_16x16x32_bf16 v[10:13], v[150:153], v[190:193], v[10:13]
	v_mfma_f32_16x16x32_bf16 v[2:5], v[158:161], v[190:193], v[2:5]
	s_barrier
; #define PG8_STAGE(bufoff, gbase, voff) do { _Pragma("unroll") for (int _i = 0; _i < 2; ++_i) \
;         __builtin_amdgcn_global_load_lds((const unsigned*)((const char*)(gbase) + (voff)[_i]), (LAS unsigned*)(lds + (bufoff) + ldsw + _i * 8192), 16, 0, 0); } while (0)
; #define PG8_LDA(dst, b, h) do { _Pragma("unroll") for (int m = 0; m < 4; ++m) _Pragma("unroll") for (int k = 0; k < 2; ++k) dst[m][k] = *(const LAS bf16x8*)(lds + PG8_SA(b, h) + aoff + m * 2048 + k * 1024); } while (0)
; #define PG8_LDB(dst, b, h) do { _Pragma("unroll") for (int n = 0; n < 2; ++n) _Pragma("unroll") for (int k = 0; k < 2; ++k) dst[n][k] = *(const LAS bf16x8*)(lds + PG8_SB(b, h) + boff + n * 2048 + k * 1024); } while (0)
; #define PG8_MMA(ai, bj, At, Bt) do { __builtin_amdgcn_s_setprio(1); _Pragma("unroll") for (int m = 0; m < 4; ++m) _Pragma("unroll") for (int n = 0; n < 2; ++n) _Pragma("unroll") for (int k = 0; k < 2; ++k) \
;         acc[ai][bj][m][n] = __builtin_amdgcn_mfma_f32_16x16x32_bf16(Bt[n][k], At[m][k], acc[ai][bj][m][n], 0, 0, 0); __builtin_amdgcn_s_setprio(0); } while (0)
; #define PG8_WAIT_V(n) asm volatile("s_waitcnt vmcnt(" #n ")" ::: "memory")
; #define PG8_WAIT_L(n) asm volatile("s_waitcnt lgkmcnt(" #n ")" ::: "memory")
; #define PG8_BAR __builtin_amdgcn_s_barrier()
; #define PG8_SCHED __builtin_amdgcn_sched_barrier(0)
; template <class Epi, class Sched>
; __device__ __forceinline__ void gemm_phase(LAS unsigned char* lds, const int lda, const int ldb, const int K, const Sched& S, const Epi& E) {
;     ...
;             PG8_LDB(B0, 1, 0); PG8_LDB(B1, 1, 1); PG8_SCHED; PG8_LDA(At, 1, 0); PG8_STAGE(PG8_SA(0, 1), a2 + hstepA, voffA);
;             PG8_WAIT_V(8); PG8_WAIT_L(0); PG8_BAR; PG8_MMA(0, 0, At, B0); PG8_MMA(0, 1, At, B1); PG8_BAR; PG8_SCHED;
;             PG8_LDA(At, 1, 1); PG8_STAGE(PG8_SB(1, 0), b3, voffB); PG8_STAGE(PG8_SB(1, 1), b3 + hstepB, voffB); PG8_STAGE(PG8_SA(1, 0), a3, voffA);
;             PG8_WAIT_V(8); PG8_WAIT_L(0); PG8_BAR;
;             if (last) E.pre(cur, wr, fr, rsv);
;     __device__ __forceinline__ void pre(const pg8::Unit& u, int wr, int fr, float (&rsv)[8]) const {
;         const float* p = ss + u.pm * 256 + wr * 64 + fr;
; #pragma unroll
;         for (int ai = 0; ai < 2; ++ai)
; #pragma unroll
;             for (int m = 0; m < 4; ++m) rsv[ai * 4 + m] = p[ai * 128 + m * 16];
;     }
.Lpeel6_join:
	v_add_u32_e32 v130, s74, v195
	v_add_u32_e32 v142, s75, v195
	ds_read_b128 v[146:149], v130
	ds_read_b128 v[150:153], v130 offset:1024
	ds_read_b128 v[154:157], v130 offset:2048
	ds_read_b128 v[158:161], v130 offset:3072
	ds_read_b128 v[130:133], v142
	ds_read_b128 v[134:137], v142 offset:1024
	ds_read_b128 v[138:141], v142 offset:2048
	ds_read_b128 v[142:145], v142 offset:3072
	s_mov_b32 m0, s41
	ds_read_b128 v[162:165], v219 offset:32768
	ds_read_b128 v[166:169], v219 offset:33792
	ds_read_b128 v[170:173], v219 offset:34816
	ds_read_b128 v[174:177], v219 offset:35840
	ds_read_b128 v[178:181], v219 offset:36864
	ds_read_b128 v[182:185], v219 offset:37888
	ds_read_b128 v[186:189], v219 offset:38912
	ds_read_b128 v[190:193], v219 offset:39936
	global_load_lds_dwordx4 v202, s[26:27]
	s_mov_b32 m0, s42
	s_nop 0
	global_load_lds_dwordx4 v198, s[26:27]
	s_waitcnt vmcnt(8)
	s_waitcnt lgkmcnt(0)
	s_barrier
	v_mfma_f32_16x16x32_bf16 v[126:129], v[146:149], v[162:165], v[126:129]
	v_mfma_f32_16x16x32_bf16 v[118:121], v[154:157], v[162:165], v[118:121]
	v_mfma_f32_16x16x32_bf16 v[110:113], v[146:149], v[170:173], v[110:113]
	v_mfma_f32_16x16x32_bf16 v[102:105], v[154:157], v[170:173], v[102:105]
	v_mfma_f32_16x16x32_bf16 v[94:97], v[146:149], v[178:181], v[94:97]
	v_mfma_f32_16x16x32_bf16 v[86:89], v[154:157], v[178:181], v[86:89]
	v_mfma_f32_16x16x32_bf16 v[78:81], v[146:149], v[186:189], v[78:81]
	v_mfma_f32_16x16x32_bf16 v[70:73], v[154:157], v[186:189], v[70:73]
	v_mfma_f32_16x16x32_bf16 v[126:129], v[150:153], v[166:169], v[126:129]
	v_mfma_f32_16x16x32_bf16 v[118:121], v[158:161], v[166:169], v[118:121]
	v_mfma_f32_16x16x32_bf16 v[110:113], v[150:153], v[174:177], v[110:113]
	v_mfma_f32_16x16x32_bf16 v[102:105], v[158:161], v[174:177], v[102:105]
	v_mfma_f32_16x16x32_bf16 v[94:97], v[150:153], v[182:185], v[94:97]
	v_mfma_f32_16x16x32_bf16 v[86:89], v[158:161], v[182:185], v[86:89]
	v_mfma_f32_16x16x32_bf16 v[78:81], v[150:153], v[190:193], v[78:81]
	v_mfma_f32_16x16x32_bf16 v[70:73], v[158:161], v[190:193], v[70:73]
	v_mfma_f32_16x16x32_bf16 v[122:125], v[130:133], v[162:165], v[122:125]
	v_mfma_f32_16x16x32_bf16 v[114:117], v[138:141], v[162:165], v[114:117]
	v_mfma_f32_16x16x32_bf16 v[106:109], v[130:133], v[170:173], v[106:109]
	v_mfma_f32_16x16x32_bf16 v[98:101], v[138:141], v[170:173], v[98:101]
	v_mfma_f32_16x16x32_bf16 v[90:93], v[130:133], v[178:181], v[90:93]
	v_mfma_f32_16x16x32_bf16 v[82:85], v[138:141], v[178:181], v[82:85]
	v_mfma_f32_16x16x32_bf16 v[74:77], v[130:133], v[186:189], v[74:77]
	v_mfma_f32_16x16x32_bf16 v[66:69], v[138:141], v[186:189], v[66:69]
	v_mfma_f32_16x16x32_bf16 v[122:125], v[134:137], v[166:169], v[122:125]
	v_mfma_f32_16x16x32_bf16 v[114:117], v[142:145], v[166:169], v[114:117]
	v_mfma_f32_16x16x32_bf16 v[106:109], v[134:137], v[174:177], v[106:109]
	v_mfma_f32_16x16x32_bf16 v[98:101], v[142:145], v[174:177], v[98:101]
	v_mfma_f32_16x16x32_bf16 v[90:93], v[134:137], v[182:185], v[90:93]
	v_mfma_f32_16x16x32_bf16 v[82:85], v[142:145], v[182:185], v[82:85]
	v_mfma_f32_16x16x32_bf16 v[74:77], v[134:137], v[190:193], v[74:77]
	v_mfma_f32_16x16x32_bf16 v[66:69], v[142:145], v[190:193], v[66:69]
	s_barrier
	s_mov_b32 m0, s66
	ds_read_b128 v[186:189], v219 offset:49152
	ds_read_b128 v[190:193], v219 offset:50176
	ds_read_b128 v[178:181], v219 offset:51200
	ds_read_b128 v[182:185], v219 offset:52224
	ds_read_b128 v[170:173], v219 offset:53248
	ds_read_b128 v[174:177], v219 offset:54272
	ds_read_b128 v[162:165], v219 offset:55296
	ds_read_b128 v[166:169], v219 offset:56320
	global_load_lds_dwordx4 v230, s[30:31]
	s_mov_b32 m0, s65
	s_nop 0
	global_load_lds_dwordx4 v231, s[30:31]
	s_mov_b32 m0, s68
	s_nop 0
	global_load_lds_dwordx4 v200, s[24:25]
	s_mov_b32 m0, s67
	s_nop 0
	global_load_lds_dwordx4 v196, s[24:25]
	s_mov_b32 m0, s44
	s_nop 0
	global_load_lds_dwordx4 v232, s[28:29]
	s_mov_b32 m0, s45
	s_nop 0
	global_load_lds_dwordx4 v233, s[28:29]
	s_waitcnt vmcnt(8)
	s_waitcnt lgkmcnt(0)
	s_barrier
	s_cbranch_scc1 .LBB0_1053
	global_load_dword v228, v[214:215], off
	global_load_dword v227, v[214:215], off offset:64
	global_load_dword v226, v[214:215], off offset:128
	global_load_dword v225, v[214:215], off offset:192
	global_load_dword v224, v[214:215], off offset:512
	global_load_dword v223, v[214:215], off offset:576
	global_load_dword v222, v[214:215], off offset:640
	global_load_dword v221, v[214:215], off offset:704
	s_branch .LBB0_1053

; #define PG8_STAGE(bufoff, gbase, voff) do { _Pragma("unroll") for (int _i = 0; _i < 2; ++_i) \
;         __builtin_amdgcn_global_load_lds((const unsigned*)((const char*)(gbase) + (voff)[_i]), (LAS unsigned*)(lds + (bufoff) + ldsw + _i * 8192), 16, 0, 0); } while (0)
; #define PG8_LDA(dst, b, h) do { _Pragma("unroll") for (int m = 0; m < 4; ++m) _Pragma("unroll") for (int k = 0; k < 2; ++k) dst[m][k] = *(const LAS bf16x8*)(lds + PG8_SA(b, h) + aoff + m * 2048 + k * 1024); } while (0)
; #define PG8_LDB(dst, b, h) do { _Pragma("unroll") for (int n = 0; n < 2; ++n) _Pragma("unroll") for (int k = 0; k < 2; ++k) dst[n][k] = *(const LAS bf16x8*)(lds + PG8_SB(b, h) + boff + n * 2048 + k * 1024); } while (0)
; #define PG8_MMA(ai, bj, At, Bt) do { __builtin_amdgcn_s_setprio(1); _Pragma("unroll") for (int m = 0; m < 4; ++m) _Pragma("unroll") for (int n = 0; n < 2; ++n) _Pragma("unroll") for (int k = 0; k < 2; ++k) \
;         acc[ai][bj][m][n] = __builtin_amdgcn_mfma_f32_16x16x32_bf16(Bt[n][k], At[m][k], acc[ai][bj][m][n], 0, 0, 0); __builtin_amdgcn_s_setprio(0); } while (0)
; #define PG8_WAIT_V(n) asm volatile("s_waitcnt vmcnt(" #n ")" ::: "memory")
; #define PG8_WAIT_L(n) asm volatile("s_waitcnt lgkmcnt(" #n ")" ::: "memory")
; #define PG8_BAR __builtin_amdgcn_s_barrier()
; #define PG8_SCHED __builtin_amdgcn_sched_barrier(0)
; template <class Epi, class Sched>
; __device__ __forceinline__ void gemm_phase(LAS unsigned char* lds, const int lda, const int ldb, const int K, const Sched& S, const Epi& E) {
;     ...
;         for (int t = 0; t < nt; t += 2) {
;             const bool last = (t == nt - 2);
;             const char* a1 = cA + (size_t)(t + 1) * kstep;
;             const char* a2 = last ? nA : cA + (size_t)(t + 2) * kstep; const char* b2 = last ? nB : cB + (size_t)(t + 2) * kstep;
;             const char* a3 = a2 + kstep; const char* b3 = b2 + kstep;
;             PG8_LDB(B0, 0, 0); PG8_LDB(B1, 0, 1); PG8_SCHED; PG8_LDA(At, 0, 0); PG8_STAGE(PG8_SA(1, 1), a1 + hstepA, voffA);
;             PG8_WAIT_V(8); PG8_WAIT_L(0); PG8_BAR; PG8_MMA(0, 0, At, B0); PG8_MMA(0, 1, At, B1); PG8_BAR; PG8_SCHED;
;             PG8_LDA(At, 0, 1); PG8_STAGE(PG8_SB(0, 0), b2, voffB); PG8_STAGE(PG8_SB(0, 1), b2 + hstepB, voffB); PG8_STAGE(PG8_SA(0, 0), a2, voffA);
;             PG8_WAIT_V(8); PG8_WAIT_L(0); PG8_BAR; PG8_MMA(1, 0, At, B0); PG8_MMA(1, 1, At, B1); PG8_BAR; PG8_SCHED;
.LBB0_1135:
	s_add_u32 s14, s14, 0xb0080
	s_addc_u32 s15, s15, 0
	s_add_u32 s39, s16, 0x100
	s_addc_u32 s40, s17, 0
	s_mov_b32 s41, -2
	v_add_u32_e32 v214, 0x80, v132
	v_add_u32_e32 v215, 0x80, v128
	v_add_u32_e32 v216, 0x80, v134
	v_add_u32_e32 v217, 0x80, v130
	ds_read_b128 v[144:147], v151
	ds_read_b128 v[154:157], v151 offset:1024
	ds_read_b128 v[158:161], v151 offset:2048
	ds_read_b128 v[162:165], v151 offset:3072
	ds_read_b128 v[166:169], v152
	ds_read_b128 v[170:173], v152 offset:1024
	ds_read_b128 v[174:177], v152 offset:2048
	ds_read_b128 v[178:181], v152 offset:3072
	s_add_u32 s16, s14, 0xfff50080
	s_addc_u32 s17, s15, -1
	s_cmp_eq_u32 s41, 40
	s_cselect_b32 s19, s11, s17
	s_cselect_b32 s18, s10, s16
	s_cselect_b32 s17, s13, s40
	s_cselect_b32 s16, s12, s39
	s_add_i32 m0, s24, 0xc000
	ds_read_b128 v[182:185], v153
	ds_read_b128 v[186:189], v153 offset:1024
	ds_read_b128 v[190:193], v153 offset:2048
	ds_read_b128 v[194:197], v153 offset:3072
	ds_read_b128 v[198:201], v153 offset:4096
	ds_read_b128 v[202:205], v153 offset:5120
	ds_read_b128 v[206:209], v153 offset:6144
	ds_read_b128 v[210:213], v153 offset:7168
	global_load_lds_dwordx4 v136, s[14:15]
	s_add_i32 m0, s24, 0xe000
	s_nop 0
	global_load_lds_dwordx4 v138, s[14:15]
	s_waitcnt vmcnt(8)
	s_waitcnt lgkmcnt(0)
	s_barrier
	v_mfma_f32_16x16x32_bf16 v[124:127], v[144:147], v[182:185], 0
	v_mfma_f32_16x16x32_bf16 v[120:123], v[158:161], v[182:185], 0
	v_mfma_f32_16x16x32_bf16 v[112:115], v[144:147], v[190:193], 0
	v_mfma_f32_16x16x32_bf16 v[104:107], v[158:161], v[190:193], 0
	v_mfma_f32_16x16x32_bf16 v[96:99], v[144:147], v[198:201], 0
	v_mfma_f32_16x16x32_bf16 v[88:91], v[158:161], v[198:201], 0
	v_mfma_f32_16x16x32_bf16 v[80:83], v[144:147], v[206:209], 0
	v_mfma_f32_16x16x32_bf16 v[72:75], v[158:161], v[206:209], 0
	v_mfma_f32_16x16x32_bf16 v[124:127], v[154:157], v[186:189], v[124:127]
	v_mfma_f32_16x16x32_bf16 v[120:123], v[162:165], v[186:189], v[120:123]
	v_mfma_f32_16x16x32_bf16 v[112:115], v[154:157], v[194:197], v[112:115]
	v_mfma_f32_16x16x32_bf16 v[104:107], v[162:165], v[194:197], v[104:107]
	v_mfma_f32_16x16x32_bf16 v[96:99], v[154:157], v[202:205], v[96:99]
	v_mfma_f32_16x16x32_bf16 v[88:91], v[162:165], v[202:205], v[88:91]
	v_mfma_f32_16x16x32_bf16 v[80:83], v[154:157], v[210:213], v[80:83]
	v_mfma_f32_16x16x32_bf16 v[72:75], v[162:165], v[210:213], v[72:75]
	v_mfma_f32_16x16x32_bf16 v[116:119], v[166:169], v[182:185], 0
	v_mfma_f32_16x16x32_bf16 v[108:111], v[174:177], v[182:185], 0
	v_mfma_f32_16x16x32_bf16 v[100:103], v[166:169], v[190:193], 0
	v_mfma_f32_16x16x32_bf16 v[92:95], v[174:177], v[190:193], 0
	v_mfma_f32_16x16x32_bf16 v[84:87], v[166:169], v[198:201], 0
	v_mfma_f32_16x16x32_bf16 v[76:79], v[174:177], v[198:201], 0
	v_mfma_f32_16x16x32_bf16 v[68:71], v[166:169], v[206:209], 0
	v_mfma_f32_16x16x32_bf16 v[64:67], v[174:177], v[206:209], 0
	v_mfma_f32_16x16x32_bf16 v[116:119], v[170:173], v[186:189], v[116:119]
	v_mfma_f32_16x16x32_bf16 v[108:111], v[178:181], v[186:189], v[108:111]
	v_mfma_f32_16x16x32_bf16 v[100:103], v[170:173], v[194:197], v[100:103]
	v_mfma_f32_16x16x32_bf16 v[92:95], v[178:181], v[194:197], v[92:95]
	v_mfma_f32_16x16x32_bf16 v[84:87], v[170:173], v[202:205], v[84:87]
	v_mfma_f32_16x16x32_bf16 v[76:79], v[178:181], v[202:205], v[76:79]
	v_mfma_f32_16x16x32_bf16 v[68:71], v[170:173], v[210:213], v[68:71]
	v_mfma_f32_16x16x32_bf16 v[64:67], v[178:181], v[210:213], v[64:67]
	s_barrier
	s_add_i32 s42, s33, s21
	s_mov_b32 m0, s42
	ds_read_b128 v[182:185], v153 offset:16384
	ds_read_b128 v[186:189], v153 offset:17408
	ds_read_b128 v[190:193], v153 offset:18432
	ds_read_b128 v[194:197], v153 offset:19456
	ds_read_b128 v[198:201], v153 offset:20480
	ds_read_b128 v[202:205], v153 offset:21504
	ds_read_b128 v[206:209], v153 offset:22528
	ds_read_b128 v[210:213], v153 offset:23552
	global_load_lds_dwordx4 v132, s[16:17]
	s_add_i32 m0, s42, 0x2000
	s_add_u32 s42, s16, 0xb0000
	s_mov_b64 s[98:99], s[16:17]
	s_addc_u32 s43, s17, 0
	s_add_i32 s44, s34, s21
	global_load_lds_dwordx4 v128, s[16:17]
	s_mov_b32 m0, s44
	s_mov_b64 s[100:101], s[18:19]
	global_load_lds_dwordx4 v132, s[42:43]
	s_add_i32 m0, s44, 0x2000
	s_nop 0
	global_load_lds_dwordx4 v128, s[42:43]
	s_mov_b32 m0, s24
	s_nop 0
	global_load_lds_dwordx4 v134, s[18:19]
	s_mov_b32 m0, s25
	s_nop 0
	global_load_lds_dwordx4 v130, s[18:19]
	s_waitcnt vmcnt(8)
	s_waitcnt lgkmcnt(0)
	s_barrier
	v_mfma_f32_16x16x32_bf16 v[60:63], v[144:147], v[182:185], 0
	v_mfma_f32_16x16x32_bf16 v[56:59], v[158:161], v[182:185], 0
	v_mfma_f32_16x16x32_bf16 v[48:51], v[144:147], v[190:193], 0
	v_mfma_f32_16x16x32_bf16 v[40:43], v[158:161], v[190:193], 0
	v_mfma_f32_16x16x32_bf16 v[32:35], v[144:147], v[198:201], 0
	v_mfma_f32_16x16x32_bf16 v[24:27], v[158:161], v[198:201], 0
	v_mfma_f32_16x16x32_bf16 v[16:19], v[144:147], v[206:209], 0
	v_mfma_f32_16x16x32_bf16 v[8:11], v[158:161], v[206:209], 0
	v_mfma_f32_16x16x32_bf16 v[60:63], v[154:157], v[186:189], v[60:63]
	v_mfma_f32_16x16x32_bf16 v[56:59], v[162:165], v[186:189], v[56:59]
	v_mfma_f32_16x16x32_bf16 v[48:51], v[154:157], v[194:197], v[48:51]
	v_mfma_f32_16x16x32_bf16 v[40:43], v[162:165], v[194:197], v[40:43]
	v_mfma_f32_16x16x32_bf16 v[32:35], v[154:157], v[202:205], v[32:35]
	v_mfma_f32_16x16x32_bf16 v[24:27], v[162:165], v[202:205], v[24:27]
	v_mfma_f32_16x16x32_bf16 v[16:19], v[154:157], v[210:213], v[16:19]
	v_mfma_f32_16x16x32_bf16 v[8:11], v[162:165], v[210:213], v[8:11]
	v_mfma_f32_16x16x32_bf16 v[52:55], v[166:169], v[182:185], 0
	v_mfma_f32_16x16x32_bf16 v[44:47], v[174:177], v[182:185], 0
	v_mfma_f32_16x16x32_bf16 v[36:39], v[166:169], v[190:193], 0
	v_mfma_f32_16x16x32_bf16 v[28:31], v[174:177], v[190:193], 0
	v_mfma_f32_16x16x32_bf16 v[20:23], v[166:169], v[198:201], 0
	v_mfma_f32_16x16x32_bf16 v[12:15], v[174:177], v[198:201], 0
	v_mfma_f32_16x16x32_bf16 v[4:7], v[166:169], v[206:209], 0
	v_mfma_f32_16x16x32_bf16 v[0:3], v[174:177], v[206:209], 0
	v_mfma_f32_16x16x32_bf16 v[52:55], v[170:173], v[186:189], v[52:55]
	v_mfma_f32_16x16x32_bf16 v[44:47], v[178:181], v[186:189], v[44:47]
	v_mfma_f32_16x16x32_bf16 v[36:39], v[170:173], v[194:197], v[36:39]
	v_mfma_f32_16x16x32_bf16 v[28:31], v[178:181], v[194:197], v[28:31]
	v_mfma_f32_16x16x32_bf16 v[20:23], v[170:173], v[202:205], v[20:23]
	v_mfma_f32_16x16x32_bf16 v[12:15], v[178:181], v[202:205], v[12:15]
	v_mfma_f32_16x16x32_bf16 v[4:7], v[170:173], v[210:213], v[4:7]
	v_mfma_f32_16x16x32_bf16 v[0:3], v[178:181], v[210:213], v[0:3]
	s_barrier
	s_branch .Lpeel7_join
; #define PG8_STAGE(bufoff, gbase, voff) do { _Pragma("unroll") for (int _i = 0; _i < 2; ++_i) \
;         __builtin_amdgcn_global_load_lds((const unsigned*)((const char*)(gbase) + (voff)[_i]), (LAS unsigned*)(lds + (bufoff) + ldsw + _i * 8192), 16, 0, 0); } while (0)
; #define PG8_LDA(dst, b, h) do { _Pragma("unroll") for (int m = 0; m < 4; ++m) _Pragma("unroll") for (int k = 0; k < 2; ++k) dst[m][k] = *(const LAS bf16x8*)(lds + PG8_SA(b, h) + aoff + m * 2048 + k * 1024); } while (0)
; #define PG8_LDB(dst, b, h) do { _Pragma("unroll") for (int n = 0; n < 2; ++n) _Pragma("unroll") for (int k = 0; k < 2; ++k) dst[n][k] = *(const LAS bf16x8*)(lds + PG8_SB(b, h) + boff + n * 2048 + k * 1024); } while (0)
; #define PG8_MMA(ai, bj, At, Bt) do { __builtin_amdgcn_s_setprio(1); _Pragma("unroll") for (int m = 0; m < 4; ++m) _Pragma("unroll") for (int n = 0; n < 2; ++n) _Pragma("unroll") for (int k = 0; k < 2; ++k) \
;         acc[ai][bj][m][n] = __builtin_amdgcn_mfma_f32_16x16x32_bf16(Bt[n][k], At[m][k], acc[ai][bj][m][n], 0, 0, 0); __builtin_amdgcn_s_setprio(0); } while (0)
; #define PG8_WAIT_V(n) asm volatile("s_waitcnt vmcnt(" #n ")" ::: "memory")
; #define PG8_WAIT_L(n) asm volatile("s_waitcnt lgkmcnt(" #n ")" ::: "memory")
; #define PG8_BAR __builtin_amdgcn_s_barrier()
; #define PG8_SCHED __builtin_amdgcn_sched_barrier(0)
; template <class Epi, class Sched>
; __device__ __forceinline__ void gemm_phase(LAS unsigned char* lds, const int lda, const int ldb, const int K, const Sched& S, const Epi& E) {
;     ...
;             PG8_LDB(B0, 0, 0); PG8_LDB(B1, 0, 1); PG8_SCHED; PG8_LDA(At, 0, 0); PG8_STAGE(PG8_SA(1, 1), a1 + hstepA, voffA);
;             PG8_WAIT_V(8); PG8_WAIT_L(0); PG8_BAR; PG8_MMA(0, 0, At, B0); PG8_MMA(0, 1, At, B1); PG8_BAR; PG8_SCHED;
;             PG8_LDA(At, 0, 1); PG8_STAGE(PG8_SB(0, 0), b2, voffB); PG8_STAGE(PG8_SB(0, 1), b2 + hstepB, voffB); PG8_STAGE(PG8_SA(0, 0), a2, voffA);
;             PG8_WAIT_V(8); PG8_WAIT_L(0); PG8_BAR; PG8_MMA(1, 0, At, B0); PG8_MMA(1, 1, At, B1); PG8_BAR; PG8_SCHED;
.LBB0_1136:
	ds_read_b128 v[144:147], v151
	ds_read_b128 v[154:157], v151 offset:1024
	ds_read_b128 v[158:161], v151 offset:2048
	ds_read_b128 v[162:165], v151 offset:3072
	ds_read_b128 v[166:169], v152
	ds_read_b128 v[170:173], v152 offset:1024
	ds_read_b128 v[174:177], v152 offset:2048
	ds_read_b128 v[178:181], v152 offset:3072
	s_add_u32 s16, s14, 0xfff50080
	s_addc_u32 s17, s15, -1
	s_cmp_eq_u32 s41, 40
	s_cselect_b32 s19, s11, s17
	s_cselect_b32 s18, s10, s16
	s_cselect_b32 s17, s13, s40
	s_cselect_b32 s16, s12, s39
	s_add_i32 m0, s24, 0xc000
	ds_read_b128 v[182:185], v153
	ds_read_b128 v[186:189], v153 offset:1024
	ds_read_b128 v[190:193], v153 offset:2048
	ds_read_b128 v[194:197], v153 offset:3072
	ds_read_b128 v[198:201], v153 offset:4096
	ds_read_b128 v[202:205], v153 offset:5120
	ds_read_b128 v[206:209], v153 offset:6144
	ds_read_b128 v[210:213], v153 offset:7168
	global_load_lds_dwordx4 v136, s[14:15]
	s_add_i32 m0, s24, 0xe000
	s_nop 0
	global_load_lds_dwordx4 v138, s[14:15]
	s_waitcnt vmcnt(8)
	s_waitcnt lgkmcnt(0)
	s_barrier
	v_mfma_f32_16x16x32_bf16 v[124:127], v[144:147], v[182:185], v[124:127]
	v_mfma_f32_16x16x32_bf16 v[120:123], v[158:161], v[182:185], v[120:123]
	v_mfma_f32_16x16x32_bf16 v[112:115], v[144:147], v[190:193], v[112:115]
	v_mfma_f32_16x16x32_bf16 v[104:107], v[158:161], v[190:193], v[104:107]
	v_mfma_f32_16x16x32_bf16 v[96:99], v[144:147], v[198:201], v[96:99]
	v_mfma_f32_16x16x32_bf16 v[88:91], v[158:161], v[198:201], v[88:91]
	v_mfma_f32_16x16x32_bf16 v[80:83], v[144:147], v[206:209], v[80:83]
	v_mfma_f32_16x16x32_bf16 v[72:75], v[158:161], v[206:209], v[72:75]
	v_mfma_f32_16x16x32_bf16 v[124:127], v[154:157], v[186:189], v[124:127]
	v_mfma_f32_16x16x32_bf16 v[120:123], v[162:165], v[186:189], v[120:123]
	v_mfma_f32_16x16x32_bf16 v[112:115], v[154:157], v[194:197], v[112:115]
	v_mfma_f32_16x16x32_bf16 v[104:107], v[162:165], v[194:197], v[104:107]
	v_mfma_f32_16x16x32_bf16 v[96:99], v[154:157], v[202:205], v[96:99]
	v_mfma_f32_16x16x32_bf16 v[88:91], v[162:165], v[202:205], v[88:91]
	v_mfma_f32_16x16x32_bf16 v[80:83], v[154:157], v[210:213], v[80:83]
	v_mfma_f32_16x16x32_bf16 v[72:75], v[162:165], v[210:213], v[72:75]
	v_mfma_f32_16x16x32_bf16 v[116:119], v[166:169], v[182:185], v[116:119]
	v_mfma_f32_16x16x32_bf16 v[108:111], v[174:177], v[182:185], v[108:111]
	v_mfma_f32_16x16x32_bf16 v[100:103], v[166:169], v[190:193], v[100:103]
	v_mfma_f32_16x16x32_bf16 v[92:95], v[174:177], v[190:193], v[92:95]
	v_mfma_f32_16x16x32_bf16 v[84:87], v[166:169], v[198:201], v[84:87]
	v_mfma_f32_16x16x32_bf16 v[76:79], v[174:177], v[198:201], v[76:79]
	v_mfma_f32_16x16x32_bf16 v[68:71], v[166:169], v[206:209], v[68:71]
	v_mfma_f32_16x16x32_bf16 v[64:67], v[174:177], v[206:209], v[64:67]
	v_mfma_f32_16x16x32_bf16 v[116:119], v[170:173], v[186:189], v[116:119]
	v_mfma_f32_16x16x32_bf16 v[108:111], v[178:181], v[186:189], v[108:111]
	v_mfma_f32_16x16x32_bf16 v[100:103], v[170:173], v[194:197], v[100:103]
	v_mfma_f32_16x16x32_bf16 v[92:95], v[178:181], v[194:197], v[92:95]
	v_mfma_f32_16x16x32_bf16 v[84:87], v[170:173], v[202:205], v[84:87]
	v_mfma_f32_16x16x32_bf16 v[76:79], v[178:181], v[202:205], v[76:79]
	v_mfma_f32_16x16x32_bf16 v[68:71], v[170:173], v[210:213], v[68:71]
	v_mfma_f32_16x16x32_bf16 v[64:67], v[178:181], v[210:213], v[64:67]
	s_barrier
	s_add_i32 s42, s33, s21
	s_mov_b32 m0, s42
	ds_read_b128 v[182:185], v153 offset:16384
	ds_read_b128 v[186:189], v153 offset:17408
	ds_read_b128 v[190:193], v153 offset:18432
	ds_read_b128 v[194:197], v153 offset:19456
	ds_read_b128 v[198:201], v153 offset:20480
	ds_read_b128 v[202:205], v153 offset:21504
	ds_read_b128 v[206:209], v153 offset:22528
	ds_read_b128 v[210:213], v153 offset:23552
	global_load_lds_dwordx4 v132, s[16:17]
	s_add_i32 m0, s42, 0x2000
	s_add_u32 s42, s16, 0xb0000
	s_mov_b64 s[98:99], s[16:17]
	s_addc_u32 s43, s17, 0
	s_add_i32 s44, s34, s21
	global_load_lds_dwordx4 v128, s[16:17]
	s_mov_b32 m0, s44
	s_mov_b64 s[100:101], s[18:19]
	global_load_lds_dwordx4 v132, s[42:43]
	s_add_i32 m0, s44, 0x2000
	s_nop 0
	global_load_lds_dwordx4 v128, s[42:43]
	s_mov_b32 m0, s24
	s_nop 0
	global_load_lds_dwordx4 v134, s[18:19]
	s_mov_b32 m0, s25
	s_nop 0
	global_load_lds_dwordx4 v130, s[18:19]
	s_waitcnt vmcnt(8)
	s_waitcnt lgkmcnt(0)
	s_barrier
	v_mfma_f32_16x16x32_bf16 v[60:63], v[144:147], v[182:185], v[60:63]
	v_mfma_f32_16x16x32_bf16 v[56:59], v[158:161], v[182:185], v[56:59]
	v_mfma_f32_16x16x32_bf16 v[48:51], v[144:147], v[190:193], v[48:51]
	v_mfma_f32_16x16x32_bf16 v[40:43], v[158:161], v[190:193], v[40:43]
	v_mfma_f32_16x16x32_bf16 v[32:35], v[144:147], v[198:201], v[32:35]
	v_mfma_f32_16x16x32_bf16 v[24:27], v[158:161], v[198:201], v[24:27]
	v_mfma_f32_16x16x32_bf16 v[16:19], v[144:147], v[206:209], v[16:19]
	v_mfma_f32_16x16x32_bf16 v[8:11], v[158:161], v[206:209], v[8:11]
	v_mfma_f32_16x16x32_bf16 v[60:63], v[154:157], v[186:189], v[60:63]
	v_mfma_f32_16x16x32_bf16 v[56:59], v[162:165], v[186:189], v[56:59]
	v_mfma_f32_16x16x32_bf16 v[48:51], v[154:157], v[194:197], v[48:51]
	v_mfma_f32_16x16x32_bf16 v[40:43], v[162:165], v[194:197], v[40:43]
	v_mfma_f32_16x16x32_bf16 v[32:35], v[154:157], v[202:205], v[32:35]
	v_mfma_f32_16x16x32_bf16 v[24:27], v[162:165], v[202:205], v[24:27]
	v_mfma_f32_16x16x32_bf16 v[16:19], v[154:157], v[210:213], v[16:19]
	v_mfma_f32_16x16x32_bf16 v[8:11], v[162:165], v[210:213], v[8:11]
	v_mfma_f32_16x16x32_bf16 v[52:55], v[166:169], v[182:185], v[52:55]
	v_mfma_f32_16x16x32_bf16 v[44:47], v[174:177], v[182:185], v[44:47]
	v_mfma_f32_16x16x32_bf16 v[36:39], v[166:169], v[190:193], v[36:39]
	v_mfma_f32_16x16x32_bf16 v[28:31], v[174:177], v[190:193], v[28:31]
	v_mfma_f32_16x16x32_bf16 v[20:23], v[166:169], v[198:201], v[20:23]
	v_mfma_f32_16x16x32_bf16 v[12:15], v[174:177], v[198:201], v[12:15]
	v_mfma_f32_16x16x32_bf16 v[4:7], v[166:169], v[206:209], v[4:7]
	v_mfma_f32_16x16x32_bf16 v[0:3], v[174:177], v[206:209], v[0:3]
	v_mfma_f32_16x16x32_bf16 v[52:55], v[170:173], v[186:189], v[52:55]
	v_mfma_f32_16x16x32_bf16 v[44:47], v[178:181], v[186:189], v[44:47]
	v_mfma_f32_16x16x32_bf16 v[36:39], v[170:173], v[194:197], v[36:39]
	v_mfma_f32_16x16x32_bf16 v[28:31], v[178:181], v[194:197], v[28:31]
	v_mfma_f32_16x16x32_bf16 v[20:23], v[170:173], v[202:205], v[20:23]
	v_mfma_f32_16x16x32_bf16 v[12:15], v[178:181], v[202:205], v[12:15]
	v_mfma_f32_16x16x32_bf16 v[4:7], v[170:173], v[210:213], v[4:7]
	v_mfma_f32_16x16x32_bf16 v[0:3], v[178:181], v[210:213], v[0:3]
	s_barrier
; #define PG8_STAGE(bufoff, gbase, voff) do { _Pragma("unroll") for (int _i = 0; _i < 2; ++_i) \
;         __builtin_amdgcn_global_load_lds((const unsigned*)((const char*)(gbase) + (voff)[_i]), (LAS unsigned*)(lds + (bufoff) + ldsw + _i * 8192), 16, 0, 0); } while (0)
; #define PG8_LDA(dst, b, h) do { _Pragma("unroll") for (int m = 0; m < 4; ++m) _Pragma("unroll") for (int k = 0; k < 2; ++k) dst[m][k] = *(const LAS bf16x8*)(lds + PG8_SA(b, h) + aoff + m * 2048 + k * 1024); } while (0)
; #define PG8_LDB(dst, b, h) do { _Pragma("unroll") for (int n = 0; n < 2; ++n) _Pragma("unroll") for (int k = 0; k < 2; ++k) dst[n][k] = *(const LAS bf16x8*)(lds + PG8_SB(b, h) + boff + n * 2048 + k * 1024); } while (0)
; #define PG8_MMA(ai, bj, At, Bt) do { __builtin_amdgcn_s_setprio(1); _Pragma("unroll") for (int m = 0; m < 4; ++m) _Pragma("unroll") for (int n = 0; n < 2; ++n) _Pragma("unroll") for (int k = 0; k < 2; ++k) \
;         acc[ai][bj][m][n] = __builtin_amdgcn_mfma_f32_16x16x32_bf16(Bt[n][k], At[m][k], acc[ai][bj][m][n], 0, 0, 0); __builtin_amdgcn_s_setprio(0); } while (0)
; #define PG8_WAIT_V(n) asm volatile("s_waitcnt vmcnt(" #n ")" ::: "memory")
; #define PG8_WAIT_L(n) asm volatile("s_waitcnt lgkmcnt(" #n ")" ::: "memory")
; #define PG8_BAR __builtin_amdgcn_s_barrier()
; #define PG8_SCHED __builtin_amdgcn_sched_barrier(0)
; template <class Epi, class Sched>
; __device__ __forceinline__ void gemm_phase(LAS unsigned char* lds, const int lda, const int ldb, const int K, const Sched& S, const Epi& E) {
;     ...
;             PG8_LDB(B0, 1, 0); PG8_LDB(B1, 1, 1); PG8_SCHED; PG8_LDA(At, 1, 0); PG8_STAGE(PG8_SA(0, 1), a2 + hstepA, voffA);
;             PG8_WAIT_V(8); PG8_WAIT_L(0); PG8_BAR; PG8_MMA(0, 0, At, B0); PG8_MMA(0, 1, At, B1); PG8_BAR; PG8_SCHED;
;             PG8_LDA(At, 1, 1); PG8_STAGE(PG8_SB(1, 0), b3, voffB); PG8_STAGE(PG8_SB(1, 1), b3 + hstepB, voffB); PG8_STAGE(PG8_SA(1, 0), a3, voffA);
;             PG8_WAIT_V(8); PG8_WAIT_L(0); PG8_BAR;
;             if (last) E.pre(cur, wr, fr, rsv);
;             PG8_MMA(1, 0, At, B0); PG8_MMA(1, 1, At, B1); PG8_BAR; PG8_SCHED;
;         }
;         if (wr == 0) PG8_BAR;
.Lpeel7_join:
	s_add_i32 s42, 0, 0x18000
	s_add_i32 s43, 0, 0x1c000
	v_add_u32_e32 v162, s42, v149
	v_add_u32_e32 v178, s43, v149
	ds_read_b128 v[144:147], v162
	ds_read_b128 v[154:157], v162 offset:1024
	ds_read_b128 v[158:161], v162 offset:2048
	ds_read_b128 v[162:165], v162 offset:3072
	ds_read_b128 v[166:169], v178
	ds_read_b128 v[170:173], v178 offset:1024
	ds_read_b128 v[174:177], v178 offset:2048
	ds_read_b128 v[178:181], v178 offset:3072
	s_add_u32 s18, s18, 0xb0000
	s_addc_u32 s19, s19, 0
	s_mov_b32 m0, s26
	ds_read_b128 v[182:185], v153 offset:32768
	ds_read_b128 v[186:189], v153 offset:33792
	ds_read_b128 v[190:193], v153 offset:34816
	ds_read_b128 v[194:197], v153 offset:35840
	ds_read_b128 v[198:201], v153 offset:36864
	ds_read_b128 v[202:205], v153 offset:37888
	ds_read_b128 v[206:209], v153 offset:38912
	ds_read_b128 v[210:213], v153 offset:39936
	global_load_lds_dwordx4 v134, s[18:19]
	s_mov_b32 m0, s27
	s_nop 0
	global_load_lds_dwordx4 v130, s[18:19]
	s_waitcnt vmcnt(8)
	s_waitcnt lgkmcnt(0)
	s_barrier
	v_mfma_f32_16x16x32_bf16 v[124:127], v[144:147], v[182:185], v[124:127]
	v_mfma_f32_16x16x32_bf16 v[120:123], v[158:161], v[182:185], v[120:123]
	v_mfma_f32_16x16x32_bf16 v[112:115], v[144:147], v[190:193], v[112:115]
	v_mfma_f32_16x16x32_bf16 v[104:107], v[158:161], v[190:193], v[104:107]
	v_mfma_f32_16x16x32_bf16 v[96:99], v[144:147], v[198:201], v[96:99]
	v_mfma_f32_16x16x32_bf16 v[88:91], v[158:161], v[198:201], v[88:91]
	v_mfma_f32_16x16x32_bf16 v[80:83], v[144:147], v[206:209], v[80:83]
	v_mfma_f32_16x16x32_bf16 v[72:75], v[158:161], v[206:209], v[72:75]
	v_mfma_f32_16x16x32_bf16 v[124:127], v[154:157], v[186:189], v[124:127]
	v_mfma_f32_16x16x32_bf16 v[120:123], v[162:165], v[186:189], v[120:123]
	v_mfma_f32_16x16x32_bf16 v[112:115], v[154:157], v[194:197], v[112:115]
	v_mfma_f32_16x16x32_bf16 v[104:107], v[162:165], v[194:197], v[104:107]
	v_mfma_f32_16x16x32_bf16 v[96:99], v[154:157], v[202:205], v[96:99]
	v_mfma_f32_16x16x32_bf16 v[88:91], v[162:165], v[202:205], v[88:91]
	v_mfma_f32_16x16x32_bf16 v[80:83], v[154:157], v[210:213], v[80:83]
	v_mfma_f32_16x16x32_bf16 v[72:75], v[162:165], v[210:213], v[72:75]
	v_mfma_f32_16x16x32_bf16 v[116:119], v[166:169], v[182:185], v[116:119]
	v_mfma_f32_16x16x32_bf16 v[108:111], v[174:177], v[182:185], v[108:111]
	v_mfma_f32_16x16x32_bf16 v[100:103], v[166:169], v[190:193], v[100:103]
	v_mfma_f32_16x16x32_bf16 v[92:95], v[174:177], v[190:193], v[92:95]
	v_mfma_f32_16x16x32_bf16 v[84:87], v[166:169], v[198:201], v[84:87]
	v_mfma_f32_16x16x32_bf16 v[76:79], v[174:177], v[198:201], v[76:79]
	v_mfma_f32_16x16x32_bf16 v[68:71], v[166:169], v[206:209], v[68:71]
	v_mfma_f32_16x16x32_bf16 v[64:67], v[174:177], v[206:209], v[64:67]
	v_mfma_f32_16x16x32_bf16 v[116:119], v[170:173], v[186:189], v[116:119]
	v_mfma_f32_16x16x32_bf16 v[108:111], v[178:181], v[186:189], v[108:111]
	v_mfma_f32_16x16x32_bf16 v[100:103], v[170:173], v[194:197], v[100:103]
	v_mfma_f32_16x16x32_bf16 v[92:95], v[178:181], v[194:197], v[92:95]
	v_mfma_f32_16x16x32_bf16 v[84:87], v[170:173], v[202:205], v[84:87]
	v_mfma_f32_16x16x32_bf16 v[76:79], v[178:181], v[202:205], v[76:79]
	v_mfma_f32_16x16x32_bf16 v[68:71], v[170:173], v[210:213], v[68:71]
	v_mfma_f32_16x16x32_bf16 v[64:67], v[178:181], v[210:213], v[64:67]
	s_barrier
	s_add_i32 s18, s42, s21
	s_mov_b32 m0, s18
	ds_read_b128 v[182:185], v153 offset:49152
	ds_read_b128 v[186:189], v153 offset:50176
	ds_read_b128 v[190:193], v153 offset:51200
	ds_read_b128 v[194:197], v153 offset:52224
	ds_read_b128 v[198:201], v153 offset:53248
	ds_read_b128 v[202:205], v153 offset:54272
	ds_read_b128 v[206:209], v153 offset:55296
	ds_read_b128 v[210:213], v153 offset:56320
	global_load_lds_dwordx4 v214, s[16:17]
	s_add_i32 m0, s18, 0x2000
	s_add_u32 s16, s16, 0xb0080
	s_addc_u32 s17, s17, 0
	s_add_i32 s18, s43, s21
	global_load_lds_dwordx4 v215, s[98:99]
	s_mov_b32 m0, s18
	s_nop 0
	global_load_lds_dwordx4 v132, s[16:17]
	s_add_i32 m0, s18, 0x2000
	s_nop 0
	global_load_lds_dwordx4 v128, s[16:17]
	s_mov_b32 m0, s29
	s_nop 0
	global_load_lds_dwordx4 v216, s[100:101]
	s_mov_b32 m0, s30
	s_nop 0
	global_load_lds_dwordx4 v217, s[100:101]
	s_waitcnt vmcnt(8)
	s_waitcnt lgkmcnt(0)
	s_barrier
	v_mfma_f32_16x16x32_bf16 v[60:63], v[144:147], v[182:185], v[60:63]
	v_mfma_f32_16x16x32_bf16 v[56:59], v[158:161], v[182:185], v[56:59]
	v_mfma_f32_16x16x32_bf16 v[48:51], v[144:147], v[190:193], v[48:51]
	v_mfma_f32_16x16x32_bf16 v[40:43], v[158:161], v[190:193], v[40:43]
	v_mfma_f32_16x16x32_bf16 v[32:35], v[144:147], v[198:201], v[32:35]
	v_mfma_f32_16x16x32_bf16 v[24:27], v[158:161], v[198:201], v[24:27]
	v_mfma_f32_16x16x32_bf16 v[16:19], v[144:147], v[206:209], v[16:19]
	v_mfma_f32_16x16x32_bf16 v[8:11], v[158:161], v[206:209], v[8:11]
	v_mfma_f32_16x16x32_bf16 v[60:63], v[154:157], v[186:189], v[60:63]
	v_mfma_f32_16x16x32_bf16 v[56:59], v[162:165], v[186:189], v[56:59]
	v_mfma_f32_16x16x32_bf16 v[48:51], v[154:157], v[194:197], v[48:51]
	v_mfma_f32_16x16x32_bf16 v[40:43], v[162:165], v[194:197], v[40:43]
	v_mfma_f32_16x16x32_bf16 v[32:35], v[154:157], v[202:205], v[32:35]
	v_mfma_f32_16x16x32_bf16 v[24:27], v[162:165], v[202:205], v[24:27]
	v_mfma_f32_16x16x32_bf16 v[16:19], v[154:157], v[210:213], v[16:19]
	v_mfma_f32_16x16x32_bf16 v[8:11], v[162:165], v[210:213], v[8:11]
	v_mfma_f32_16x16x32_bf16 v[52:55], v[166:169], v[182:185], v[52:55]
	v_mfma_f32_16x16x32_bf16 v[44:47], v[174:177], v[182:185], v[44:47]
	v_mfma_f32_16x16x32_bf16 v[36:39], v[166:169], v[190:193], v[36:39]
	v_mfma_f32_16x16x32_bf16 v[28:31], v[174:177], v[190:193], v[28:31]
	v_mfma_f32_16x16x32_bf16 v[20:23], v[166:169], v[198:201], v[20:23]
	v_mfma_f32_16x16x32_bf16 v[12:15], v[174:177], v[198:201], v[12:15]
	v_mfma_f32_16x16x32_bf16 v[4:7], v[166:169], v[206:209], v[4:7]
	v_mfma_f32_16x16x32_bf16 v[0:3], v[174:177], v[206:209], v[0:3]
	v_mfma_f32_16x16x32_bf16 v[52:55], v[170:173], v[186:189], v[52:55]
	v_mfma_f32_16x16x32_bf16 v[44:47], v[178:181], v[186:189], v[44:47]
	v_mfma_f32_16x16x32_bf16 v[36:39], v[170:173], v[194:197], v[36:39]
	v_mfma_f32_16x16x32_bf16 v[28:31], v[178:181], v[194:197], v[28:31]
	v_mfma_f32_16x16x32_bf16 v[20:23], v[170:173], v[202:205], v[20:23]
	v_mfma_f32_16x16x32_bf16 v[12:15], v[178:181], v[202:205], v[12:15]
	v_mfma_f32_16x16x32_bf16 v[4:7], v[170:173], v[210:213], v[4:7]
	v_mfma_f32_16x16x32_bf16 v[0:3], v[178:181], v[210:213], v[0:3]
	s_barrier
	s_add_i32 s41, s41, 2
	s_add_u32 s14, s14, 0x100
	s_addc_u32 s15, s15, 0
	s_add_u32 s39, s39, 0x100
	s_addc_u32 s40, s40, 0
	s_cmp_gt_u32 s41, 41
	s_cbranch_scc0 .LBB0_1136
	s_and_b64 vcc, exec, s[8:9]
	s_cbranch_vccz .LBB0_1139
	s_barrier
